# v18 plus: scan-chain LDS operand prefetch, resid epilogue bulk loads, rmsnorm row loads issued together, MLA softmax max-subtraction folded into QK accumulator init
# speedup vs baseline: 1.0251x; 1.0150x over previous
; #define MFMA32(a, b, c) __builtin_amdgcn_mfma_f32_32x32x16_bf16((a), (b), (c), 0, 0, 0)
; DI void gemm_main_bd(f32x16 (&acc)[4][2], const bf16_t* __restrict__ A, int lda, const bf16_t* __restrict__ Bf, int n0,
;                      int K, char* lds) {
;     ...
;   for (int k = 0; k < nsteps; ++k) {
;     const bf16_t* As = As0 + (k & 1) * (128 * 72);
;     bf16_t* Aw = As0 + ((k + 1) & 1) * (128 * 72);
; #pragma unroll
;     for (int ks = 0; ks < 4; ++ks) { bc[0][ks] = bn[0][ks]; bc[1][ks] = bn[1][ks]; }
;     if (k + 1 < nsteps) {
; #pragma unroll
;       for (int ks = 0; ks < 4; ++ks) {
;         bn[0][ks] = *(const bf16x8*)(Bb0 + (loff + 1024u * (unsigned)(4 * (k + 1) + ks)));
;         bn[1][ks] = *(const bf16x8*)(Bb1 + (loff + 1024u * (unsigned)(4 * (k + 1) + ks)));
;       }
; #pragma unroll
;       for (int i = 0; i < 4; ++i) *(u32x4*)(Aw + (lr + 32 * i) * 72 + lc) = ra[i];
;       if (k + 2 < nsteps) {
; #pragma unroll
;         for (int i = 0; i < 4; ++i) ra[i] = *(const u32x4*)(Ab + (aoff + astep * i + 128u * (unsigned)(k + 2)));
;       }
;     }
;     __builtin_amdgcn_s_setprio(1);
; #pragma unroll
;     for (int ks = 0; ks < 4; ++ks) {
;       bf16x8 af[4];
; #pragma unroll
;       for (int mi = 0; mi < 4; ++mi) af[mi] = *(const bf16x8*)(As + (32 * mi + l31) * 72 + 16 * ks + 8 * h2);
; #pragma unroll
;       for (int mi = 0; mi < 4; ++mi)
; #pragma unroll
;         for (int ni = 0; ni < 2; ++ni) acc[mi][ni] = MFMA32(bc[ni][ks], af[mi], acc[mi][ni]);
;     }
;     __builtin_amdgcn_s_setprio(0);
;     __syncthreads();
;   }
.LBB0_273:
	s_waitcnt vmcnt(4)
	v_mov_b64_e32 v[208:209], v[132:133]
	v_mov_b64_e32 v[206:207], v[130:131]
	v_lshl_add_u64 v[130:131], v[222:223], 0, s[44:45]
	s_mov_b32 s51, 0xb01000
	s_and_b32 s49, 1, s48
	s_add_i32 s48, s48, 1
	v_add_co_u32_e32 v132, vcc, s51, v130
	s_and_b32 s50, 1, s48
	s_nop 0
	v_addc_co_u32_e32 v133, vcc, 0, v131, vcc
	s_mov_b32 s51, 0xb2d000
	s_cmp_eq_u32 s49, 1
	v_add_co_u32_e32 v130, vcc, s51, v130
	s_cselect_b32 s49, 0x4800, 0
	s_cmp_eq_u32 s50, 1
	v_addc_co_u32_e32 v131, vcc, 0, v131, vcc
	s_cselect_b32 s50, 0x4800, 0
	global_load_dwordx4 v[198:201], v[132:133], off
	global_load_dwordx4 v[202:205], v[130:131], off
	global_load_dwordx4 v[194:197], v[132:133], off offset:1024
	global_load_dwordx4 v[190:193], v[130:131], off offset:1024
	global_load_dwordx4 v[182:185], v[132:133], off offset:2048
	global_load_dwordx4 v[186:189], v[130:131], off offset:2048
	global_load_dwordx4 v[178:181], v[132:133], off offset:3072
	s_nop 0
	global_load_dwordx4 v[130:133], v[130:131], off offset:3072
	v_add_u32_e32 v0, s50, v236
	s_waitcnt vmcnt(11)
	ds_write_b128 v0, v[134:137]
	s_waitcnt vmcnt(10)
	ds_write_b128 v0, v[138:141] offset:4608
	s_waitcnt vmcnt(9)
	ds_write_b128 v0, v[142:145] offset:9216
	s_waitcnt vmcnt(8)
	ds_write_b128 v0, v[146:149] offset:13824
	v_add_u32_e32 v0, 0xfff7c000, v237
	global_load_dwordx4 v[134:137], v0, s[34:35]
	v_add_u32_e32 v0, 0xfffa8000, v237
	global_load_dwordx4 v[138:141], v0, s[34:35]
	v_add_u32_e32 v0, 0xfffd4000, v237
	global_load_dwordx4 v[142:145], v0, s[34:35]
	global_load_dwordx4 v[146:149], v237, s[34:35]
	s_setprio 1
	v_add_u32_e32 v0, s49, v234
	ds_read_b128 v[238:241], v0
	ds_read_b128 v[248:251], v0 offset:4608
	s_waitcnt lgkmcnt(1)
	v_mfma_f32_32x32x16_bf16 v[114:129], v[170:173], v[238:241], v[114:129]
	v_mfma_f32_32x32x16_bf16 v[98:113], v[174:177], v[238:241], v[98:113]
	ds_read_b128 v[238:241], v0 offset:9216
	s_waitcnt lgkmcnt(1)
	v_mfma_f32_32x32x16_bf16 v[82:97], v[170:173], v[248:251], v[82:97]
	v_mfma_f32_32x32x16_bf16 v[66:81], v[174:177], v[248:251], v[66:81]
	ds_read_b128 v[248:251], v0 offset:13824
	s_waitcnt lgkmcnt(1)
	v_mfma_f32_32x32x16_bf16 v[50:65], v[170:173], v[238:241], v[50:65]
	v_mfma_f32_32x32x16_bf16 v[34:49], v[174:177], v[238:241], v[34:49]
	ds_read_b128 v[238:241], v0 offset:32
	s_waitcnt lgkmcnt(1)
	v_mfma_f32_32x32x16_bf16 v[18:33], v[170:173], v[248:251], v[18:33]
	v_mfma_f32_32x32x16_bf16 v[2:17], v[174:177], v[248:251], v[2:17]
	ds_read_b128 v[248:251], v0 offset:4640
	s_waitcnt lgkmcnt(1)
	v_mfma_f32_32x32x16_bf16 v[114:129], v[158:161], v[238:241], v[114:129]
	v_mfma_f32_32x32x16_bf16 v[98:113], v[166:169], v[238:241], v[98:113]
	ds_read_b128 v[238:241], v0 offset:9248
	s_waitcnt lgkmcnt(1)
	v_mfma_f32_32x32x16_bf16 v[82:97], v[158:161], v[248:251], v[82:97]
	v_mfma_f32_32x32x16_bf16 v[66:81], v[166:169], v[248:251], v[66:81]
	ds_read_b128 v[248:251], v0 offset:13856
	s_waitcnt lgkmcnt(1)
	v_mfma_f32_32x32x16_bf16 v[50:65], v[158:161], v[238:241], v[50:65]
	v_mfma_f32_32x32x16_bf16 v[34:49], v[166:169], v[238:241], v[34:49]
	ds_read_b128 v[238:241], v0 offset:64
	s_waitcnt lgkmcnt(1)
	v_mfma_f32_32x32x16_bf16 v[18:33], v[158:161], v[248:251], v[18:33]
	v_mfma_f32_32x32x16_bf16 v[2:17], v[166:169], v[248:251], v[2:17]
	ds_read_b128 v[248:251], v0 offset:4672
	s_waitcnt lgkmcnt(1)
	v_mfma_f32_32x32x16_bf16 v[114:129], v[154:157], v[238:241], v[114:129]
	v_mfma_f32_32x32x16_bf16 v[98:113], v[162:165], v[238:241], v[98:113]
	ds_read_b128 v[238:241], v0 offset:9280
	s_waitcnt lgkmcnt(1)
	v_mfma_f32_32x32x16_bf16 v[82:97], v[154:157], v[248:251], v[82:97]
	v_mfma_f32_32x32x16_bf16 v[66:81], v[162:165], v[248:251], v[66:81]
	ds_read_b128 v[248:251], v0 offset:13888
	s_waitcnt lgkmcnt(1)
	v_mfma_f32_32x32x16_bf16 v[50:65], v[154:157], v[238:241], v[50:65]
	v_mfma_f32_32x32x16_bf16 v[34:49], v[162:165], v[238:241], v[34:49]
	ds_read_b128 v[238:241], v0 offset:96
	s_waitcnt lgkmcnt(1)
	v_mfma_f32_32x32x16_bf16 v[18:33], v[154:157], v[248:251], v[18:33]
	v_mfma_f32_32x32x16_bf16 v[2:17], v[162:165], v[248:251], v[2:17]
	ds_read_b128 v[248:251], v0 offset:4704
	s_waitcnt lgkmcnt(1)
	v_mfma_f32_32x32x16_bf16 v[114:129], v[150:153], v[238:241], v[114:129]
	v_mfma_f32_32x32x16_bf16 v[98:113], v[206:209], v[238:241], v[98:113]
	ds_read_b128 v[238:241], v0 offset:9312
	s_waitcnt lgkmcnt(1)
	v_mfma_f32_32x32x16_bf16 v[82:97], v[150:153], v[248:251], v[82:97]
	v_mfma_f32_32x32x16_bf16 v[66:81], v[206:209], v[248:251], v[66:81]
	ds_read_b128 v[248:251], v0 offset:13920
	s_waitcnt lgkmcnt(1)
	v_mfma_f32_32x32x16_bf16 v[50:65], v[150:153], v[238:241], v[50:65]
	v_mfma_f32_32x32x16_bf16 v[34:49], v[206:209], v[238:241], v[34:49]
	s_waitcnt lgkmcnt(0)
	v_mfma_f32_32x32x16_bf16 v[18:33], v[150:153], v[248:251], v[18:33]
	v_mfma_f32_32x32x16_bf16 v[2:17], v[206:209], v[248:251], v[2:17]
	s_setprio 0
	s_add_u32 s44, s44, 0x1000
	s_addc_u32 s45, s45, 0
	v_add_u32_e32 v237, 0x80, v237
	s_cmp_eq_u32 s44, 0x2a000
	s_waitcnt vmcnt(11)
	v_mov_b32_e32 v170, v198
	v_mov_b32_e32 v171, v199
	v_mov_b32_e32 v172, v200
	v_mov_b32_e32 v173, v201
	s_waitcnt vmcnt(9)
	v_mov_b32_e32 v158, v194
	v_mov_b32_e32 v159, v195
	v_mov_b32_e32 v160, v196
	v_mov_b32_e32 v161, v197
	s_waitcnt vmcnt(7)
	v_mov_b32_e32 v154, v182
	v_mov_b32_e32 v155, v183
	v_mov_b32_e32 v156, v184
	v_mov_b32_e32 v157, v185
	s_waitcnt vmcnt(5)
	v_mov_b32_e32 v150, v178
	v_mov_b32_e32 v151, v179
	v_mov_b32_e32 v152, v180
	v_mov_b32_e32 v153, v181
	v_mov_b32_e32 v174, v202
	v_mov_b32_e32 v175, v203
	v_mov_b32_e32 v176, v204
	v_mov_b32_e32 v177, v205
	v_mov_b32_e32 v166, v190
	v_mov_b32_e32 v167, v191
	v_mov_b32_e32 v168, v192
	v_mov_b32_e32 v169, v193
	v_mov_b32_e32 v162, v186
	v_mov_b32_e32 v163, v187
	v_mov_b32_e32 v164, v188
	v_mov_b32_e32 v165, v189
	s_barrier
; #define MFMA32(a, b, c) __builtin_amdgcn_mfma_f32_32x32x16_bf16((a), (b), (c), 0, 0, 0)
; DI void gemm_main_bd(f32x16 (&acc)[4][2], const bf16_t* __restrict__ A, int lda, const bf16_t* __restrict__ Bf, int n0,
;                      int K, char* lds) {
;     ...
;   for (int k = 0; k < nsteps; ++k) {
;     const bf16_t* As = As0 + (k & 1) * (128 * 72);
;     bf16_t* Aw = As0 + ((k + 1) & 1) * (128 * 72);
; #pragma unroll
;     for (int ks = 0; ks < 4; ++ks) { bc[0][ks] = bn[0][ks]; bc[1][ks] = bn[1][ks]; }
;     if (k + 1 < nsteps) {
; #pragma unroll
;       for (int ks = 0; ks < 4; ++ks) {
;         bn[0][ks] = *(const bf16x8*)(Bb0 + (loff + 1024u * (unsigned)(4 * (k + 1) + ks)));
;         bn[1][ks] = *(const bf16x8*)(Bb1 + (loff + 1024u * (unsigned)(4 * (k + 1) + ks)));
;       }
; #pragma unroll
;       for (int i = 0; i < 4; ++i) *(u32x4*)(Aw + (lr + 32 * i) * 72 + lc) = ra[i];
;       if (k + 2 < nsteps) {
; #pragma unroll
;         for (int i = 0; i < 4; ++i) ra[i] = *(const u32x4*)(Ab + (aoff + astep * i + 128u * (unsigned)(k + 2)));
;       }
;     }
;     __builtin_amdgcn_s_setprio(1);
; #pragma unroll
;     for (int ks = 0; ks < 4; ++ks) {
;       bf16x8 af[4];
; #pragma unroll
;       for (int mi = 0; mi < 4; ++mi) af[mi] = *(const bf16x8*)(As + (32 * mi + l31) * 72 + 16 * ks + 8 * h2);
; #pragma unroll
;       for (int mi = 0; mi < 4; ++mi)
; #pragma unroll
;         for (int ni = 0; ni < 2; ++ni) acc[mi][ni] = MFMA32(bc[ni][ks], af[mi], acc[mi][ni]);
;     }
;     __builtin_amdgcn_s_setprio(0);
;     __syncthreads();
;   }
	s_cbranch_scc0 .LBB0_273
	v_or_b32_e32 v150, 0x2b000, v235
	global_load_dwordx4 v[174:177], v150, s[38:39]
	global_load_dwordx4 v[206:209], v150, s[42:43]
	v_or_b32_e32 v150, 0x2b400, v235
	global_load_dwordx4 v[170:173], v150, s[38:39]
	global_load_dwordx4 v[166:169], v150, s[42:43]
	v_or_b32_e32 v150, 0x2b800, v235
	global_load_dwordx4 v[158:161], v150, s[38:39]
	global_load_dwordx4 v[162:165], v150, s[42:43]
	v_or_b32_e32 v150, 0x2bc00, v235
	global_load_dwordx4 v[154:157], v150, s[38:39]
	s_nop 0
	global_load_dwordx4 v[150:153], v150, s[42:43]
	s_waitcnt vmcnt(11)
	ds_write_b128 v236, v[134:137] offset:18432
	s_waitcnt vmcnt(10)
	ds_write_b128 v236, v[138:141] offset:23040
	s_waitcnt vmcnt(9)
	ds_write_b128 v236, v[142:145] offset:27648
	s_waitcnt vmcnt(8)
	ds_write_b128 v236, v[146:149] offset:32256
	s_setprio 1
	ds_read_b128 v[134:137], v234
	s_waitcnt lgkmcnt(0)
	v_mfma_f32_32x32x16_bf16 v[114:129], v[198:201], v[134:137], v[114:129]
	v_mfma_f32_32x32x16_bf16 v[98:113], v[202:205], v[134:137], v[98:113]
	ds_read_b128 v[134:137], v234 offset:4608
	s_waitcnt lgkmcnt(0)
	v_mfma_f32_32x32x16_bf16 v[82:97], v[198:201], v[134:137], v[82:97]
	v_mfma_f32_32x32x16_bf16 v[66:81], v[202:205], v[134:137], v[66:81]
	ds_read_b128 v[134:137], v234 offset:9216
	s_waitcnt lgkmcnt(0)
	v_mfma_f32_32x32x16_bf16 v[50:65], v[198:201], v[134:137], v[50:65]
	v_mfma_f32_32x32x16_bf16 v[34:49], v[202:205], v[134:137], v[34:49]
	ds_read_b128 v[134:137], v234 offset:13824
	s_waitcnt lgkmcnt(0)
	v_mfma_f32_32x32x16_bf16 v[18:33], v[198:201], v[134:137], v[18:33]
	v_mfma_f32_32x32x16_bf16 v[2:17], v[202:205], v[134:137], v[2:17]
	ds_read_b128 v[134:137], v234 offset:32
	s_waitcnt lgkmcnt(0)
	v_mfma_f32_32x32x16_bf16 v[114:129], v[194:197], v[134:137], v[114:129]
	v_mfma_f32_32x32x16_bf16 v[98:113], v[190:193], v[134:137], v[98:113]
	ds_read_b128 v[134:137], v234 offset:4640
	s_waitcnt lgkmcnt(0)
	v_mfma_f32_32x32x16_bf16 v[82:97], v[194:197], v[134:137], v[82:97]
	v_mfma_f32_32x32x16_bf16 v[66:81], v[190:193], v[134:137], v[66:81]
	ds_read_b128 v[134:137], v234 offset:9248
	s_waitcnt lgkmcnt(0)
	v_mfma_f32_32x32x16_bf16 v[50:65], v[194:197], v[134:137], v[50:65]
	v_mfma_f32_32x32x16_bf16 v[34:49], v[190:193], v[134:137], v[34:49]
	ds_read_b128 v[134:137], v234 offset:13856
	s_waitcnt lgkmcnt(0)
	v_mfma_f32_32x32x16_bf16 v[18:33], v[194:197], v[134:137], v[18:33]
	v_mfma_f32_32x32x16_bf16 v[2:17], v[190:193], v[134:137], v[2:17]
	ds_read_b128 v[134:137], v234 offset:64
	s_waitcnt lgkmcnt(0)
	v_mfma_f32_32x32x16_bf16 v[114:129], v[182:185], v[134:137], v[114:129]
	v_mfma_f32_32x32x16_bf16 v[98:113], v[186:189], v[134:137], v[98:113]
	ds_read_b128 v[134:137], v234 offset:4672
	s_waitcnt lgkmcnt(0)
	v_mfma_f32_32x32x16_bf16 v[82:97], v[182:185], v[134:137], v[82:97]
	v_mfma_f32_32x32x16_bf16 v[66:81], v[186:189], v[134:137], v[66:81]
	ds_read_b128 v[134:137], v234 offset:9280
	s_waitcnt lgkmcnt(0)
	v_mfma_f32_32x32x16_bf16 v[50:65], v[182:185], v[134:137], v[50:65]
	v_mfma_f32_32x32x16_bf16 v[34:49], v[186:189], v[134:137], v[34:49]
	ds_read_b128 v[134:137], v234 offset:13888
	s_waitcnt lgkmcnt(0)
	v_mfma_f32_32x32x16_bf16 v[18:33], v[182:185], v[134:137], v[18:33]
	v_mfma_f32_32x32x16_bf16 v[2:17], v[186:189], v[134:137], v[2:17]
	ds_read_b128 v[134:137], v234 offset:96
	s_waitcnt lgkmcnt(0)
	v_mfma_f32_32x32x16_bf16 v[114:129], v[178:181], v[134:137], v[114:129]
	v_mfma_f32_32x32x16_bf16 v[98:113], v[130:133], v[134:137], v[98:113]
	ds_read_b128 v[134:137], v234 offset:4704
	s_waitcnt lgkmcnt(0)
	v_mfma_f32_32x32x16_bf16 v[82:97], v[178:181], v[134:137], v[82:97]
	v_mfma_f32_32x32x16_bf16 v[66:81], v[130:133], v[134:137], v[66:81]
	ds_read_b128 v[134:137], v234 offset:9312
	s_waitcnt lgkmcnt(0)
	v_mfma_f32_32x32x16_bf16 v[50:65], v[178:181], v[134:137], v[50:65]
	v_mfma_f32_32x32x16_bf16 v[34:49], v[130:133], v[134:137], v[34:49]
	ds_read_b128 v[134:137], v234 offset:13920
	s_waitcnt lgkmcnt(0)
	v_mfma_f32_32x32x16_bf16 v[18:33], v[178:181], v[134:137], v[18:33]
	v_mfma_f32_32x32x16_bf16 v[2:17], v[130:133], v[134:137], v[2:17]
	s_setprio 0
	s_and_b32 s28, s28, 0x7fffff00
	s_barrier
	s_setprio 1
	ds_read_b128 v[130:133], v0
	s_waitcnt vmcnt(7) lgkmcnt(0)
	v_mfma_f32_32x32x16_bf16 v[114:129], v[174:177], v[130:133], v[114:129]
	s_waitcnt vmcnt(6)
	v_mfma_f32_32x32x16_bf16 v[98:113], v[206:209], v[130:133], v[98:113]
	ds_read_b128 v[130:133], v0 offset:4608
	s_waitcnt lgkmcnt(0)
	v_mfma_f32_32x32x16_bf16 v[82:97], v[174:177], v[130:133], v[82:97]
	v_mfma_f32_32x32x16_bf16 v[66:81], v[206:209], v[130:133], v[66:81]
	ds_read_b128 v[130:133], v0 offset:9216
	s_waitcnt lgkmcnt(0)
	v_mfma_f32_32x32x16_bf16 v[50:65], v[174:177], v[130:133], v[50:65]
	v_mfma_f32_32x32x16_bf16 v[34:49], v[206:209], v[130:133], v[34:49]
	ds_read_b128 v[130:133], v0 offset:13824
	s_waitcnt lgkmcnt(0)
	v_mfma_f32_32x32x16_bf16 v[18:33], v[174:177], v[130:133], v[18:33]
	v_mfma_f32_32x32x16_bf16 v[2:17], v[206:209], v[130:133], v[2:17]
	ds_read_b128 v[130:133], v0 offset:32
	s_waitcnt vmcnt(5) lgkmcnt(0)
	v_mfma_f32_32x32x16_bf16 v[114:129], v[170:173], v[130:133], v[114:129]
	s_waitcnt vmcnt(4)
	v_mfma_f32_32x32x16_bf16 v[98:113], v[166:169], v[130:133], v[98:113]
	ds_read_b128 v[130:133], v0 offset:4640
	s_waitcnt lgkmcnt(0)
	v_mfma_f32_32x32x16_bf16 v[82:97], v[170:173], v[130:133], v[82:97]
	v_mfma_f32_32x32x16_bf16 v[66:81], v[166:169], v[130:133], v[66:81]
	ds_read_b128 v[130:133], v0 offset:9248
	s_waitcnt lgkmcnt(0)
	v_mfma_f32_32x32x16_bf16 v[50:65], v[170:173], v[130:133], v[50:65]
	v_mfma_f32_32x32x16_bf16 v[34:49], v[166:169], v[130:133], v[34:49]
	ds_read_b128 v[130:133], v0 offset:13856
	s_waitcnt lgkmcnt(0)
; DI void phase_gemm_resid(const bf16_t* __restrict__ A, int K, const bf16_t* __restrict__ Bf, const float* xsrc, float* x,
;                          float scale, char* lds) {
;     ...
; #pragma unroll
;     for (int mi = 0; mi < 4; ++mi)
; #pragma unroll
;       for (int ni = 0; ni < 2; ++ni) {
;         float4 xs[4];
;         const size_t base = (size_t)(mt * 128 + 32 * mi + l31) * 1024 + nt * 256 + 64 * w + 32 * ni + 4 * h2;
; #pragma unroll
;         for (int g = 0; g < 4; ++g) xs[g] = *(const float4*)(xsrc + base + 8 * g);
; #pragma unroll
;         for (int g = 0; g < 4; ++g) {
;           float4 o;
;           o.x = xs[g].x + scale * a0[mi][ni][4 * g];
;           o.y = xs[g].y + scale * a0[mi][ni][4 * g + 1];
;           o.z = xs[g].z + scale * a0[mi][ni][4 * g + 2];
;           o.w = xs[g].w + scale * a0[mi][ni][4 * g + 3];
;           *(float4*)(x + base + 8 * g) = o;
;         }
;       }
	v_mfma_f32_32x32x16_bf16 v[18:33], v[170:173], v[130:133], v[18:33]
	v_mfma_f32_32x32x16_bf16 v[2:17], v[166:169], v[130:133], v[2:17]
	ds_read_b128 v[130:133], v0 offset:64
	s_waitcnt vmcnt(3) lgkmcnt(0)
	v_mfma_f32_32x32x16_bf16 v[114:129], v[158:161], v[130:133], v[114:129]
	s_waitcnt vmcnt(2)
	v_mfma_f32_32x32x16_bf16 v[98:113], v[162:165], v[130:133], v[98:113]
	ds_read_b128 v[130:133], v0 offset:4672
	s_waitcnt lgkmcnt(0)
	v_mfma_f32_32x32x16_bf16 v[82:97], v[158:161], v[130:133], v[82:97]
	v_mfma_f32_32x32x16_bf16 v[66:81], v[162:165], v[130:133], v[66:81]
	ds_read_b128 v[130:133], v0 offset:9280
	s_waitcnt lgkmcnt(0)
	v_mfma_f32_32x32x16_bf16 v[50:65], v[158:161], v[130:133], v[50:65]
	v_mfma_f32_32x32x16_bf16 v[34:49], v[162:165], v[130:133], v[34:49]
	ds_read_b128 v[130:133], v0 offset:13888
	s_waitcnt lgkmcnt(0)
	v_mfma_f32_32x32x16_bf16 v[18:33], v[158:161], v[130:133], v[18:33]
	v_mfma_f32_32x32x16_bf16 v[2:17], v[162:165], v[130:133], v[2:17]
	ds_read_b128 v[130:133], v0 offset:96
	s_waitcnt vmcnt(1) lgkmcnt(0)
	v_mfma_f32_32x32x16_bf16 v[114:129], v[154:157], v[130:133], v[114:129]
	s_waitcnt vmcnt(0)
	v_mfma_f32_32x32x16_bf16 v[98:113], v[150:153], v[130:133], v[98:113]
	ds_read_b128 v[130:133], v0 offset:4704
	s_waitcnt lgkmcnt(0)
	v_mfma_f32_32x32x16_bf16 v[82:97], v[154:157], v[130:133], v[82:97]
	v_mfma_f32_32x32x16_bf16 v[66:81], v[150:153], v[130:133], v[66:81]
	ds_read_b128 v[130:133], v0 offset:9312
	s_waitcnt lgkmcnt(0)
	v_mfma_f32_32x32x16_bf16 v[50:65], v[154:157], v[130:133], v[50:65]
	v_mfma_f32_32x32x16_bf16 v[34:49], v[150:153], v[130:133], v[34:49]
	ds_read_b128 v[130:133], v0 offset:13920
	s_waitcnt lgkmcnt(0)
	v_mfma_f32_32x32x16_bf16 v[18:33], v[154:157], v[130:133], v[18:33]
	v_mfma_f32_32x32x16_bf16 v[2:17], v[150:153], v[130:133], v[2:17]
	s_setprio 0
	v_lshl_add_u64 v[130:131], v[220:221], 0, s[28:29]
	v_lshl_or_b32 v0, s41, 17, v233
	v_lshl_add_u64 v[132:133], v[130:131], 0, v[0:1]
	v_lshlrev_b64 v[132:133], 2, v[132:133]
	v_lshl_add_u64 v[136:137], s[0:1], 0, v[132:133]
	s_barrier
	v_lshl_add_u64 v[138:139], s[24:25], 0, v[132:133]
	s_add_i32 s40, s40, 1
	s_mul_i32 s28, s40, s66
	s_add_i32 s28, s28, s3
	v_readlane_b32 s34, v243, 23
	s_cmp_ge_u32 s28, s34
	s_mov_b32 s100, 0x20000
	s_mov_b32 s101, 0
	v_lshl_add_u64 v[140:141], v[136:137], 0, s[100:101]
	v_lshl_add_u64 v[142:143], v[140:141], 0, s[100:101]
	v_lshl_add_u64 v[144:145], v[142:143], 0, s[100:101]
	v_lshl_add_u64 v[238:239], v[138:139], 0, s[100:101]
	v_lshl_add_u64 v[240:241], v[238:239], 0, s[100:101]
	v_lshl_add_u64 v[248:249], v[240:241], 0, s[100:101]
	global_load_dwordx4 v[146:149], v[136:137], off
	global_load_dwordx4 v[150:153], v[136:137], off offset:32
	global_load_dwordx4 v[154:157], v[136:137], off offset:64
	global_load_dwordx4 v[158:161], v[136:137], off offset:96
	global_load_dwordx4 v[162:165], v[136:137], off offset:128
	global_load_dwordx4 v[166:169], v[136:137], off offset:160
	global_load_dwordx4 v[170:173], v[136:137], off offset:192
	global_load_dwordx4 v[174:177], v[136:137], off offset:224
	global_load_dwordx4 v[178:181], v[140:141], off
	global_load_dwordx4 v[182:185], v[140:141], off offset:32
	global_load_dwordx4 v[186:189], v[140:141], off offset:64
	global_load_dwordx4 v[190:193], v[140:141], off offset:96
	global_load_dwordx4 v[194:197], v[140:141], off offset:128
	global_load_dwordx4 v[198:201], v[140:141], off offset:160
	global_load_dwordx4 v[202:205], v[140:141], off offset:192
	global_load_dwordx4 v[206:209], v[140:141], off offset:224
	s_waitcnt vmcnt(8)
	v_pk_fma_f32 v[114:115], v[114:115], 0.5, v[146:147] op_sel_hi:[1,0,1]
	v_pk_fma_f32 v[116:117], v[116:117], 0.5, v[148:149] op_sel_hi:[1,0,1]
	v_pk_fma_f32 v[118:119], v[118:119], 0.5, v[150:151] op_sel_hi:[1,0,1]
	v_pk_fma_f32 v[120:121], v[120:121], 0.5, v[152:153] op_sel_hi:[1,0,1]
	v_pk_fma_f32 v[122:123], v[122:123], 0.5, v[154:155] op_sel_hi:[1,0,1]
	v_pk_fma_f32 v[124:125], v[124:125], 0.5, v[156:157] op_sel_hi:[1,0,1]
	v_pk_fma_f32 v[126:127], v[126:127], 0.5, v[158:159] op_sel_hi:[1,0,1]
	v_pk_fma_f32 v[128:129], v[128:129], 0.5, v[160:161] op_sel_hi:[1,0,1]
	v_pk_fma_f32 v[98:99], v[98:99], 0.5, v[162:163] op_sel_hi:[1,0,1]
	v_pk_fma_f32 v[100:101], v[100:101], 0.5, v[164:165] op_sel_hi:[1,0,1]
	v_pk_fma_f32 v[102:103], v[102:103], 0.5, v[166:167] op_sel_hi:[1,0,1]
	v_pk_fma_f32 v[104:105], v[104:105], 0.5, v[168:169] op_sel_hi:[1,0,1]
	v_pk_fma_f32 v[106:107], v[106:107], 0.5, v[170:171] op_sel_hi:[1,0,1]
	v_pk_fma_f32 v[108:109], v[108:109], 0.5, v[172:173] op_sel_hi:[1,0,1]
	v_pk_fma_f32 v[110:111], v[110:111], 0.5, v[174:175] op_sel_hi:[1,0,1]
	v_pk_fma_f32 v[112:113], v[112:113], 0.5, v[176:177] op_sel_hi:[1,0,1]
	global_store_dwordx4 v[138:139], v[114:117], off
	global_store_dwordx4 v[138:139], v[118:121], off offset:32
	global_store_dwordx4 v[138:139], v[122:125], off offset:64
	global_store_dwordx4 v[138:139], v[126:129], off offset:96
	global_store_dwordx4 v[138:139], v[98:101], off offset:128
	global_store_dwordx4 v[138:139], v[102:105], off offset:160
	global_store_dwordx4 v[138:139], v[106:109], off offset:192
	global_store_dwordx4 v[138:139], v[110:113], off offset:224
	global_load_dwordx4 v[146:149], v[142:143], off
	global_load_dwordx4 v[150:153], v[142:143], off offset:32
	global_load_dwordx4 v[154:157], v[142:143], off offset:64
	global_load_dwordx4 v[158:161], v[142:143], off offset:96
	global_load_dwordx4 v[162:165], v[142:143], off offset:128
	global_load_dwordx4 v[166:169], v[142:143], off offset:160
	global_load_dwordx4 v[170:173], v[142:143], off offset:192
	global_load_dwordx4 v[174:177], v[142:143], off offset:224
	s_waitcnt vmcnt(16)
; DI void phase_gemm_resid(const bf16_t* __restrict__ A, int K, const bf16_t* __restrict__ Bf, const float* xsrc, float* x,
;                          float scale, char* lds) {
;     ...
; #pragma unroll
;     for (int mi = 0; mi < 4; ++mi)
; #pragma unroll
;       for (int ni = 0; ni < 2; ++ni) {
;         float4 xs[4];
;         const size_t base = (size_t)(mt * 128 + 32 * mi + l31) * 1024 + nt * 256 + 64 * w + 32 * ni + 4 * h2;
; #pragma unroll
;         for (int g = 0; g < 4; ++g) xs[g] = *(const float4*)(xsrc + base + 8 * g);
; #pragma unroll
;         for (int g = 0; g < 4; ++g) {
;           float4 o;
;           o.x = xs[g].x + scale * a0[mi][ni][4 * g];
;           o.y = xs[g].y + scale * a0[mi][ni][4 * g + 1];
;           o.z = xs[g].z + scale * a0[mi][ni][4 * g + 2];
;           o.w = xs[g].w + scale * a0[mi][ni][4 * g + 3];
;           *(float4*)(x + base + 8 * g) = o;
;         }
;       }
	v_pk_fma_f32 v[82:83], v[82:83], 0.5, v[178:179] op_sel_hi:[1,0,1]
	v_pk_fma_f32 v[84:85], v[84:85], 0.5, v[180:181] op_sel_hi:[1,0,1]
	v_pk_fma_f32 v[86:87], v[86:87], 0.5, v[182:183] op_sel_hi:[1,0,1]
	v_pk_fma_f32 v[88:89], v[88:89], 0.5, v[184:185] op_sel_hi:[1,0,1]
	v_pk_fma_f32 v[90:91], v[90:91], 0.5, v[186:187] op_sel_hi:[1,0,1]
	v_pk_fma_f32 v[92:93], v[92:93], 0.5, v[188:189] op_sel_hi:[1,0,1]
	v_pk_fma_f32 v[94:95], v[94:95], 0.5, v[190:191] op_sel_hi:[1,0,1]
	v_pk_fma_f32 v[96:97], v[96:97], 0.5, v[192:193] op_sel_hi:[1,0,1]
	v_pk_fma_f32 v[66:67], v[66:67], 0.5, v[194:195] op_sel_hi:[1,0,1]
	v_pk_fma_f32 v[68:69], v[68:69], 0.5, v[196:197] op_sel_hi:[1,0,1]
	v_pk_fma_f32 v[70:71], v[70:71], 0.5, v[198:199] op_sel_hi:[1,0,1]
	v_pk_fma_f32 v[72:73], v[72:73], 0.5, v[200:201] op_sel_hi:[1,0,1]
	v_pk_fma_f32 v[74:75], v[74:75], 0.5, v[202:203] op_sel_hi:[1,0,1]
	v_pk_fma_f32 v[76:77], v[76:77], 0.5, v[204:205] op_sel_hi:[1,0,1]
	v_pk_fma_f32 v[78:79], v[78:79], 0.5, v[206:207] op_sel_hi:[1,0,1]
	v_pk_fma_f32 v[80:81], v[80:81], 0.5, v[208:209] op_sel_hi:[1,0,1]
	global_store_dwordx4 v[238:239], v[82:85], off
	global_store_dwordx4 v[238:239], v[86:89], off offset:32
	global_store_dwordx4 v[238:239], v[90:93], off offset:64
	global_store_dwordx4 v[238:239], v[94:97], off offset:96
	global_store_dwordx4 v[238:239], v[66:69], off offset:128
	global_store_dwordx4 v[238:239], v[70:73], off offset:160
	global_store_dwordx4 v[238:239], v[74:77], off offset:192
	global_store_dwordx4 v[238:239], v[78:81], off offset:224
	global_load_dwordx4 v[178:181], v[144:145], off
	global_load_dwordx4 v[182:185], v[144:145], off offset:32
	global_load_dwordx4 v[186:189], v[144:145], off offset:64
	global_load_dwordx4 v[190:193], v[144:145], off offset:96
	global_load_dwordx4 v[194:197], v[144:145], off offset:128
	global_load_dwordx4 v[198:201], v[144:145], off offset:160
	global_load_dwordx4 v[202:205], v[144:145], off offset:192
	global_load_dwordx4 v[206:209], v[144:145], off offset:224
	s_waitcnt vmcnt(16)
	v_pk_fma_f32 v[50:51], v[50:51], 0.5, v[146:147] op_sel_hi:[1,0,1]
	v_pk_fma_f32 v[52:53], v[52:53], 0.5, v[148:149] op_sel_hi:[1,0,1]
	v_pk_fma_f32 v[54:55], v[54:55], 0.5, v[150:151] op_sel_hi:[1,0,1]
	v_pk_fma_f32 v[56:57], v[56:57], 0.5, v[152:153] op_sel_hi:[1,0,1]
	v_pk_fma_f32 v[58:59], v[58:59], 0.5, v[154:155] op_sel_hi:[1,0,1]
	v_pk_fma_f32 v[60:61], v[60:61], 0.5, v[156:157] op_sel_hi:[1,0,1]
	v_pk_fma_f32 v[62:63], v[62:63], 0.5, v[158:159] op_sel_hi:[1,0,1]
	v_pk_fma_f32 v[64:65], v[64:65], 0.5, v[160:161] op_sel_hi:[1,0,1]
	v_pk_fma_f32 v[34:35], v[34:35], 0.5, v[162:163] op_sel_hi:[1,0,1]
	v_pk_fma_f32 v[36:37], v[36:37], 0.5, v[164:165] op_sel_hi:[1,0,1]
	v_pk_fma_f32 v[38:39], v[38:39], 0.5, v[166:167] op_sel_hi:[1,0,1]
	v_pk_fma_f32 v[40:41], v[40:41], 0.5, v[168:169] op_sel_hi:[1,0,1]
	v_pk_fma_f32 v[42:43], v[42:43], 0.5, v[170:171] op_sel_hi:[1,0,1]
	v_pk_fma_f32 v[44:45], v[44:45], 0.5, v[172:173] op_sel_hi:[1,0,1]
	v_pk_fma_f32 v[46:47], v[46:47], 0.5, v[174:175] op_sel_hi:[1,0,1]
	v_pk_fma_f32 v[48:49], v[48:49], 0.5, v[176:177] op_sel_hi:[1,0,1]
	global_store_dwordx4 v[240:241], v[50:53], off
	global_store_dwordx4 v[240:241], v[54:57], off offset:32
	global_store_dwordx4 v[240:241], v[58:61], off offset:64
	global_store_dwordx4 v[240:241], v[62:65], off offset:96
	global_store_dwordx4 v[240:241], v[34:37], off offset:128
	global_store_dwordx4 v[240:241], v[38:41], off offset:160
	global_store_dwordx4 v[240:241], v[42:45], off offset:192
	global_store_dwordx4 v[240:241], v[46:49], off offset:224
	s_waitcnt vmcnt(8)
	v_pk_fma_f32 v[18:19], v[18:19], 0.5, v[178:179] op_sel_hi:[1,0,1]
	v_pk_fma_f32 v[20:21], v[20:21], 0.5, v[180:181] op_sel_hi:[1,0,1]
	v_pk_fma_f32 v[22:23], v[22:23], 0.5, v[182:183] op_sel_hi:[1,0,1]
	v_pk_fma_f32 v[24:25], v[24:25], 0.5, v[184:185] op_sel_hi:[1,0,1]
	v_pk_fma_f32 v[26:27], v[26:27], 0.5, v[186:187] op_sel_hi:[1,0,1]
	v_pk_fma_f32 v[28:29], v[28:29], 0.5, v[188:189] op_sel_hi:[1,0,1]
	v_pk_fma_f32 v[30:31], v[30:31], 0.5, v[190:191] op_sel_hi:[1,0,1]
	v_pk_fma_f32 v[32:33], v[32:33], 0.5, v[192:193] op_sel_hi:[1,0,1]
	v_pk_fma_f32 v[2:3], v[2:3], 0.5, v[194:195] op_sel_hi:[1,0,1]
	v_pk_fma_f32 v[4:5], v[4:5], 0.5, v[196:197] op_sel_hi:[1,0,1]
	v_pk_fma_f32 v[6:7], v[6:7], 0.5, v[198:199] op_sel_hi:[1,0,1]
	v_pk_fma_f32 v[8:9], v[8:9], 0.5, v[200:201] op_sel_hi:[1,0,1]
	v_pk_fma_f32 v[10:11], v[10:11], 0.5, v[202:203] op_sel_hi:[1,0,1]
	v_pk_fma_f32 v[12:13], v[12:13], 0.5, v[204:205] op_sel_hi:[1,0,1]
	v_pk_fma_f32 v[14:15], v[14:15], 0.5, v[206:207] op_sel_hi:[1,0,1]
	v_pk_fma_f32 v[16:17], v[16:17], 0.5, v[208:209] op_sel_hi:[1,0,1]
	global_store_dwordx4 v[248:249], v[18:21], off
	global_store_dwordx4 v[248:249], v[22:25], off offset:32
	global_store_dwordx4 v[248:249], v[26:29], off offset:64
	global_store_dwordx4 v[248:249], v[30:33], off offset:96
	global_store_dwordx4 v[248:249], v[2:5], off offset:128
	global_store_dwordx4 v[248:249], v[6:9], off offset:160
	global_store_dwordx4 v[248:249], v[10:13], off offset:192
	global_store_dwordx4 v[248:249], v[14:17], off offset:224
	s_cbranch_scc0 .LBB0_272

; DI unsigned pack2(float a, float b) { f2_t v = {a, b}; return __builtin_bit_cast(unsigned, __builtin_convertvector(v, bf2_t)); }
; DI void phase_norm(const float* __restrict__ x, const float* __restrict__ g, bf16_t* __restrict__ dst,
;                            const float* __restrict__ psrc, bf16_t* __restrict__ pdst) {
;     ...
;   for (int r = blockIdx.x * 4 + wave; r < TG; r += gridDim.x * 4) {
;     const float4* xr = (const float4*)(x + (size_t)r * 1024);
;     float4 v[4];
;     float ss = 0.f;
; #pragma unroll
;     for (int i = 0; i < 4; ++i) { v[i] = xr[lane + 64 * i]; ss += v[i].x * v[i].x + v[i].y * v[i].y + v[i].z * v[i].z + v[i].w * v[i].w; }
;     ss = wave_sum(ss);
;     const float rs = rsqrtf(ss * (1.f / 1024.f) + EPS);
; #pragma unroll
;     for (int i = 0; i < 4; ++i) {
;       const float4 gg = ((const float4*)g)[lane + 64 * i];
;       u32x2 o; o.x = pack2(v[i].x * rs * gg.x, v[i].y * rs * gg.y); o.y = pack2(v[i].z * rs * gg.z, v[i].w * rs * gg.w);
;       ((u32x2*)(dst + (size_t)r * 1024))[lane + 64 * i] = o;
;     }
.LBB0_325:
	v_ashrrev_i32_e32 v19, 31, v18
	v_lshlrev_b64 v[30:31], 12, v[18:19]
	v_lshl_add_u64 v[42:43], v[20:21], 0, v[30:31]
	v_lshlrev_b64 v[34:35], 11, v[18:19]
	global_load_dwordx4 v[30:33], v[42:43], off
	v_lshl_add_u64 v[46:47], v[22:23], 0, v[34:35]
	global_load_dwordx4 v[34:37], v[42:43], off offset:1024
	global_load_dwordx4 v[58:61], v[42:43], off offset:2048
	global_load_dwordx4 v[62:65], v[42:43], off offset:3072
	v_add_u32_e32 v18, s56, v18
	s_waitcnt vmcnt(3)
	v_mov_b32_e32 v48, v31
	v_mov_b32_e32 v44, v30
	s_waitcnt vmcnt(2)
	v_mov_b32_e32 v49, v35
	v_mov_b32_e32 v45, v34
	v_pk_mul_f32 v[48:49], v[48:49], v[48:49]
	v_mov_b32_e32 v38, v32
	v_mov_b32_e32 v39, v36
	v_pk_fma_f32 v[44:45], v[44:45], v[44:45], v[48:49]
	v_mov_b32_e32 v40, v33
	v_mov_b32_e32 v41, v37
	v_pk_fma_f32 v[38:39], v[38:39], v[38:39], v[44:45]
	s_nop 0
	v_pk_fma_f32 v[48:49], v[40:41], v[40:41], v[38:39]
	v_add_f32_e32 v0, v48, v49
	s_waitcnt vmcnt(1)
	v_mov_b32_e32 v56, v59
	s_waitcnt vmcnt(0)
	v_mov_b32_e32 v57, v63
	v_mov_b32_e32 v54, v58
	v_mov_b32_e32 v55, v62
	v_pk_mul_f32 v[56:57], v[56:57], v[56:57]
	v_mov_b32_e32 v50, v60
	v_mov_b32_e32 v51, v64
	v_pk_fma_f32 v[54:55], v[54:55], v[54:55], v[56:57]
	v_mov_b32_e32 v52, v61
	v_mov_b32_e32 v53, v65
	v_pk_fma_f32 v[50:51], v[50:51], v[50:51], v[54:55]
	s_nop 0
	v_pk_fma_f32 v[50:51], v[52:53], v[52:53], v[50:51]
	s_nop 0
	v_add_f32_e32 v0, v0, v50
	v_add_f32_e32 v0, v0, v51
	ds_bpermute_b32 v19, v24, v0
	s_waitcnt lgkmcnt(0)
	v_add_f32_e32 v0, v0, v19
	ds_bpermute_b32 v19, v25, v0
	s_waitcnt lgkmcnt(0)
	v_add_f32_e32 v0, v0, v19
	ds_bpermute_b32 v19, v26, v0
	s_waitcnt lgkmcnt(0)
	v_add_f32_e32 v0, v0, v19
	ds_bpermute_b32 v19, v27, v0
	s_waitcnt lgkmcnt(0)
	v_add_f32_e32 v0, v0, v19
	ds_bpermute_b32 v19, v28, v0
	s_waitcnt lgkmcnt(0)
	v_add_f32_e32 v0, v0, v19
	ds_bpermute_b32 v19, v29, v0
	s_waitcnt lgkmcnt(0)
	v_add_f32_e32 v0, v0, v19
	v_fmamk_f32 v0, v0, 0x3a800000, v216
	v_cmp_gt_f32_e32 vcc, s15, v0
	v_mul_f32_e32 v19, 0x4b800000, v0
	s_nop 0
	v_cndmask_b32_e32 v0, v0, v19, vcc
	v_rsq_f32_e32 v0, v0
	s_nop 0
	v_mul_f32_e32 v19, 0x45800000, v0
	v_cndmask_b32_e32 v0, v0, v19, vcc
	v_pk_mul_f32 v[30:31], v[30:31], v[0:1] op_sel_hi:[1,0]
	v_pk_mul_f32 v[32:33], v[32:33], v[0:1] op_sel_hi:[1,0]
	v_pk_mul_f32 v[30:31], v[2:3], v[30:31]
	v_pk_mul_f32 v[32:33], v[4:5], v[32:33]
	v_cvt_pk_bf16_f32 v30, v30, v31
	v_cvt_pk_bf16_f32 v31, v32, v33
	global_store_dwordx2 v[46:47], v[30:31], off
	v_pk_mul_f32 v[30:31], v[34:35], v[0:1] op_sel_hi:[1,0]
	v_pk_mul_f32 v[32:33], v[36:37], v[0:1] op_sel_hi:[1,0]
	v_pk_mul_f32 v[30:31], v[6:7], v[30:31]
	v_pk_mul_f32 v[32:33], v[8:9], v[32:33]
	v_cvt_pk_bf16_f32 v30, v30, v31
	v_cvt_pk_bf16_f32 v31, v32, v33
	global_store_dwordx2 v[46:47], v[30:31], off offset:512
	v_pk_mul_f32 v[30:31], v[58:59], v[0:1] op_sel_hi:[1,0]
	v_pk_mul_f32 v[32:33], v[60:61], v[0:1] op_sel_hi:[1,0]
	v_pk_mul_f32 v[30:31], v[10:11], v[30:31]
	v_pk_mul_f32 v[32:33], v[12:13], v[32:33]
	v_cvt_pk_bf16_f32 v30, v30, v31
	v_cvt_pk_bf16_f32 v31, v32, v33
	global_store_dwordx2 v[46:47], v[30:31], off offset:1024
	v_pk_mul_f32 v[30:31], v[62:63], v[0:1] op_sel_hi:[1,0]
	v_pk_mul_f32 v[32:33], v[64:65], v[0:1] op_sel_hi:[1,0]
	v_pk_mul_f32 v[30:31], v[14:15], v[30:31]
	v_pk_mul_f32 v[32:33], v[16:17], v[32:33]
	v_cmp_lt_i32_e32 vcc, s28, v18
	v_cvt_pk_bf16_f32 v30, v30, v31
	v_cvt_pk_bf16_f32 v31, v32, v33
	s_or_b64 s[6:7], vcc, s[6:7]
	global_store_dwordx2 v[46:47], v[30:31], off offset:1536
	s_andn2_b64 exec, exec, s[6:7]
	s_cbranch_execnz .LBB0_325

; #define MFMA16(a, b, c) __builtin_amdgcn_mfma_f32_16x16x32_bf16((a), (b), (c), 0, 0, 0)
; DI float bf2f(bf16_t b) { return __uint_as_float(((unsigned)b) << 16); }
; DI void dn_scan_chain(CParams& p, int it, int S, char* lds) {
;     ...
;     __syncthreads();
;     {
;       bf16x8 Bs[2];
; #pragma unroll
;       for (int ks = 0; ks < 2; ++ks)
;         Bs[ks] = pack8(Sd[2 * ks][0], Sd[2 * ks][1], Sd[2 * ks][2], Sd[2 * ks][3], Sd[2 * ks + 1][0], Sd[2 * ks + 1][1],
;                        Sd[2 * ks + 1][2], Sd[2 * ks + 1][3]);
;       f32x4 vn[4], qs[4], iv[4];
; #pragma unroll
;       for (int rt = 0; rt < 4; ++rt) {
; #pragma unroll
;         for (int r = 0; r < 4; ++r) vn[rt][r] = bf2f(Uimg[(16 * rt + 4 * g4 + r) * 72 + e_col]);
;         qs[rt] = f32x4{0.f, 0.f, 0.f, 0.f};
;         iv[rt] = f32x4{0.f, 0.f, 0.f, 0.f};
; #pragma unroll
;         for (int ks = 0; ks < 2; ++ks) {
;           const bf16_t* wp = Wn + (16 * rt + l15) * 72 + 32 * ks + 4 * g4;
;           const bf16_t* qp = Qimg + (16 * rt + l15) * 72 + 32 * ks + 4 * g4;
;           vn[rt] = MFMA16(ld2x4(wp, wp + 16), Bs[ks], vn[rt]);
;           qs[rt] = MFMA16(ld2x4(qp, qp + 16), Bs[ks], qs[rt]);
;         }
;       }
;       bf16x8 Bv[2];
; #pragma unroll
;       for (int ks = 0; ks < 2; ++ks)
;         Bv[ks] = pack8(vn[2 * ks][0], vn[2 * ks][1], vn[2 * ks][2], vn[2 * ks][3], vn[2 * ks + 1][0], vn[2 * ks + 1][1],
;                        vn[2 * ks + 1][2], vn[2 * ks + 1][3]);
; #pragma unroll
;       for (int rt = 0; rt < 4; ++rt)
; #pragma unroll
;         for (int ks = 0; ks < 2; ++ks) {
;           const bf16_t* ip = Iimg + (16 * rt + l15) * 72 + 32 * ks + 4 * g4;
;           iv[rt] = MFMA16(ld2x4(ip, ip + 16), Bv[ks], iv[rt]);
;         }
.LBB0_609:
	s_or_b64 exec, exec, s[6:7]
	v_lshl_add_u32 v59, v98, 1, 16
	v_add_u32_e32 v71, v59, v62
	v_mul_u32_u24_e32 v62, 0x48, v68
	ds_write_b16 v63, v50 offset:53280
	v_lshlrev_b32_e32 v63, 1, v0
	v_lshlrev_b32_e32 v62, 1, v62
	v_add3_u32 v72, 16, v63, v62
	v_add_u32_e32 v66, 0x2000, v72
	s_waitcnt lgkmcnt(0)
	s_barrier
	s_add_i32 s8, s41, -1
	s_and_b64 s[6:7], vcc, exec
	s_cselect_b32 s6, s8, s62
	s_lshl_b32 s6, s6, 6
	s_ashr_i32 s7, s6, 31
	s_add_u32 s6, s6, s28
	s_addc_u32 s7, s7, s40
	s_add_i32 s62, s62, -1
	s_add_i32 s41, s41, 1
	s_cmp_lg_u32 s62, -1
	ds_read_b32 v117, v229 offset:55548
	v_cvt_pk_bf16_f32 v50, v34, v35
	v_cvt_pk_bf16_f32 v51, v36, v37
	v_cvt_pk_bf16_f32 v52, v38, v39
	v_cvt_pk_bf16_f32 v53, v40, v41
	v_cvt_pk_bf16_f32 v54, v46, v47
	v_cvt_pk_bf16_f32 v55, v48, v49
	v_cvt_pk_bf16_f32 v56, v42, v43
	v_cvt_pk_bf16_f32 v57, v44, v45
	v_lshlrev_b32_e32 v100, 3, v69
	v_add_u32_e32 v101, 16, v100
	v_add_u32_e32 v108, v101, v70
	v_add_u32_e32 v125, v101, v100
	v_lshl_add_u32 v128, v69, 4, 16
	s_waitcnt lgkmcnt(0)
	v_lshlrev_b32_e32 v58, 16, v194
	v_lshlrev_b32_e32 v59, 16, v195
	v_lshlrev_b32_e32 v60, 16, v196
	v_lshlrev_b32_e32 v61, 16, v197
	s_nop 1
	v_mfma_f32_16x16x32_bf16 v[58:61], v[130:133], v[50:53], v[58:61]
	v_mfma_f32_16x16x32_bf16 v[62:65], v[138:141], v[50:53], 0
	v_mfma_f32_16x16x32_bf16 v[74:77], v[134:137], v[54:57], v[58:61]
	v_mfma_f32_16x16x32_bf16 v[78:81], v[142:145], v[54:57], v[62:65]
	ds_read_b64 v[130:131], v126 offset:46080
	ds_read_b64 v[132:133], v126 offset:46112
	ds_read_b64 v[134:135], v126 offset:46144
	ds_read_b64 v[136:137], v126 offset:46176
	ds_read_b64 v[138:139], v126 offset:48384
	ds_read_b64 v[140:141], v126 offset:48416
	ds_read_b64 v[142:143], v126 offset:48448
	ds_read_b64 v[144:145], v126 offset:48480
	v_lshlrev_b32_e32 v58, 16, v198
	v_lshlrev_b32_e32 v59, 16, v199
	v_lshlrev_b32_e32 v60, 16, v200
	v_lshlrev_b32_e32 v61, 16, v201
	s_nop 1
	v_mfma_f32_16x16x32_bf16 v[58:61], v[146:149], v[50:53], v[58:61]
	v_mfma_f32_16x16x32_bf16 v[62:65], v[154:157], v[50:53], 0
	v_mfma_f32_16x16x32_bf16 v[82:85], v[150:153], v[54:57], v[58:61]
	v_mfma_f32_16x16x32_bf16 v[86:89], v[158:161], v[54:57], v[62:65]
	ds_read_b64 v[146:147], v126 offset:50688
	ds_read_b64 v[148:149], v126 offset:50720
	ds_read_b64 v[150:151], v126 offset:50752
	ds_read_b64 v[152:153], v126 offset:50784
	ds_read_b64 v[154:155], v126 offset:52992
	ds_read_b64 v[156:157], v126 offset:53024
	ds_read_b64 v[158:159], v126 offset:53056
	ds_read_b64 v[160:161], v126 offset:53088
	v_lshlrev_b32_e32 v58, 16, v202
	v_lshlrev_b32_e32 v59, 16, v203
	v_lshlrev_b32_e32 v60, 16, v204
	v_lshlrev_b32_e32 v61, 16, v205
	s_nop 1
	v_mfma_f32_16x16x32_bf16 v[58:61], v[162:165], v[50:53], v[58:61]
	v_mfma_f32_16x16x32_bf16 v[66:69], v[170:173], v[50:53], 0
	v_mfma_f32_16x16x32_bf16 v[62:65], v[166:169], v[54:57], v[58:61]
	v_mfma_f32_16x16x32_bf16 v[66:69], v[174:177], v[54:57], v[66:69]
	ds_read_b64 v[162:163], v126 offset:36864
	ds_read_b64 v[164:165], v126 offset:36896
	ds_read_b64 v[166:167], v126 offset:36928
	ds_read_b64 v[168:169], v126 offset:36960
	ds_read_b64 v[170:171], v126 offset:39168
	ds_read_b64 v[172:173], v126 offset:39200
	ds_read_b64 v[174:175], v126 offset:39232
	ds_read_b64 v[176:177], v126 offset:39264
	v_lshlrev_b32_e32 v58, 16, v206
	v_lshlrev_b32_e32 v59, 16, v207
	v_lshlrev_b32_e32 v60, 16, v208
	v_lshlrev_b32_e32 v61, 16, v209
	s_nop 1
	v_mfma_f32_16x16x32_bf16 v[58:61], v[178:181], v[50:53], v[58:61]
	v_mfma_f32_16x16x32_bf16 v[90:93], v[186:189], v[50:53], 0
	v_mfma_f32_16x16x32_bf16 v[50:53], v[182:185], v[54:57], v[58:61]
	v_mfma_f32_16x16x32_bf16 v[54:57], v[190:193], v[54:57], v[90:93]
	ds_read_b64 v[178:179], v126 offset:41472
	ds_read_b64 v[180:181], v126 offset:41504
	ds_read_b64 v[182:183], v126 offset:41536
	ds_read_b64 v[184:185], v126 offset:41568
	ds_read_b64 v[186:187], v126 offset:43776
	ds_read_b64 v[188:189], v126 offset:43808
	ds_read_b64 v[190:191], v126 offset:43840
	ds_read_b64 v[192:193], v126 offset:43872
	ds_read_b128 v[194:197], v128 offset:55296
	ds_read_b128 v[198:201], v128 offset:55360
	ds_read_b128 v[202:205], v128 offset:55424
	ds_read_b128 v[206:209], v128 offset:55488
	s_nop 7
	v_cvt_pk_bf16_f32 v102, v62, v63
	v_cvt_pk_bf16_f32 v103, v64, v65
	v_cvt_pk_bf16_f32 v104, v50, v51
	v_cvt_pk_bf16_f32 v105, v52, v53
	v_cvt_pk_bf16_f32 v58, v74, v75
	v_cvt_pk_bf16_f32 v59, v76, v77
	v_cvt_pk_bf16_f32 v60, v82, v83
	v_cvt_pk_bf16_f32 v61, v84, v85
	s_waitcnt lgkmcnt(0)
; #define MFMA16(a, b, c) __builtin_amdgcn_mfma_f32_16x16x32_bf16((a), (b), (c), 0, 0, 0)
; DI void dn_scan_chain(CParams& p, int it, int S, char* lds) {
;     ...
; #pragma unroll
;       for (int rt = 0; rt < 4; ++rt)
; #pragma unroll
;         for (int ks = 0; ks < 2; ++ks) {
;           const bf16_t* ip = Iimg + (16 * rt + l15) * 72 + 32 * ks + 4 * g4;
;           iv[rt] = MFMA16(ld2x4(ip, ip + 16), Bv[ks], iv[rt]);
;         }
;       const float gc63 = gcs[63];
; #pragma unroll
;       for (int rt = 0; rt < 4; ++rt)
; #pragma unroll
;         for (int r = 0; r < 4; ++r) {
;           const int pos = 16 * rt + 4 * g4 + r;
;           const float o = qs[rt][r] * __expf(gcs[pos]) + iv[rt][r];
;           const int i = dir ? 63 - pos : pos;
;           OUT[((size_t)tokbase + s0 + i) * 256 + h * 64 + e_col] = f2bf(o);
;           vn[rt][r] *= __expf(gc63 - gcs[pos]);
;         }
	s_nop 1
	v_mfma_f32_16x16x32_bf16 v[94:97], v[130:133], v[58:61], 0
	v_mfma_f32_16x16x32_bf16 v[90:93], v[138:141], v[58:61], 0
	v_mfma_f32_16x16x32_bf16 v[70:73], v[146:149], v[58:61], 0
	v_mfma_f32_16x16x32_bf16 v[94:97], v[134:137], v[102:105], v[94:97]
	v_mfma_f32_16x16x32_bf16 v[90:93], v[142:145], v[102:105], v[90:93]
	v_mfma_f32_16x16x32_bf16 v[70:73], v[150:153], v[102:105], v[70:73]
	v_mfma_f32_16x16x32_bf16 v[58:61], v[154:157], v[58:61], 0
	v_mfma_f32_16x16x32_bf16 v[58:61], v[158:161], v[102:105], v[58:61]
	v_ashrrev_i32_e32 v99, 31, v98
	v_lshl_add_u64 v[102:103], v[98:99], 1, s[42:43]
	v_mov_b32_e32 v98, v194
	v_mov_b32_e32 v99, v195
	v_mov_b32_e32 v100, v196
	v_mov_b32_e32 v101, v197
	v_mov_b32_e32 v105, s7
	s_nop 1
	v_mul_f32_e32 v104, 0x3fb8aa3b, v98
	v_exp_f32_e32 v104, v104
	s_nop 0
	v_fma_f32 v78, v78, v104, v94
	v_xor_b32_e32 v94, 63, v0
	v_cndmask_b32_e32 v94, v94, v0, vcc
	v_or_b32_e32 v104, s6, v94
	v_mul_f32_e32 v94, 0x3fb8aa3b, v99
	v_exp_f32_e32 v94, v94
	v_lshlrev_b64 v[126:127], 9, v[104:105]
	v_cvt_pk_bf16_f32 v78, v78, s0
	v_lshl_add_u64 v[126:127], v[102:103], 0, v[126:127]
	v_fma_f32 v79, v79, v94, v95
	v_xor_b32_e32 v94, 62, v0
	v_cndmask_b32_e32 v94, v94, v124, vcc
	v_or_b32_e32 v104, s6, v94
	v_lshlrev_b64 v[94:95], 9, v[104:105]
	v_cvt_pk_bf16_f32 v79, v79, s0
	v_lshl_add_u64 v[94:95], v[102:103], 0, v[94:95]
	global_store_short v[126:127], v78, off
	v_sub_f32_e32 v78, v117, v98
	global_store_short v[94:95], v79, off
	v_sub_f32_e32 v79, v117, v99
	v_mul_f32_e32 v78, 0x3fb8aa3b, v78
	v_mul_f32_e32 v79, 0x3fb8aa3b, v79
	v_exp_f32_e32 v78, v78
	v_exp_f32_e32 v79, v79
	s_nop 0
	v_pk_mul_f32 v[78:79], v[74:75], v[78:79]
	v_mul_f32_e32 v74, 0x3fb8aa3b, v100
	v_exp_f32_e32 v74, v74
	v_xor_b32_e32 v75, 61, v0
	v_cndmask_b32_e32 v75, v75, v123, vcc
	v_or_b32_e32 v104, s6, v75
	v_fma_f32 v74, v80, v74, v96
	v_cvt_pk_bf16_f32 v80, v74, s0
	v_lshlrev_b64 v[74:75], 9, v[104:105]
	v_lshl_add_u64 v[74:75], v[102:103], 0, v[74:75]
	global_store_short v[74:75], v80, off
	v_mul_f32_e32 v75, 0x3fb8aa3b, v101
	v_exp_f32_e32 v75, v75
	v_sub_f32_e32 v74, v117, v100
	v_mul_f32_e32 v74, 0x3fb8aa3b, v74
	v_exp_f32_e32 v74, v74
	v_fmac_f32_e32 v97, v81, v75
	v_xor_b32_e32 v75, 60, v0
	v_cndmask_b32_e32 v75, v75, v121, vcc
	v_or_b32_e32 v104, s6, v75
	v_sub_f32_e32 v75, v117, v101
	v_mul_f32_e32 v75, 0x3fb8aa3b, v75
	v_exp_f32_e32 v75, v75
	v_lshlrev_b64 v[80:81], 9, v[104:105]
	v_cvt_pk_bf16_f32 v94, v97, s0
	v_lshl_add_u64 v[80:81], v[102:103], 0, v[80:81]
	global_store_short v[80:81], v94, off
	v_pk_mul_f32 v[80:81], v[76:77], v[74:75]
	v_mov_b32_e32 v74, v198
	v_mov_b32_e32 v75, v199
	v_mov_b32_e32 v76, v200
	v_mov_b32_e32 v77, v201
	s_nop 1
	v_mul_f32_e32 v94, 0x3fb8aa3b, v74
	v_exp_f32_e32 v94, v94
	v_sub_f32_e32 v74, v117, v74
	v_mul_f32_e32 v74, 0x3fb8aa3b, v74
	v_exp_f32_e32 v74, v74
	v_fma_f32 v86, v86, v94, v90
	v_xor_b32_e32 v90, 47, v0
	v_cndmask_b32_e32 v90, v90, v118, vcc
	v_or_b32_e32 v104, s6, v90
	v_lshlrev_b64 v[94:95], 9, v[104:105]
	v_cvt_pk_bf16_f32 v86, v86, s0
	v_lshl_add_u64 v[94:95], v[102:103], 0, v[94:95]
	global_store_short v[94:95], v86, off
	v_mul_f32_e32 v86, 0x3fb8aa3b, v75
	v_sub_f32_e32 v75, v117, v75
	v_mul_f32_e32 v75, 0x3fb8aa3b, v75
	v_exp_f32_e32 v75, v75
	v_exp_f32_e32 v86, v86
	v_pk_mul_f32 v[82:83], v[82:83], v[74:75]
	v_mul_f32_e32 v74, 0x3fb8aa3b, v76
	v_fma_f32 v86, v87, v86, v91
	v_xor_b32_e32 v87, 46, v0
	v_exp_f32_e32 v74, v74
	v_cndmask_b32_e32 v87, v87, v119, vcc
	v_or_b32_e32 v104, s6, v87
	v_xor_b32_e32 v75, 45, v0
	v_cvt_pk_bf16_f32 v90, v86, s0
	v_lshlrev_b64 v[86:87], 9, v[104:105]
	v_cndmask_b32_e32 v75, v75, v120, vcc
	v_lshl_add_u64 v[86:87], v[102:103], 0, v[86:87]
	v_fma_f32 v74, v88, v74, v92
	v_or_b32_e32 v104, s6, v75
	global_store_short v[86:87], v90, off
	v_cvt_pk_bf16_f32 v86, v74, s0
	v_lshlrev_b64 v[74:75], 9, v[104:105]
	v_lshl_add_u64 v[74:75], v[102:103], 0, v[74:75]
	global_store_short v[74:75], v86, off
	v_mul_f32_e32 v75, 0x3fb8aa3b, v77
	v_exp_f32_e32 v75, v75
	v_sub_f32_e32 v74, v117, v76
	v_mul_f32_e32 v74, 0x3fb8aa3b, v74
	v_exp_f32_e32 v74, v74
	v_fmac_f32_e32 v93, v89, v75
	v_xor_b32_e32 v75, 44, v0
	v_cndmask_b32_e32 v75, v75, v122, vcc
	v_or_b32_e32 v104, s6, v75
	v_sub_f32_e32 v75, v117, v77
	v_mul_f32_e32 v75, 0x3fb8aa3b, v75
	v_exp_f32_e32 v75, v75
	v_lshlrev_b64 v[86:87], 9, v[104:105]
	v_cvt_pk_bf16_f32 v76, v93, s0
	v_lshl_add_u64 v[86:87], v[102:103], 0, v[86:87]
	global_store_short v[86:87], v76, off
	v_pk_mul_f32 v[84:85], v[84:85], v[74:75]
	v_mov_b32_e32 v74, v202
	v_mov_b32_e32 v75, v203
	v_mov_b32_e32 v76, v204
	v_mov_b32_e32 v77, v205
	s_nop 1
	v_mul_f32_e32 v86, 0x3fb8aa3b, v74
	v_exp_f32_e32 v86, v86
	s_nop 0
	v_fma_f32 v66, v66, v86, v70
	v_xor_b32_e32 v70, 31, v0
	v_cndmask_b32_e32 v70, v70, v116, vcc
	v_or_b32_e32 v104, s6, v70
	v_mul_f32_e32 v70, 0x3fb8aa3b, v75
	v_exp_f32_e32 v70, v70
	v_lshlrev_b64 v[86:87], 9, v[104:105]
	v_cvt_pk_bf16_f32 v66, v66, s0
; #define MFMA16(a, b, c) __builtin_amdgcn_mfma_f32_16x16x32_bf16((a), (b), (c), 0, 0, 0)
; DI void dn_scan_chain(CParams& p, int it, int S, char* lds) {
;     ...
;       const float gc63 = gcs[63];
; #pragma unroll
;       for (int rt = 0; rt < 4; ++rt)
; #pragma unroll
;         for (int r = 0; r < 4; ++r) {
;           const int pos = 16 * rt + 4 * g4 + r;
;           const float o = qs[rt][r] * __expf(gcs[pos]) + iv[rt][r];
;           const int i = dir ? 63 - pos : pos;
;           OUT[((size_t)tokbase + s0 + i) * 256 + h * 64 + e_col] = f2bf(o);
;           vn[rt][r] *= __expf(gc63 - gcs[pos]);
;         }
;       bf16x8 Bv2[2];
; #pragma unroll
;       for (int ks = 0; ks < 2; ++ks)
;         Bv2[ks] = pack8(vn[2 * ks][0], vn[2 * ks][1], vn[2 * ks][2], vn[2 * ks][3], vn[2 * ks + 1][0], vn[2 * ks + 1][1],
;                         vn[2 * ks + 1][2], vn[2 * ks + 1][3]);
;       const float gl = __expf(gc63);
; #pragma unroll
;       for (int dt = 0; dt < 4; ++dt) {
; #pragma unroll
;         for (int r = 0; r < 4; ++r) Sd[dt][r] *= gl;
; #pragma unroll
;         for (int ks = 0; ks < 2; ++ks) {
;           const bf16_t* kp = Kt + (16 * dt + l15) * 72 + 32 * ks + 4 * g4;
;           Sd[dt] = MFMA16(ld2x4(kp, kp + 16), Bv2[ks], Sd[dt]);
;         }
;       }
	v_lshl_add_u64 v[86:87], v[102:103], 0, v[86:87]
	v_fma_f32 v67, v67, v70, v71
	v_xor_b32_e32 v70, 30, v0
	v_cndmask_b32_e32 v70, v70, v115, vcc
	v_or_b32_e32 v104, s6, v70
	v_lshlrev_b64 v[70:71], 9, v[104:105]
	v_cvt_pk_bf16_f32 v67, v67, s0
	v_lshl_add_u64 v[70:71], v[102:103], 0, v[70:71]
	global_store_short v[86:87], v66, off
	v_sub_f32_e32 v66, v117, v74
	global_store_short v[70:71], v67, off
	v_sub_f32_e32 v67, v117, v75
	v_mul_f32_e32 v66, 0x3fb8aa3b, v66
	v_mul_f32_e32 v67, 0x3fb8aa3b, v67
	v_exp_f32_e32 v66, v66
	v_exp_f32_e32 v67, v67
	s_nop 0
	v_pk_mul_f32 v[62:63], v[62:63], v[66:67]
	v_mul_f32_e32 v66, 0x3fb8aa3b, v76
	v_exp_f32_e32 v66, v66
	v_xor_b32_e32 v67, 29, v0
	v_cndmask_b32_e32 v67, v67, v114, vcc
	v_or_b32_e32 v104, s6, v67
	v_fma_f32 v66, v68, v66, v72
	v_cvt_pk_bf16_f32 v68, v66, s0
	v_lshlrev_b64 v[66:67], 9, v[104:105]
	v_lshl_add_u64 v[66:67], v[102:103], 0, v[66:67]
	global_store_short v[66:67], v68, off
	v_mul_f32_e32 v67, 0x3fb8aa3b, v77
	v_exp_f32_e32 v67, v67
	v_sub_f32_e32 v66, v117, v76
	v_mul_f32_e32 v66, 0x3fb8aa3b, v66
	v_exp_f32_e32 v66, v66
	v_fmac_f32_e32 v73, v69, v67
	v_xor_b32_e32 v67, 28, v0
	v_cndmask_b32_e32 v67, v67, v113, vcc
	v_or_b32_e32 v104, s6, v67
	v_sub_f32_e32 v67, v117, v77
	v_mul_f32_e32 v67, 0x3fb8aa3b, v67
	v_exp_f32_e32 v67, v67
	v_lshlrev_b64 v[68:69], 9, v[104:105]
	v_cvt_pk_bf16_f32 v70, v73, s0
	v_lshl_add_u64 v[68:69], v[102:103], 0, v[68:69]
	global_store_short v[68:69], v70, off
	v_pk_mul_f32 v[68:69], v[64:65], v[66:67]
	v_mov_b32_e32 v64, v206
	v_mov_b32_e32 v65, v207
	v_mov_b32_e32 v66, v208
	v_mov_b32_e32 v67, v209
	s_nop 1
	v_mul_f32_e32 v70, 0x3fb8aa3b, v64
	v_exp_f32_e32 v70, v70
	s_nop 0
	v_fma_f32 v54, v54, v70, v58
	v_xor_b32_e32 v58, 15, v0
	v_cndmask_b32_e32 v58, v58, v112, vcc
	v_or_b32_e32 v104, s6, v58
	v_mul_f32_e32 v58, 0x3fb8aa3b, v65
	v_exp_f32_e32 v58, v58
	v_lshlrev_b64 v[70:71], 9, v[104:105]
	v_cvt_pk_bf16_f32 v54, v54, s0
	v_lshl_add_u64 v[70:71], v[102:103], 0, v[70:71]
	v_fma_f32 v55, v55, v58, v59
	v_xor_b32_e32 v58, 14, v0
	v_cndmask_b32_e32 v58, v58, v111, vcc
	v_or_b32_e32 v104, s6, v58
	v_lshlrev_b64 v[58:59], 9, v[104:105]
	v_cvt_pk_bf16_f32 v55, v55, s0
	v_lshl_add_u64 v[58:59], v[102:103], 0, v[58:59]
	global_store_short v[70:71], v54, off
	v_sub_f32_e32 v54, v117, v64
	global_store_short v[58:59], v55, off
	v_sub_f32_e32 v55, v117, v65
	v_mul_f32_e32 v54, 0x3fb8aa3b, v54
	v_mul_f32_e32 v55, 0x3fb8aa3b, v55
	v_exp_f32_e32 v54, v54
	v_exp_f32_e32 v55, v55
	s_nop 0
	v_pk_mul_f32 v[58:59], v[50:51], v[54:55]
	v_mul_f32_e32 v50, 0x3fb8aa3b, v66
	v_exp_f32_e32 v50, v50
	v_xor_b32_e32 v51, 13, v0
	v_cndmask_b32_e32 v51, v51, v109, vcc
	v_or_b32_e32 v104, s6, v51
	v_fma_f32 v50, v56, v50, v60
	v_cvt_pk_bf16_f32 v54, v50, s0
	v_lshlrev_b64 v[50:51], 9, v[104:105]
	v_lshl_add_u64 v[50:51], v[102:103], 0, v[50:51]
	global_store_short v[50:51], v54, off
	v_mul_f32_e32 v51, 0x3fb8aa3b, v67
	v_exp_f32_e32 v51, v51
	v_xor_b32_e32 v0, 12, v0
	v_cndmask_b32_e32 v0, v0, v110, vcc
	v_or_b32_e32 v104, s6, v0
	v_sub_f32_e32 v50, v117, v66
	v_fmac_f32_e32 v61, v57, v51
	v_lshlrev_b64 v[54:55], 9, v[104:105]
	v_sub_f32_e32 v0, v117, v67
	v_mul_f32_e32 v50, 0x3fb8aa3b, v50
	v_cvt_pk_bf16_f32 v51, v61, s0
	v_lshl_add_u64 v[54:55], v[102:103], 0, v[54:55]
	v_mul_f32_e32 v0, 0x3fb8aa3b, v0
	v_exp_f32_e32 v50, v50
	global_store_short v[54:55], v51, off
	v_exp_f32_e32 v51, v0
	v_mul_f32_e32 v0, 0x3fb8aa3b, v117
	v_exp_f32_e32 v0, v0
	v_cvt_pk_bf16_f32 v54, v78, v79
	v_pk_mul_f32 v[60:61], v[52:53], v[50:51]
	v_cvt_pk_bf16_f32 v50, v62, v63
	v_add_u32_e32 v62, 0x9000, v108
	v_cvt_pk_bf16_f32 v52, v58, v59
	v_cvt_pk_bf16_f32 v53, v60, v61
	v_cvt_pk_bf16_f32 v55, v80, v81
	v_cvt_pk_bf16_f32 v56, v82, v83
	v_cvt_pk_bf16_f32 v57, v84, v85
	v_pk_mul_f32 v[36:37], v[36:37], v[0:1] op_sel_hi:[1,0]
	v_pk_mul_f32 v[34:35], v[34:35], v[0:1] op_sel_hi:[1,0]
	v_cvt_pk_bf16_f32 v51, v68, v69
	v_pk_mul_f32 v[40:41], v[40:41], v[0:1] op_sel_hi:[1,0]
	s_nop 1
	v_mfma_f32_16x16x32_bf16 v[34:37], v[162:165], v[54:57], v[34:37]
	v_add_u32_e32 v62, 0x9800, v108
	v_pk_mul_f32 v[38:39], v[38:39], v[0:1] op_sel_hi:[1,0]
	s_nop 1
	v_mfma_f32_16x16x32_bf16 v[34:37], v[166:169], v[50:53], v[34:37]
	v_pk_mul_f32 v[48:49], v[48:49], v[0:1] op_sel_hi:[1,0]
	v_pk_mul_f32 v[46:47], v[46:47], v[0:1] op_sel_hi:[1,0]
	s_nop 1
	v_mfma_f32_16x16x32_bf16 v[38:41], v[170:173], v[54:57], v[38:41]
	v_add_u32_e32 v62, 0xa000, v108
	v_pk_mul_f32 v[44:45], v[44:45], v[0:1] op_sel_hi:[1,0]
	s_nop 1
	v_mfma_f32_16x16x32_bf16 v[38:41], v[174:177], v[50:53], v[38:41]
	v_pk_mul_f32 v[42:43], v[42:43], v[0:1] op_sel_hi:[1,0]
	v_add_u32_e32 v0, 0xa800, v108
	s_nop 1
	v_mfma_f32_16x16x32_bf16 v[46:49], v[178:181], v[54:57], v[46:49]
	s_nop 1
	v_mfma_f32_16x16x32_bf16 v[46:49], v[182:185], v[50:53], v[46:49]
	s_nop 1
	v_mfma_f32_16x16x32_bf16 v[42:45], v[186:189], v[54:57], v[42:45]
	s_nop 1
	v_mfma_f32_16x16x32_bf16 v[42:45], v[190:193], v[50:53], v[42:45]
	s_cbranch_scc0 .LBB0_599

; #define MFMA16(a, b, c) __builtin_amdgcn_mfma_f32_16x16x32_bf16((a), (b), (c), 0, 0, 0)
; DI float bf2f(bf16_t b) { return __uint_as_float(((unsigned)b) << 16); }
; DI void dn_scan_chain(CParams& p, int it, int S, char* lds) {
;     ...
;     {
;       f32x4 QK[4];
; #pragma unroll
;       for (int t = 0; t < 4; ++t) QK[t] = f32x4{0.f, 0.f, 0.f, 0.f};
; #pragma unroll
;       for (int ks = 0; ks < 2; ++ks) {
;         const bf16x8 bfk = *(const bf16x8*)(Kimg + (16 * w + l15) * 72 + 32 * ks + 8 * g4);
; #pragma unroll
;         for (int rt = 0; rt < 4; ++rt) {
;           const bf16x8 afq = *(const bf16x8*)(Qimg + (16 * rt + l15) * 72 + 32 * ks + 8 * g4);
;           QK[rt] = MFMA16(afq, bfk, QK[rt]);
;         }
;       }
;       const float gcj = gcs[e_col];
; #pragma unroll
;       for (int rt = 0; rt < 4; ++rt)
; #pragma unroll
;         for (int r = 0; r < 4; ++r) {
;           const int i = 16 * rt + 4 * g4 + r;
;           const float ee = __expf(fminf(gcs[i] - gcj, 0.f));
;           Iimg[i * 72 + e_col] = f2bf((i >= e_col) ? QK[rt][r] * ee : 0.f);
;         }
;     ...
;       for (int rt = 0; rt < 4; ++rt) {
; #pragma unroll
;         for (int r = 0; r < 4; ++r) vn[rt][r] = bf2f(Uimg[(16 * rt + 4 * g4 + r) * 72 + e_col]);
;         qs[rt] = f32x4{0.f, 0.f, 0.f, 0.f};
;         iv[rt] = f32x4{0.f, 0.f, 0.f, 0.f};
; #pragma unroll
;         for (int ks = 0; ks < 2; ++ks) {
;           const bf16_t* wp = Wn + (16 * rt + l15) * 72 + 32 * ks + 4 * g4;
;           const bf16_t* qp = Qimg + (16 * rt + l15) * 72 + 32 * ks + 4 * g4;
;           vn[rt] = MFMA16(ld2x4(wp, wp + 16), Bs[ks], vn[rt]);
;           qs[rt] = MFMA16(ld2x4(qp, qp + 16), Bs[ks], qs[rt]);
.LBB0_616:
	v_and_b32_e32 v68, 15, v52
	v_bfe_u32 v69, v52, 4, 2
	v_lshlrev_b32_e32 v54, 4, v69
	v_mul_u32_u24_e32 v70, 0x90, v68
	v_ashrrev_i32_e32 v0, 2, v52
	v_add3_u32 v67, 16, v54, v70
	v_bfi_b32 v98, -16, v0, v52
	s_waitcnt lgkmcnt(0)
	s_barrier
	ds_read_b128 v[58:61], v67 offset:20736
	ds_read_b128 v[62:65], v67 offset:23040
	v_mul_lo_u32 v0, v98, s12
	v_add_u32_e32 v0, 16, v0
	v_add_u32_e32 v66, v0, v54
	ds_read_b128 v[50:53], v66 offset:27648
	ds_read_b128 v[54:57], v67 offset:18432
	s_waitcnt lgkmcnt(1)
	v_mfma_f32_16x16x32_bf16 v[72:75], v[62:65], v[50:53], 0
	ds_read_b128 v[62:65], v67 offset:25344
	s_movk_i32 s6, 0xff74
	s_waitcnt lgkmcnt(1)
	v_mfma_f32_16x16x32_bf16 v[54:57], v[54:57], v[50:53], 0
	v_mfma_f32_16x16x32_bf16 v[58:61], v[58:61], v[50:53], 0
	s_waitcnt lgkmcnt(0)
	v_mfma_f32_16x16x32_bf16 v[50:53], v[62:65], v[50:53], 0
	ds_read_b128 v[76:79], v66 offset:27712
	ds_read_b128 v[62:65], v67 offset:18496
	s_waitcnt lgkmcnt(0)
	v_mfma_f32_16x16x32_bf16 v[62:65], v[62:65], v[76:79], v[54:57]
	s_nop 2
	ds_read_b128 v[54:57], v67 offset:20800
	s_waitcnt lgkmcnt(0)
	v_mfma_f32_16x16x32_bf16 v[58:61], v[54:57], v[76:79], v[58:61]
	ds_read_b128 v[54:57], v67 offset:23104
	s_waitcnt lgkmcnt(0)
	v_mfma_f32_16x16x32_bf16 v[54:57], v[54:57], v[76:79], v[72:75]
	s_nop 2
	ds_read_b128 v[72:75], v67 offset:25408
	v_mad_u64_u32 v[66:67], s[6:7], v98, s6, v[0:1]
	ds_read_b32 v67, v66 offset:55296
	s_waitcnt lgkmcnt(1)
	v_mfma_f32_16x16x32_bf16 v[50:53], v[72:75], v[76:79], v[50:53]
	v_lshlrev_b32_e32 v0, 2, v69
	v_cmp_ge_i32_e64 s[44:45], v0, v98
	v_mov_b32_e32 v72, 0
	v_lshl_add_u32 v71, v0, 2, 16
	v_mov_b32_e32 v73, 0
	v_lshlrev_b32_e32 v126, 3, v69
	v_add3_u32 v126, 16, v126, v70
	v_mul_u32_u24_e32 v127, 0x240, v69
	v_lshl_add_u32 v128, v98, 1, 16
	v_add_u32_e32 v127, v127, v128
	ds_read_b64 v[130:131], v126 offset:9216
	ds_read_b64 v[132:133], v126 offset:9248
	ds_read_b64 v[138:139], v126 offset:18432
	ds_read_b64 v[140:141], v126 offset:18464
	ds_read_b64 v[134:135], v126 offset:9280
	ds_read_b64 v[136:137], v126 offset:9312
	ds_read_b64 v[142:143], v126 offset:18496
	ds_read_b64 v[144:145], v126 offset:18528
	ds_read_b64 v[146:147], v126 offset:11520
	ds_read_b64 v[148:149], v126 offset:11552
	ds_read_b64 v[154:155], v126 offset:20736
	ds_read_b64 v[156:157], v126 offset:20768
	ds_read_b64 v[150:151], v126 offset:11584
	ds_read_b64 v[152:153], v126 offset:11616
	ds_read_b64 v[158:159], v126 offset:20800
	ds_read_b64 v[160:161], v126 offset:20832
	ds_read_b64 v[162:163], v126 offset:13824
	ds_read_b64 v[164:165], v126 offset:13856
	ds_read_b64 v[170:171], v126 offset:23040
	ds_read_b64 v[172:173], v126 offset:23072
	ds_read_b64 v[166:167], v126 offset:13888
	ds_read_b64 v[168:169], v126 offset:13920
	ds_read_b64 v[174:175], v126 offset:23104
	ds_read_b64 v[176:177], v126 offset:23136
	ds_read_b64 v[178:179], v126 offset:16128
	ds_read_b64 v[180:181], v126 offset:16160
	ds_read_b64 v[186:187], v126 offset:25344
	ds_read_b64 v[188:189], v126 offset:25376
	ds_read_b64 v[182:183], v126 offset:16192
	ds_read_b64 v[184:185], v126 offset:16224
	ds_read_b64 v[190:191], v126 offset:25408
	ds_read_b64 v[192:193], v126 offset:25440
	ds_read_u16 v194, v127 offset:0
	ds_read_u16 v195, v127 offset:144
	ds_read_u16 v196, v127 offset:288
	ds_read_u16 v197, v127 offset:432
	ds_read_u16 v198, v127 offset:2304
	ds_read_u16 v199, v127 offset:2448
	ds_read_u16 v200, v127 offset:2592
	ds_read_u16 v201, v127 offset:2736
	ds_read_u16 v202, v127 offset:4608
	ds_read_u16 v203, v127 offset:4752
	ds_read_u16 v204, v127 offset:4896
	ds_read_u16 v205, v127 offset:5040
	ds_read_u16 v206, v127 offset:6912
	ds_read_u16 v207, v127 offset:7056
	ds_read_u16 v208, v127 offset:7200
	ds_read_u16 v209, v127 offset:7344
	s_and_saveexec_b64 s[6:7], s[44:45]
	s_cbranch_execz .LBB0_618
	ds_read_b32 v73, v71 offset:55296
	s_waitcnt lgkmcnt(0)
	v_sub_f32_e32 v73, v73, v67
	v_min_f32_e32 v73, 0, v73
	v_mul_f32_e32 v73, 0x3fb8aa3b, v73
	v_exp_f32_e32 v73, v73
	s_nop 0
	v_mul_f32_e32 v62, v62, v73
	v_cvt_pk_bf16_f32 v73, v62, s0

; template <int DK, bool BAND>
; DI void flash_loop(f32x16 (&O)[2], float& m, float& l, const bf16_t* __restrict__ qrow, const bf16_t* __restrict__ kbase,
;                    size_t kstride, const bf16_t* __restrict__ vbase, size_t vstride, int ntiles, int tq, int u0, int L,
;                    char* lds) {
;   const int tid = threadIdx.x + opq(), lane = tid & 63, l31 = lane & 31, h2 = lane >> 5;
;   constexpr int KR = DK + 8, KCH = DK / 8, KN = 64 * KCH / 256;
;   constexpr int STAGE = 64 * KR * 2 + 64 * 72 * 2;
;   bf16x8 qf[DK / 16];
; #pragma unroll
;   for (int ks = 0; ks < DK / 16; ++ks) qf[ks] = *(const bf16x8*)(qrow + 16 * ks + 8 * h2);
;   u32x4 rkA[KN], rvA[2], rkB[KN], rvB[2];
;   auto gload = [&](int kt, u32x4 (&rk)[KN], u32x4 (&rv)[2]) {
; #pragma unroll
;     for (int i = 0; i < KN; ++i) {
;       const int ci = tid + 256 * i, row = ci / KCH, c = ci % KCH;
;       int rr = u0 + 64 * kt + row;
;       if (BAND) rr = min(max(rr, 0), L - 1);
;       rk[i] = *(const u32x4*)((const char*)kbase + ((unsigned)rr * (unsigned)(kstride * 2) + (unsigned)c * 16u));
;     }
; #pragma unroll
;     for (int i = 0; i < 2; ++i) {
;       const int ci = tid + 256 * i, row = ci >> 3, c = ci & 7;
;       int rr = u0 + 64 * kt + row;
;       if (BAND) rr = min(max(rr, 0), L - 1);
;       rv[i] = *(const u32x4*)((const char*)vbase + ((unsigned)rr * (unsigned)(vstride * 2) + (unsigned)c * 16u));
;     }
;   };
;   auto swrite = [&](int st, const u32x4 (&rk)[KN], const u32x4 (&rv)[2]) {
;     bf16_t* Ks = (bf16_t*)(lds + st * STAGE);
;     bf16_t* Vs = Ks + 64 * KR;
; #pragma unroll
;     for (int i = 0; i < KN; ++i) {
;       const int ci = tid + 256 * i, row = ci / KCH, c = ci % KCH;
;       *(u32x4*)(Ks + row * KR + c * 8) = rk[i];
;     }
; #pragma unroll
;     for (int i = 0; i < 2; ++i) {
;       const int ci = tid + 256 * i, row = ci >> 3, c = ci & 7;
;       *(u32x4*)(Vs + row * 72 + c * 8) = rv[i];
;     }
;   };
;   const int trq = (lane & 15) >> 2, trp = lane & 3, trblk = (lane >> 4) & 1;
;   const int troff = (4 * h2 + trq) * 72 + 16 * trblk + 4 * trp;
;   __syncthreads();
;   gload(0, rkA, rvA);
;   swrite(0, rkA, rvA);
;   gload(1, rkA, rvA);
;   if (ntiles > 2) gload(2, rkB, rvB);
; __global__ void __launch_bounds__(256, 2) mega(Params pk) {
;     ...
;           for (;;) {
;             __syncthreads();
.LBB0_842:
	s_or_b64 exec, exec, s[6:7]
	s_waitcnt lgkmcnt(0)
	s_barrier
	flat_load_dword v0, v[218:219] sc0 sc1
	s_waitcnt vmcnt(0)
	s_mov_b64 s[6:7], -1
	s_waitcnt lgkmcnt(0)
	v_readfirstlane_b32 s8, v0
	s_cmpk_gt_i32 s8, 0x7f
	s_cbranch_scc1 .LBB0_837
	s_ashr_i32 s6, s8, s68
	s_lshl_b32 s6, s6, 3
	s_or_b32 s6, s6, s50
	s_and_b32 s7, s8, s69
	s_lshl_b32 s6, s6, s68
	s_add_i32 s6, s6, s7
	s_ashr_i32 s8, s6, s68
	s_and_b32 s7, s6, s69
	s_and_b32 s6, s8, 3
	s_ashr_i32 s8, s8, 2
	v_mov_b32 v0, 0
	s_lshl_b32 s8, s8, s89
	v_add_u32_e32 v132, v0, v210
	s_lshl_b32 s7, s7, 7
	s_add_i32 s7, s8, s7
	v_ashrrev_i32_e32 v0, 1, v132
	v_and_b32_e32 v0, 0xffffffe0, v0
	v_and_or_b32 v2, v132, 31, s7
	v_add_u32_e32 v130, v2, v0
	v_ashrrev_i32_e32 v131, 31, v130
	v_lshlrev_b64 v[2:3], 2, v[130:131]
	v_or_b32_e32 v0, s6, v2
	v_mov_b64_e32 v[4:5], s[0:1]
	v_mad_u64_u32 v[4:5], s[38:39], v0, s81, v[4:5]
	v_mov_b32 v0, 0
	v_mad_i32_i24 v5, v3, s81, v5
	v_add_u32_e32 v23, v0, v210
	v_bfe_u32 v27, v23, 5, 1
	s_ashr_i32 s9, s8, 31
	v_lshlrev_b32_e32 v0, 4, v27
	s_lshl_b64 s[8:9], s[8:9], 2
	v_lshl_add_u64 v[2:3], v[4:5], 0, v[0:1]
	s_or_b32 s8, s8, s6
	global_load_dwordx4 v[66:69], v[2:3], off
	global_load_dwordx4 v[70:73], v[2:3], off offset:32
	global_load_dwordx4 v[74:77], v[2:3], off offset:64
	global_load_dwordx4 v[78:81], v[2:3], off offset:96
	global_load_dwordx4 v[82:85], v[2:3], off offset:128
	global_load_dwordx4 v[86:89], v[2:3], off offset:160
	v_mul_hi_i32 v2, v23, s17
	s_mul_i32 s7, s9, 0xc0
	s_mul_hi_u32 s28, s8, 0xc0
	v_lshrrev_b32_e32 v3, 31, v2
	v_ashrrev_i32_e32 v2, 1, v2
	s_add_i32 s28, s28, s7
	s_mul_i32 s7, s8, 0xc0
	v_add_u32_e32 v31, v2, v3
	s_add_u32 s38, s45, s7
	v_mul_lo_u32 v2, v31, 12
	s_addc_u32 s39, s46, s28
	s_lshl_b64 s[8:9], s[8:9], 7
	v_sub_u32_e32 v2, v23, v2
	v_add_u32_e32 v18, 0x100, v23
	s_add_u32 s42, s47, s8
	v_lshlrev_b32_e32 v22, 4, v2
	v_mul_hi_i32 v2, v18, s17
	s_addc_u32 s43, s48, s9
	v_mad_u64_u32 v[24:25], s[8:9], v31, s84, v[22:23]
	v_lshrrev_b32_e32 v3, 31, v2
	v_ashrrev_i32_e32 v2, 1, v2
	v_add_u32_e32 v25, v2, v3
	v_mul_lo_u32 v2, v25, 12
	v_sub_u32_e32 v2, v18, v2
	v_add_u32_e32 v10, 0x200, v23
	v_lshlrev_b32_e32 v26, 4, v2
	v_mul_hi_i32 v11, v10, s17
	v_mad_u64_u32 v[28:29], s[8:9], v25, s84, v[26:27]
	v_lshrrev_b32_e32 v12, 31, v11
	v_ashrrev_i32_e32 v11, 1, v11
	v_add_u32_e32 v29, v11, v12
	v_mul_lo_u32 v11, v29, 12
	v_sub_u32_e32 v10, v10, v11
	s_barrier
	global_load_dwordx4 v[2:5], v24, s[38:39]
	global_load_dwordx4 v[6:9], v28, s[38:39]
	v_lshlrev_b32_e32 v30, 4, v10
	v_mad_u64_u32 v[32:33], s[8:9], v29, s84, v[30:31]
	v_lshlrev_b32_e32 v134, 4, v23
	v_ashrrev_i32_e32 v35, 3, v18
	v_ashrrev_i32_e32 v33, 3, v23
	v_and_b32_e32 v135, 0x70, v134
	v_lshlrev_b32_e32 v136, 9, v35
	v_lshlrev_b32_e32 v133, 9, v33
	v_or_b32_e32 v36, v136, v135
	v_add_u32_e32 v37, 0xc000, v24
	v_or_b32_e32 v34, v133, v135
	global_load_dwordx4 v[18:21], v36, s[42:43]
	global_load_dwordx4 v[90:93], v37, s[38:39]
	v_add_u32_e32 v37, 0xc000, v28
	global_load_dwordx4 v[10:13], v32, s[38:39]
	global_load_dwordx4 v[14:17], v34, s[42:43]
	v_add_u32_e32 v38, 0xc000, v32
	global_load_dwordx4 v[94:97], v37, s[38:39]
	global_load_dwordx4 v[98:101], v38, s[38:39]
	v_add_u32_e32 v37, 0x8000, v34
	v_add_u32_e32 v24, 0x18000, v24
	v_add_u32_e32 v38, 0x8000, v36
	global_load_dwordx4 v[106:109], v37, s[42:43]
	global_load_dwordx4 v[114:117], v38, s[42:43]
	v_add_u32_e32 v28, 0x18000, v28
	global_load_dwordx4 v[102:105], v24, s[38:39]
	global_load_dwordx4 v[110:113], v28, s[38:39]
	v_add_u32_e32 v24, 0x18000, v32
	v_add_u32_e32 v28, 0x10000, v34
	global_load_dwordx4 v[118:121], v24, s[38:39]
	global_load_dwordx4 v[122:125], v28, s[42:43]
	v_add_u32_e32 v24, 0x10000, v36
	global_load_dwordx4 v[126:129], v24, s[42:43]
	v_and_b32_e32 v24, 31, v23
	v_bfe_u32 v28, v23, 2, 2
	v_and_b32_e32 v32, 16, v23
	v_lshlrev_b32_e32 v23, 2, v23
	v_lshl_or_b32 v27, v27, 2, v28
	v_and_or_b32 v23, v23, 12, v32
	v_mad_u32_u24 v23, v27, s13, v23
	v_mul_lo_u32 v27, v31, s33
	v_add3_u32 v137, 16, v27, v22
	v_lshl_add_u32 v142, v23, 1, 16
	v_mul_lo_u32 v144, v29, s21
	v_mul_lo_u32 v145, v25, s21
	v_mul_lo_u32 v146, v31, s21
	v_mov_b32_e32 v22, v1
	v_mov_b32_e32 v23, v1
	v_mov_b32_e32 v27, v1
	v_mov_b32_e32 v28, v1
	v_mov_b32_e32 v31, v1
	s_mov_b32 s7, 0
	v_mov_b32_e32 v148, 0
	v_mov_b32_e32 v147, 0xf149f2ca
	s_waitcnt vmcnt(14)
	ds_write_b128 v137, v[2:5]
	v_mul_lo_u32 v2, v25, s33
	v_add3_u32 v138, 16, v2, v26
	v_mul_lo_u32 v2, v29, s33
	v_add3_u32 v139, 16, v2, v30
	v_mul_lo_u32 v2, v33, s12
	v_add3_u32 v140, 16, v2, v135
	v_mul_lo_u32 v2, v35, s12
	v_add3_u32 v141, 16, v2, v135
	v_mul_u32_u24_e32 v2, 0x68, v24
	v_lshlrev_b32_e32 v2, 1, v2
	s_waitcnt vmcnt(13)
	ds_write_b128 v138, v[6:9]
	v_add3_u32 v143, 16, v0, v2
	v_mov_b32_e32 v2, v1
	v_mov_b32_e32 v3, v1
	v_mov_b32_e32 v4, v1
	v_mov_b32_e32 v5, v1
	s_waitcnt vmcnt(10)
	ds_write_b128 v139, v[10:13]
	s_waitcnt vmcnt(9)
	ds_write_b128 v140, v[14:17] offset:13312
	ds_write_b128 v141, v[18:21] offset:13312
	v_mov_b32_e32 v6, v1
	v_mov_b32_e32 v7, v1
	v_mov_b32_e32 v8, v1
	v_mov_b32_e32 v9, v1
	v_mov_b32_e32 v10, v1
	v_mov_b32_e32 v11, v1
	v_mov_b32_e32 v12, v1
	v_mov_b32_e32 v13, v1
	v_mov_b32_e32 v14, v1
	v_mov_b32_e32 v15, v1
	v_mov_b32_e32 v16, v1
	v_mov_b32_e32 v17, v1
	v_mov_b32_e32 v18, v1
	v_mov_b32_e32 v19, v1
	v_mov_b32_e32 v20, v1
	v_mov_b32_e32 v21, v1
	v_mov_b32_e32 v24, v1
	v_mov_b32_e32 v25, v1
	v_mov_b32_e32 v26, v1
	v_mov_b32_e32 v29, v1
	v_mov_b32_e32 v30, v1
	v_mov_b32_e32 v0, v1
	v_mov_b64_e32 v[32:33], v[30:31]
	v_mov_b64_e32 v[30:31], v[28:29]
	v_mov_b64_e32 v[28:29], v[26:27]
	v_mov_b64_e32 v[26:27], v[24:25]
	v_mov_b64_e32 v[24:25], v[22:23]
	v_mov_b64_e32 v[22:23], v[20:21]
	v_mov_b64_e32 v[20:21], v[18:19]
	v_mov_b64_e32 v[18:19], v[16:17]
	v_mov_b64_e32 v[16:17], v[14:15]
	v_mov_b64_e32 v[14:15], v[12:13]
	v_mov_b64_e32 v[12:13], v[10:11]
	v_mov_b64_e32 v[10:11], v[8:9]
	v_mov_b64_e32 v[8:9], v[6:7]
	v_mov_b64_e32 v[6:7], v[4:5]
	v_mov_b64_e32 v[4:5], v[2:3]
	v_mov_b64_e32 v[2:3], v[0:1]
	v_mov_b32_e32 v158, 0
	v_mov_b32_e32 v159, 0
	v_mov_b32_e32 v160, 0
	v_mov_b32_e32 v161, 0
	v_mov_b32_e32 v162, 0
	v_mov_b32_e32 v163, 0
	v_mov_b32_e32 v164, 0
	v_mov_b32_e32 v165, 0
	v_mov_b32_e32 v166, 0
	v_mov_b32_e32 v167, 0
	v_mov_b32_e32 v168, 0
	v_mov_b32_e32 v169, 0
	v_mov_b32_e32 v170, 0
	v_mov_b32_e32 v171, 0
	v_mov_b32_e32 v172, 0
	v_mov_b32_e32 v173, 0
	s_branch .LBB0_845
; #define MFMA32(a, b, c) __builtin_amdgcn_mfma_f32_32x32x16_bf16((a), (b), (c), 0, 0, 0)
; DI float exp2_(float x) { return __builtin_amdgcn_exp2f(x); }
; template <int DK, bool BAND>
; DI void flash_loop(f32x16 (&O)[2], float& m, float& l, const bf16_t* __restrict__ qrow, const bf16_t* __restrict__ kbase,
;                    size_t kstride, const bf16_t* __restrict__ vbase, size_t vstride, int ntiles, int tq, int u0, int L,
;                    char* lds) {
;     ...
;     float ls = 0.f;
; #pragma unroll
;     for (int j = 0; j < 2; ++j)
; #pragma unroll
;       for (int r = 0; r < 16; ++r) { const float pv = exp2_(Sx[j][r] - m); Sx[j][r] = pv; ls += pv; }
;     l += ls;
; #pragma unroll
;     for (int j = 0; j < 2; ++j)
; #pragma unroll
;       for (int s = 0; s < 2; ++s) {
;         const bf16x8 pf = pack8(Sx[j][8 * s], Sx[j][8 * s + 1], Sx[j][8 * s + 2], Sx[j][8 * s + 3], Sx[j][8 * s + 4],
;                                 Sx[j][8 * s + 5], Sx[j][8 * s + 6], Sx[j][8 * s + 7]);
; #pragma unroll
;         for (int t = 0; t < 2; ++t) {
;           const bf16_t* vp = Vs + (32 * j + 16 * s) * 72 + 32 * t + troff;
;           const bf16x8 vf = tr_pair(vp, vp + 8 * 72);
;           O[t] = MFMA32(vf, pf, O[t]);
;         }
;       }
.LBB0_844:
	v_exp_f32_e32 v50, v50
	v_exp_f32_e32 v51, v51
	v_exp_f32_e32 v52, v52
	v_exp_f32_e32 v53, v53
	v_add_f32_e32 v148, 0, v50
	v_exp_f32_e32 v54, v54
	v_add_f32_e32 v148, v51, v148
	v_exp_f32_e32 v55, v55
	v_add_f32_e32 v148, v52, v148
	v_exp_f32_e32 v56, v56
	v_add_f32_e32 v148, v53, v148
	v_exp_f32_e32 v57, v57
	v_add_f32_e32 v148, v54, v148
	v_exp_f32_e32 v58, v58
	v_add_f32_e32 v148, v55, v148
	v_exp_f32_e32 v59, v59
	v_add_f32_e32 v148, v56, v148
	v_exp_f32_e32 v60, v60
	v_add_f32_e32 v148, v57, v148
	v_exp_f32_e32 v61, v61
	v_add_f32_e32 v148, v58, v148
	v_exp_f32_e32 v62, v62
	v_add_f32_e32 v148, v59, v148
	v_exp_f32_e32 v63, v63
	v_add_f32_e32 v148, v60, v148
	v_exp_f32_e32 v64, v64
	v_add_f32_e32 v148, v61, v148
	v_exp_f32_e32 v65, v65
	v_add_f32_e32 v148, v62, v148
	v_exp_f32_e32 v149, v34
	v_add_f32_e32 v148, v63, v148
	v_exp_f32_e32 v150, v35
	v_add_f32_e32 v148, v64, v148
	v_exp_f32_e32 v151, v36
	v_add_f32_e32 v148, v65, v148
	v_exp_f32_e32 v152, v37
	v_add_f32_e32 v34, v149, v148
	v_exp_f32_e32 v153, v38
	v_add_f32_e32 v34, v150, v34
	v_exp_f32_e32 v154, v39
	v_add_f32_e32 v34, v151, v34
	v_exp_f32_e32 v155, v40
	v_add_f32_e32 v34, v152, v34
	v_exp_f32_e32 v156, v41
	v_add_f32_e32 v34, v153, v34
	v_exp_f32_e32 v42, v42
	v_add_f32_e32 v34, v154, v34
	v_exp_f32_e32 v43, v43
	v_add_f32_e32 v34, v155, v34
	v_exp_f32_e32 v44, v44
	v_add_f32_e32 v34, v156, v34
	v_exp_f32_e32 v45, v45
	v_add_f32_e32 v34, v42, v34
	v_exp_f32_e32 v46, v46
	v_add_f32_e32 v34, v43, v34
	v_exp_f32_e32 v47, v47
	v_add_f32_e32 v34, v44, v34
	v_exp_f32_e32 v48, v48
	v_add_f32_e32 v34, v45, v34
	v_exp_f32_e32 v49, v49
	v_add_f32_e32 v34, v46, v34
	ds_read_b64_tr_b16 v[38:39], v142 offset:35840
	ds_read_b64_tr_b16 v[40:41], v142 offset:36992
	v_add_f32_e32 v34, v47, v34
	v_add_f32_e32 v34, v48, v34
	v_add_f32_e32 v34, v49, v34
	v_add_f32_e32 v148, v0, v34
	v_cvt_pk_bf16_f32 v34, v50, v51
	v_cvt_pk_bf16_f32 v35, v52, v53
	v_cvt_pk_bf16_f32 v36, v54, v55
	v_cvt_pk_bf16_f32 v37, v56, v57
	s_add_i32 s7, s7, 2
	v_add_u32_e32 v136, 0x10000, v136
	s_waitcnt lgkmcnt(0)
	v_mfma_f32_32x32x16_bf16 v[2:17], v[38:41], v[34:37], v[2:17]
	ds_read_b64_tr_b16 v[38:39], v142 offset:35904
	ds_read_b64_tr_b16 v[40:41], v142 offset:37056
	v_add_u32_e32 v133, 0x10000, v133
	v_add_u32_e32 v144, 0x18000, v144
	v_add_u32_e32 v145, 0x18000, v145
	v_add_u32_e32 v146, 0x18000, v146
	s_cmp_lt_u32 s7, s88
	s_waitcnt lgkmcnt(0)
	v_mfma_f32_32x32x16_bf16 v[18:33], v[38:41], v[34:37], v[18:33]
	ds_read_b64_tr_b16 v[38:39], v142 offset:38144
	ds_read_b64_tr_b16 v[40:41], v142 offset:39296
	v_cvt_pk_bf16_f32 v34, v58, v59
	v_cvt_pk_bf16_f32 v35, v60, v61
	v_cvt_pk_bf16_f32 v36, v62, v63
	v_cvt_pk_bf16_f32 v37, v64, v65
	s_waitcnt lgkmcnt(0)
	s_nop 0
	v_mfma_f32_32x32x16_bf16 v[2:17], v[38:41], v[34:37], v[2:17]
	ds_read_b64_tr_b16 v[38:39], v142 offset:38208
	ds_read_b64_tr_b16 v[40:41], v142 offset:39360
	s_waitcnt lgkmcnt(0)
	v_mfma_f32_32x32x16_bf16 v[18:33], v[38:41], v[34:37], v[18:33]
	ds_read_b64_tr_b16 v[38:39], v142 offset:40448
	ds_read_b64_tr_b16 v[40:41], v142 offset:41600
	v_cvt_pk_bf16_f32 v34, v149, v150
	v_cvt_pk_bf16_f32 v35, v151, v152
	v_cvt_pk_bf16_f32 v36, v153, v154
	v_cvt_pk_bf16_f32 v37, v155, v156
	s_waitcnt lgkmcnt(0)
	s_nop 0
	v_mfma_f32_32x32x16_bf16 v[2:17], v[38:41], v[34:37], v[2:17]
	ds_read_b64_tr_b16 v[38:39], v142 offset:40512
	ds_read_b64_tr_b16 v[40:41], v142 offset:41664
	s_waitcnt lgkmcnt(0)
	v_mfma_f32_32x32x16_bf16 v[18:33], v[38:41], v[34:37], v[18:33]
	ds_read_b64_tr_b16 v[38:39], v142 offset:42752
	ds_read_b64_tr_b16 v[40:41], v142 offset:43904
	v_cvt_pk_bf16_f32 v34, v42, v43
	v_cvt_pk_bf16_f32 v35, v44, v45
	v_cvt_pk_bf16_f32 v36, v46, v47
	v_cvt_pk_bf16_f32 v37, v48, v49
	s_waitcnt lgkmcnt(0)
	s_nop 0
	v_mfma_f32_32x32x16_bf16 v[2:17], v[38:41], v[34:37], v[2:17]
	ds_read_b64_tr_b16 v[38:39], v142 offset:42816
	ds_read_b64_tr_b16 v[40:41], v142 offset:43968
	s_waitcnt lgkmcnt(0)
	v_mfma_f32_32x32x16_bf16 v[18:33], v[38:41], v[34:37], v[18:33]
	s_cbranch_scc0 .LBB0_836

; #define MFMA32(a, b, c) __builtin_amdgcn_mfma_f32_32x32x16_bf16((a), (b), (c), 0, 0, 0)
; DI float exp2_(float x) { return __builtin_amdgcn_exp2f(x); }
; DI int crow(int r, int h2) { return (r & 3) + 8 * (r >> 2) + 4 * h2; }
; template <int DK, bool BAND>
; DI void flash_loop(f32x16 (&O)[2], float& m, float& l, const bf16_t* __restrict__ qrow, const bf16_t* __restrict__ kbase,
;                    size_t kstride, const bf16_t* __restrict__ vbase, size_t vstride, int ntiles, int tq, int u0, int L,
;                    char* lds) {
;     ...
; #pragma unroll
;     for (int ks = 0; ks < DK / 16; ++ks)
; #pragma unroll
;       for (int j = 0; j < 2; ++j) {
;         const bf16x8 kf = *(const bf16x8*)(Ks + (32 * j + l31) * KR + 16 * ks + 8 * h2);
;         Sx[j] = MFMA32(kf, qf[ks], Sx[j]);
;       }
;     if (BAND) {
; #pragma unroll
;       for (int j = 0; j < 2; ++j)
; #pragma unroll
;         for (int r = 0; r < 16; ++r) {
;           const int u = u0 + 64 * kt + 32 * j + crow(r, h2);
;           const int d = u - tq;
;           const bool valid = (d <= 64) && (d >= -64) && (u >= 0) && (u < L);
;           Sx[j][r] = valid ? Sx[j][r] : -1e30f;
;         }
;     }
;     float mx = Sx[0][0];
; #pragma unroll
;     for (int j = 0; j < 2; ++j)
; #pragma unroll
;       for (int r = 0; r < 16; ++r) mx = fmaxf(mx, Sx[j][r]);
;     mx = xhalf_max(mx);
;     if (__any(mx - m > DEFER_THR)) {
;       const float mn = fmaxf(m, mx);
;       const float alpha = exp2_(m - mn);
;       m = mn;
;       l *= alpha;
; #pragma unroll
;       for (int t = 0; t < 2; ++t)
; #pragma unroll
;         for (int r = 0; r < 16; ++r) O[t][r] *= alpha;
;     }
.LBB0_849:
	ds_read_b128 v[34:37], v143
	ds_read_b128 v[150:153], v143 offset:32
	s_waitcnt lgkmcnt(1)
	v_mfma_f32_32x32x16_bf16 v[50:65], v[34:37], v[66:69], v[158:173]
	ds_read_b128 v[34:37], v143 offset:6656
	s_waitcnt lgkmcnt(1)
	v_mfma_f32_32x32x16_bf16 v[50:65], v[150:153], v[70:73], v[50:65]
	ds_read_b128 v[150:153], v143 offset:6688
	s_waitcnt lgkmcnt(1)
	v_mfma_f32_32x32x16_bf16 v[34:49], v[34:37], v[66:69], v[158:173]
	s_waitcnt lgkmcnt(0)
	v_mfma_f32_32x32x16_bf16 v[34:49], v[150:153], v[70:73], v[34:49]
	ds_read_b128 v[150:153], v143 offset:64
	s_waitcnt lgkmcnt(0)
	v_mfma_f32_32x32x16_bf16 v[50:65], v[150:153], v[74:77], v[50:65]
	ds_read_b128 v[150:153], v143 offset:6720
	s_waitcnt lgkmcnt(0)
	v_mfma_f32_32x32x16_bf16 v[34:49], v[150:153], v[74:77], v[34:49]
	ds_read_b128 v[150:153], v143 offset:96
	s_waitcnt lgkmcnt(0)
	v_mfma_f32_32x32x16_bf16 v[50:65], v[150:153], v[78:81], v[50:65]
	ds_read_b128 v[150:153], v143 offset:6752
	s_waitcnt lgkmcnt(0)
	v_mfma_f32_32x32x16_bf16 v[34:49], v[150:153], v[78:81], v[34:49]
	ds_read_b128 v[150:153], v143 offset:128
	s_waitcnt lgkmcnt(0)
	v_mfma_f32_32x32x16_bf16 v[50:65], v[150:153], v[82:85], v[50:65]
	ds_read_b128 v[150:153], v143 offset:6784
	s_waitcnt lgkmcnt(0)
	v_mfma_f32_32x32x16_bf16 v[34:49], v[150:153], v[82:85], v[34:49]
	ds_read_b128 v[150:153], v143 offset:160
	s_waitcnt lgkmcnt(0)
	v_mfma_f32_32x32x16_bf16 v[50:65], v[150:153], v[86:89], v[50:65]
	ds_read_b128 v[150:153], v143 offset:6816
	s_waitcnt lgkmcnt(0)
	v_mfma_f32_32x32x16_bf16 v[34:49], v[150:153], v[86:89], v[34:49]
	s_nop 8
	v_max_f32_e32 v0, v51, v51
	v_max_f32_e32 v149, v50, v50
	v_max_f32_e32 v0, v149, v0
	v_max3_f32 v0, v0, v52, v53
	v_max3_f32 v0, v0, v54, v55
	v_max3_f32 v0, v0, v56, v57
	v_max3_f32 v0, v0, v58, v59
	v_max3_f32 v0, v0, v60, v61
	v_max3_f32 v0, v0, v62, v63
	v_max3_f32 v0, v0, v64, v65
	v_max3_f32 v0, v0, v34, v35
	v_max3_f32 v0, v0, v36, v37
	v_max3_f32 v0, v0, v38, v39
	v_max3_f32 v0, v0, v40, v41
	v_max3_f32 v0, v0, v42, v43
	v_max3_f32 v0, v0, v44, v45
	v_max3_f32 v0, v0, v46, v47
	v_max3_f32 v0, v0, v48, v49
	v_mov_b32_e32 v149, v0
	s_nop 1
	v_permlane32_swap_b32_e32 v0, v149
	v_max_f32_e32 v149, v149, v149
	v_max_f32_e32 v0, v0, v0
	v_max_f32_e32 v0, v0, v149
	v_sub_f32_e32 v0, v0, v158
	v_sub_f32_e32 v149, v0, v147
	v_cmp_lt_f32_e32 vcc, s22, v149
	s_cbranch_vccz .LBB0_851
	v_max_f32_e32 v0, v0, v0
	v_max_f32_e32 v149, v147, v147
	v_max_f32_e32 v149, v149, v0
	v_sub_f32_e32 v0, v147, v149
	v_exp_f32_e32 v0, v0
	v_mov_b32_e32 v147, v149
	v_mul_f32_e32 v148, v148, v0
	v_pk_mul_f32 v[32:33], v[32:33], v[0:1] op_sel_hi:[1,0]
	v_pk_mul_f32 v[30:31], v[30:31], v[0:1] op_sel_hi:[1,0]
	v_pk_mul_f32 v[28:29], v[28:29], v[0:1] op_sel_hi:[1,0]
	v_pk_mul_f32 v[26:27], v[26:27], v[0:1] op_sel_hi:[1,0]
	v_pk_mul_f32 v[24:25], v[24:25], v[0:1] op_sel_hi:[1,0]
	v_pk_mul_f32 v[22:23], v[22:23], v[0:1] op_sel_hi:[1,0]
	v_pk_mul_f32 v[20:21], v[20:21], v[0:1] op_sel_hi:[1,0]
	v_pk_mul_f32 v[18:19], v[18:19], v[0:1] op_sel_hi:[1,0]
	v_pk_mul_f32 v[16:17], v[16:17], v[0:1] op_sel_hi:[1,0]
	v_pk_mul_f32 v[14:15], v[14:15], v[0:1] op_sel_hi:[1,0]
	v_pk_mul_f32 v[12:13], v[12:13], v[0:1] op_sel_hi:[1,0]
	v_pk_mul_f32 v[10:11], v[10:11], v[0:1] op_sel_hi:[1,0]
	v_pk_mul_f32 v[8:9], v[8:9], v[0:1] op_sel_hi:[1,0]
	v_pk_mul_f32 v[6:7], v[6:7], v[0:1] op_sel_hi:[1,0]
	v_pk_mul_f32 v[4:5], v[4:5], v[0:1] op_sel_hi:[1,0]
	v_pk_mul_f32 v[2:3], v[2:3], v[0:1] op_sel_hi:[1,0]
	v_add_f32_e32 v174, v147, v158
	v_sub_f32_e32 v50, v50, v174
	v_sub_f32_e32 v51, v51, v174
	v_sub_f32_e32 v52, v52, v174
	v_sub_f32_e32 v53, v53, v174
	v_sub_f32_e32 v54, v54, v174
	v_sub_f32_e32 v55, v55, v174
	v_sub_f32_e32 v56, v56, v174
	v_sub_f32_e32 v57, v57, v174
	v_sub_f32_e32 v58, v58, v174
	v_sub_f32_e32 v59, v59, v174
	v_sub_f32_e32 v60, v60, v174
	v_sub_f32_e32 v61, v61, v174
	v_sub_f32_e32 v62, v62, v174
	v_sub_f32_e32 v63, v63, v174
	v_sub_f32_e32 v64, v64, v174
	v_sub_f32_e32 v65, v65, v174
	v_sub_f32_e32 v34, v34, v174
	v_sub_f32_e32 v35, v35, v174
	v_sub_f32_e32 v36, v36, v174
	v_sub_f32_e32 v37, v37, v174
	v_sub_f32_e32 v38, v38, v174
	v_sub_f32_e32 v39, v39, v174
	v_sub_f32_e32 v40, v40, v174
	v_sub_f32_e32 v41, v41, v174
	v_sub_f32_e32 v42, v42, v174
	v_sub_f32_e32 v43, v43, v174
	v_sub_f32_e32 v44, v44, v174
	v_sub_f32_e32 v45, v45, v174
	v_sub_f32_e32 v46, v46, v174
	v_sub_f32_e32 v47, v47, v174
	v_sub_f32_e32 v48, v48, v174
	v_sub_f32_e32 v49, v49, v174
	v_sub_f32_e32 v158, 0, v147
	v_sub_f32_e32 v159, 0, v147
	v_sub_f32_e32 v160, 0, v147
	v_sub_f32_e32 v161, 0, v147
	v_sub_f32_e32 v162, 0, v147
	v_sub_f32_e32 v163, 0, v147
	v_sub_f32_e32 v164, 0, v147
	v_sub_f32_e32 v165, 0, v147
	v_sub_f32_e32 v166, 0, v147
	v_sub_f32_e32 v167, 0, v147
	v_sub_f32_e32 v168, 0, v147
	v_sub_f32_e32 v169, 0, v147
	v_sub_f32_e32 v170, 0, v147
	v_sub_f32_e32 v171, 0, v147
	v_sub_f32_e32 v172, 0, v147
	v_sub_f32_e32 v173, 0, v147
; #define MFMA32(a, b, c) __builtin_amdgcn_mfma_f32_32x32x16_bf16((a), (b), (c), 0, 0, 0)
; DI float exp2_(float x) { return __builtin_amdgcn_exp2f(x); }
; template <int DK, bool BAND>
; DI void flash_loop(f32x16 (&O)[2], float& m, float& l, const bf16_t* __restrict__ qrow, const bf16_t* __restrict__ kbase,
;                    size_t kstride, const bf16_t* __restrict__ vbase, size_t vstride, int ntiles, int tq, int u0, int L,
;                    char* lds) {
;     ...
;     __syncthreads();
;     if (par == 0) {
;       if (kt + 1 < ntiles) swrite((kt + 1) & 1, rkA, rvA);
;       if (kt + 3 < ntiles) gload(kt + 3, rkA, rvA);
;     } else {
;       if (kt + 1 < ntiles) swrite((kt + 1) & 1, rkB, rvB);
;       if (kt + 3 < ntiles) gload(kt + 3, rkB, rvB);
;     }
;     ...
;     float ls = 0.f;
; #pragma unroll
;     for (int j = 0; j < 2; ++j)
; #pragma unroll
;       for (int r = 0; r < 16; ++r) { const float pv = exp2_(Sx[j][r] - m); Sx[j][r] = pv; ls += pv; }
;     l += ls;
; #pragma unroll
;     for (int j = 0; j < 2; ++j)
; #pragma unroll
;       for (int s = 0; s < 2; ++s) {
;         const bf16x8 pf = pack8(Sx[j][8 * s], Sx[j][8 * s + 1], Sx[j][8 * s + 2], Sx[j][8 * s + 3], Sx[j][8 * s + 4],
;                                 Sx[j][8 * s + 5], Sx[j][8 * s + 6], Sx[j][8 * s + 7]);
; #pragma unroll
;         for (int t = 0; t < 2; ++t) {
;           const bf16_t* vp = Vs + (32 * j + 16 * s) * 72 + 32 * t + troff;
;           const bf16x8 vf = tr_pair(vp, vp + 8 * 72);
;           O[t] = MFMA32(vf, pf, O[t]);
;         }
;       }
.LBB0_851:
	v_exp_f32_e32 v0, v50
	v_exp_f32_e32 v50, v51
	v_exp_f32_e32 v51, v52
	v_exp_f32_e32 v52, v53
	v_exp_f32_e32 v53, v54
	v_exp_f32_e32 v54, v55
	v_exp_f32_e32 v55, v56
	v_exp_f32_e32 v56, v57
	ds_read_b64_tr_b16 v[154:155], v142 offset:13312
	ds_read_b64_tr_b16 v[156:157], v142 offset:14464
	v_cvt_pk_bf16_f32 v150, v0, v50
	v_cvt_pk_bf16_f32 v151, v51, v52
	v_cvt_pk_bf16_f32 v152, v53, v54
	v_cvt_pk_bf16_f32 v153, v55, v56
	s_waitcnt lgkmcnt(0)
	v_mfma_f32_32x32x16_bf16 v[2:17], v[154:157], v[150:153], v[2:17]
	ds_read_b64_tr_b16 v[154:155], v142 offset:13376
	ds_read_b64_tr_b16 v[156:157], v142 offset:14528
	v_exp_f32_e32 v57, v58
	v_exp_f32_e32 v58, v59
	v_exp_f32_e32 v59, v60
	v_exp_f32_e32 v60, v61
	v_exp_f32_e32 v61, v62
	v_exp_f32_e32 v62, v63
	v_exp_f32_e32 v63, v64
	v_exp_f32_e32 v64, v65
	s_waitcnt lgkmcnt(0)
	v_mfma_f32_32x32x16_bf16 v[18:33], v[154:157], v[150:153], v[18:33]
	ds_read_b64_tr_b16 v[154:155], v142 offset:15616
	ds_read_b64_tr_b16 v[156:157], v142 offset:16768
	v_cvt_pk_bf16_f32 v150, v57, v58
	v_cvt_pk_bf16_f32 v151, v59, v60
	v_cvt_pk_bf16_f32 v152, v61, v62
	v_cvt_pk_bf16_f32 v153, v63, v64
	s_waitcnt lgkmcnt(0)
	v_mfma_f32_32x32x16_bf16 v[2:17], v[154:157], v[150:153], v[2:17]
	ds_read_b64_tr_b16 v[154:155], v142 offset:15680
	ds_read_b64_tr_b16 v[156:157], v142 offset:16832
	v_exp_f32_e32 v34, v34
	v_exp_f32_e32 v35, v35
	v_exp_f32_e32 v36, v36
	v_exp_f32_e32 v37, v37
	v_exp_f32_e32 v38, v38
	v_exp_f32_e32 v39, v39
	v_exp_f32_e32 v40, v40
	v_exp_f32_e32 v41, v41
	s_waitcnt lgkmcnt(0)
	v_mfma_f32_32x32x16_bf16 v[18:33], v[154:157], v[150:153], v[18:33]
	ds_read_b64_tr_b16 v[154:155], v142 offset:17920
	ds_read_b64_tr_b16 v[156:157], v142 offset:19072
	v_cvt_pk_bf16_f32 v150, v34, v35
	v_cvt_pk_bf16_f32 v151, v36, v37
	v_cvt_pk_bf16_f32 v152, v38, v39
	v_cvt_pk_bf16_f32 v153, v40, v41
	s_waitcnt lgkmcnt(0)
	v_mfma_f32_32x32x16_bf16 v[2:17], v[154:157], v[150:153], v[2:17]
	ds_read_b64_tr_b16 v[154:155], v142 offset:17984
	ds_read_b64_tr_b16 v[156:157], v142 offset:19136
	v_exp_f32_e32 v42, v42
	v_exp_f32_e32 v43, v43
	v_exp_f32_e32 v44, v44
	v_exp_f32_e32 v45, v45
	v_exp_f32_e32 v46, v46
	v_exp_f32_e32 v47, v47
	v_exp_f32_e32 v48, v48
	v_exp_f32_e32 v49, v49
	s_waitcnt lgkmcnt(0)
	v_mfma_f32_32x32x16_bf16 v[18:33], v[154:157], v[150:153], v[18:33]
	ds_read_b64_tr_b16 v[154:155], v142 offset:20224
	ds_read_b64_tr_b16 v[156:157], v142 offset:21376
	v_cvt_pk_bf16_f32 v150, v42, v43
	v_cvt_pk_bf16_f32 v151, v44, v45
	v_cvt_pk_bf16_f32 v152, v46, v47
	v_cvt_pk_bf16_f32 v153, v48, v49
	s_cmp_ge_u32 s7, s40
	s_waitcnt lgkmcnt(0)
	v_mfma_f32_32x32x16_bf16 v[2:17], v[154:157], v[150:153], v[2:17]
	ds_read_b64_tr_b16 v[154:155], v142 offset:20288
	ds_read_b64_tr_b16 v[156:157], v142 offset:21440
	s_waitcnt lgkmcnt(0)
	s_barrier
	v_mfma_f32_32x32x16_bf16 v[18:33], v[154:157], v[150:153], v[18:33]
	s_cbranch_scc1 .LBB0_853
	s_waitcnt vmcnt(4)
	ds_write_b128 v137, v[102:105]
	s_waitcnt vmcnt(3)
	ds_write_b128 v138, v[110:113]
	s_waitcnt vmcnt(2)
	ds_write_b128 v139, v[118:121]
	s_waitcnt vmcnt(1)
	ds_write_b128 v140, v[122:125] offset:13312
	s_waitcnt vmcnt(0)
	ds_write_b128 v141, v[126:129] offset:13312

; #define MFMA32(a, b, c) __builtin_amdgcn_mfma_f32_32x32x16_bf16((a), (b), (c), 0, 0, 0)
; DI float exp2_(float x) { return __builtin_amdgcn_exp2f(x); }
; DI int crow(int r, int h2) { return (r & 3) + 8 * (r >> 2) + 4 * h2; }
; template <int DK, bool BAND>
; DI void flash_loop(f32x16 (&O)[2], float& m, float& l, const bf16_t* __restrict__ qrow, const bf16_t* __restrict__ kbase,
;                    size_t kstride, const bf16_t* __restrict__ vbase, size_t vstride, int ntiles, int tq, int u0, int L,
;                    char* lds) {
;     ...
; #pragma unroll
;     for (int ks = 0; ks < DK / 16; ++ks)
; #pragma unroll
;       for (int j = 0; j < 2; ++j) {
;         const bf16x8 kf = *(const bf16x8*)(Ks + (32 * j + l31) * KR + 16 * ks + 8 * h2);
;         Sx[j] = MFMA32(kf, qf[ks], Sx[j]);
;       }
;     if (BAND) {
; #pragma unroll
;       for (int j = 0; j < 2; ++j)
; #pragma unroll
;         for (int r = 0; r < 16; ++r) {
;           const int u = u0 + 64 * kt + 32 * j + crow(r, h2);
;           const int d = u - tq;
;           const bool valid = (d <= 64) && (d >= -64) && (u >= 0) && (u < L);
;           Sx[j][r] = valid ? Sx[j][r] : -1e30f;
;         }
;     }
;     float mx = Sx[0][0];
; #pragma unroll
;     for (int j = 0; j < 2; ++j)
; #pragma unroll
;       for (int r = 0; r < 16; ++r) mx = fmaxf(mx, Sx[j][r]);
;     mx = xhalf_max(mx);
;     if (__any(mx - m > DEFER_THR)) {
;       const float mn = fmaxf(m, mx);
;       const float alpha = exp2_(m - mn);
;       m = mn;
;       l *= alpha;
; #pragma unroll
;       for (int t = 0; t < 2; ++t)
; #pragma unroll
;         for (int r = 0; r < 16; ++r) O[t][r] *= alpha;
;     }
;     float ls = 0.f;
; #pragma unroll
;     for (int j = 0; j < 2; ++j)
; #pragma unroll
;       for (int r = 0; r < 16; ++r) { const float pv = exp2_(Sx[j][r] - m); Sx[j][r] = pv; ls += pv; }
;     l += ls;
.LBB0_855:
	v_add_f32_e32 v0, 0, v0
	v_add_f32_e32 v0, v50, v0
	v_add_f32_e32 v0, v51, v0
	v_add_f32_e32 v0, v52, v0
	v_add_f32_e32 v0, v53, v0
	v_add_f32_e32 v0, v54, v0
	v_add_f32_e32 v0, v55, v0
	v_add_f32_e32 v0, v56, v0
	v_add_f32_e32 v0, v57, v0
	v_add_f32_e32 v0, v58, v0
	v_add_f32_e32 v0, v59, v0
	v_add_f32_e32 v0, v60, v0
	v_add_f32_e32 v0, v61, v0
	v_add_f32_e32 v0, v62, v0
	v_add_f32_e32 v0, v63, v0
	v_add_f32_e32 v0, v64, v0
	v_add_f32_e32 v0, v34, v0
	v_add_f32_e32 v0, v35, v0
	v_add_f32_e32 v0, v36, v0
	v_add_f32_e32 v0, v37, v0
	v_add_f32_e32 v0, v38, v0
	v_add_f32_e32 v0, v39, v0
	v_add_f32_e32 v0, v40, v0
	v_add_f32_e32 v0, v41, v0
	v_add_f32_e32 v0, v42, v0
	v_add_f32_e32 v0, v43, v0
	v_add_f32_e32 v0, v44, v0
	v_add_f32_e32 v0, v45, v0
	v_add_f32_e32 v0, v46, v0
	v_add_f32_e32 v0, v47, v0
	v_add_f32_e32 v0, v48, v0
	v_add_f32_e32 v0, v49, v0
	v_add_f32_e32 v0, v148, v0
	ds_read_b128 v[34:37], v143 offset:22528
	ds_read_b128 v[148:151], v143 offset:22560
	s_waitcnt lgkmcnt(1)
	v_mfma_f32_32x32x16_bf16 v[50:65], v[34:37], v[66:69], v[158:173]
	ds_read_b128 v[34:37], v143 offset:29184
	s_waitcnt lgkmcnt(1)
	v_mfma_f32_32x32x16_bf16 v[50:65], v[148:151], v[70:73], v[50:65]
	ds_read_b128 v[148:151], v143 offset:29216
	s_waitcnt lgkmcnt(1)
	v_mfma_f32_32x32x16_bf16 v[34:49], v[34:37], v[66:69], v[158:173]
	s_waitcnt lgkmcnt(0)
	v_mfma_f32_32x32x16_bf16 v[34:49], v[148:151], v[70:73], v[34:49]
	ds_read_b128 v[148:151], v143 offset:22592
	s_waitcnt lgkmcnt(0)
	v_mfma_f32_32x32x16_bf16 v[50:65], v[148:151], v[74:77], v[50:65]
	ds_read_b128 v[148:151], v143 offset:29248
	s_waitcnt lgkmcnt(0)
	v_mfma_f32_32x32x16_bf16 v[34:49], v[148:151], v[74:77], v[34:49]
	ds_read_b128 v[148:151], v143 offset:22624
	s_waitcnt lgkmcnt(0)
	v_mfma_f32_32x32x16_bf16 v[50:65], v[148:151], v[78:81], v[50:65]
	ds_read_b128 v[148:151], v143 offset:29280
	s_waitcnt lgkmcnt(0)
	v_mfma_f32_32x32x16_bf16 v[34:49], v[148:151], v[78:81], v[34:49]
	ds_read_b128 v[148:151], v143 offset:22656
	s_waitcnt lgkmcnt(0)
	v_mfma_f32_32x32x16_bf16 v[50:65], v[148:151], v[82:85], v[50:65]
	ds_read_b128 v[148:151], v143 offset:29312
	s_waitcnt lgkmcnt(0)
	v_mfma_f32_32x32x16_bf16 v[34:49], v[148:151], v[82:85], v[34:49]
	ds_read_b128 v[148:151], v143 offset:22688
	s_waitcnt lgkmcnt(0)
	v_mfma_f32_32x32x16_bf16 v[50:65], v[148:151], v[86:89], v[50:65]
	ds_read_b128 v[148:151], v143 offset:29344
	s_waitcnt lgkmcnt(0)
	v_mfma_f32_32x32x16_bf16 v[34:49], v[148:151], v[86:89], v[34:49]
	s_nop 8
	v_max_f32_e32 v148, v51, v51
	v_max_f32_e32 v149, v50, v50
	v_max_f32_e32 v148, v149, v148
	v_max3_f32 v148, v148, v52, v53
	v_max3_f32 v148, v148, v54, v55
	v_max3_f32 v148, v148, v56, v57
	v_max3_f32 v148, v148, v58, v59
	v_max3_f32 v148, v148, v60, v61
	v_max3_f32 v148, v148, v62, v63
	v_max3_f32 v148, v148, v64, v65
	v_max3_f32 v148, v148, v34, v35
	v_max3_f32 v148, v148, v36, v37
	v_max3_f32 v148, v148, v38, v39
	v_max3_f32 v148, v148, v40, v41
	v_max3_f32 v148, v148, v42, v43
	v_max3_f32 v148, v148, v44, v45
	v_max3_f32 v148, v148, v46, v47
	v_max3_f32 v148, v148, v48, v49
	v_mov_b32_e32 v149, v148
	s_nop 1
	v_permlane32_swap_b32_e32 v148, v149
	v_max_f32_e32 v149, v149, v149
	v_max_f32_e32 v148, v148, v148
	v_max_f32_e32 v148, v148, v149
	v_sub_f32_e32 v148, v148, v158
	v_sub_f32_e32 v149, v148, v147
	v_cmp_lt_f32_e32 vcc, s22, v149
	s_cbranch_vccz .LBB0_844
	v_max_f32_e32 v148, v148, v148
	v_max_f32_e32 v149, v147, v147
	v_max_f32_e32 v149, v149, v148
	v_sub_f32_e32 v147, v147, v149
	v_exp_f32_e32 v148, v147
	v_mov_b32_e32 v147, v149
	v_mul_f32_e32 v0, v0, v148
	v_pk_mul_f32 v[32:33], v[32:33], v[148:149] op_sel_hi:[1,0]
	v_pk_mul_f32 v[30:31], v[30:31], v[148:149] op_sel_hi:[1,0]
	v_pk_mul_f32 v[28:29], v[28:29], v[148:149] op_sel_hi:[1,0]
	v_pk_mul_f32 v[26:27], v[26:27], v[148:149] op_sel_hi:[1,0]
	v_pk_mul_f32 v[24:25], v[24:25], v[148:149] op_sel_hi:[1,0]
	v_pk_mul_f32 v[22:23], v[22:23], v[148:149] op_sel_hi:[1,0]
	v_pk_mul_f32 v[20:21], v[20:21], v[148:149] op_sel_hi:[1,0]
	v_pk_mul_f32 v[18:19], v[18:19], v[148:149] op_sel_hi:[1,0]
	v_pk_mul_f32 v[16:17], v[16:17], v[148:149] op_sel_hi:[1,0]
	v_pk_mul_f32 v[14:15], v[14:15], v[148:149] op_sel_hi:[1,0]
	v_pk_mul_f32 v[12:13], v[12:13], v[148:149] op_sel_hi:[1,0]
	v_pk_mul_f32 v[10:11], v[10:11], v[148:149] op_sel_hi:[1,0]
	v_pk_mul_f32 v[8:9], v[8:9], v[148:149] op_sel_hi:[1,0]
	v_pk_mul_f32 v[6:7], v[6:7], v[148:149] op_sel_hi:[1,0]
	v_pk_mul_f32 v[4:5], v[4:5], v[148:149] op_sel_hi:[1,0]
	v_pk_mul_f32 v[2:3], v[2:3], v[148:149] op_sel_hi:[1,0]
	v_add_f32_e32 v174, v147, v158
	v_sub_f32_e32 v50, v50, v174
	v_sub_f32_e32 v51, v51, v174
	v_sub_f32_e32 v52, v52, v174
	v_sub_f32_e32 v53, v53, v174
	v_sub_f32_e32 v54, v54, v174
	v_sub_f32_e32 v55, v55, v174
	v_sub_f32_e32 v56, v56, v174
	v_sub_f32_e32 v57, v57, v174
	v_sub_f32_e32 v58, v58, v174
	v_sub_f32_e32 v59, v59, v174
	v_sub_f32_e32 v60, v60, v174
	v_sub_f32_e32 v61, v61, v174
	v_sub_f32_e32 v62, v62, v174
	v_sub_f32_e32 v63, v63, v174
	v_sub_f32_e32 v64, v64, v174
	v_sub_f32_e32 v65, v65, v174
	v_sub_f32_e32 v34, v34, v174
	v_sub_f32_e32 v35, v35, v174
	v_sub_f32_e32 v36, v36, v174
	v_sub_f32_e32 v37, v37, v174
	v_sub_f32_e32 v38, v38, v174
	v_sub_f32_e32 v39, v39, v174
	v_sub_f32_e32 v40, v40, v174
	v_sub_f32_e32 v41, v41, v174
	v_sub_f32_e32 v42, v42, v174
	v_sub_f32_e32 v43, v43, v174
	v_sub_f32_e32 v44, v44, v174
	v_sub_f32_e32 v45, v45, v174
	v_sub_f32_e32 v46, v46, v174
	v_sub_f32_e32 v47, v47, v174
	v_sub_f32_e32 v48, v48, v174
	v_sub_f32_e32 v49, v49, v174
	v_sub_f32_e32 v158, 0, v147
	v_sub_f32_e32 v159, 0, v147
	v_sub_f32_e32 v160, 0, v147
	v_sub_f32_e32 v161, 0, v147
	v_sub_f32_e32 v162, 0, v147
	v_sub_f32_e32 v163, 0, v147
	v_sub_f32_e32 v164, 0, v147
	v_sub_f32_e32 v165, 0, v147
	v_sub_f32_e32 v166, 0, v147
	v_sub_f32_e32 v167, 0, v147
	v_sub_f32_e32 v168, 0, v147
	v_sub_f32_e32 v169, 0, v147
	v_sub_f32_e32 v170, 0, v147
	v_sub_f32_e32 v171, 0, v147
	v_sub_f32_e32 v172, 0, v147
	v_sub_f32_e32 v173, 0, v147
	s_branch .LBB0_844

; #define MFMA32(a, b, c) __builtin_amdgcn_mfma_f32_32x32x16_bf16((a), (b), (c), 0, 0, 0)
; DI void gemm_main_bd(f32x16 (&acc)[4][2], const bf16_t* __restrict__ A, int lda, const bf16_t* __restrict__ Bf, int n0,
;                      int K, char* lds) {
;     ...
;   for (int k = 0; k < nsteps; ++k) {
;     const bf16_t* As = As0 + (k & 1) * (128 * 72);
;     bf16_t* Aw = As0 + ((k + 1) & 1) * (128 * 72);
; #pragma unroll
;     for (int ks = 0; ks < 4; ++ks) { bc[0][ks] = bn[0][ks]; bc[1][ks] = bn[1][ks]; }
;     if (k + 1 < nsteps) {
; #pragma unroll
;       for (int ks = 0; ks < 4; ++ks) {
;         bn[0][ks] = *(const bf16x8*)(Bb0 + (loff + 1024u * (unsigned)(4 * (k + 1) + ks)));
;         bn[1][ks] = *(const bf16x8*)(Bb1 + (loff + 1024u * (unsigned)(4 * (k + 1) + ks)));
;       }
; #pragma unroll
;       for (int i = 0; i < 4; ++i) *(u32x4*)(Aw + (lr + 32 * i) * 72 + lc) = ra[i];
;       if (k + 2 < nsteps) {
; #pragma unroll
;         for (int i = 0; i < 4; ++i) ra[i] = *(const u32x4*)(Ab + (aoff + astep * i + 128u * (unsigned)(k + 2)));
;       }
;     }
;     __builtin_amdgcn_s_setprio(1);
; #pragma unroll
;     for (int ks = 0; ks < 4; ++ks) {
;       bf16x8 af[4];
; #pragma unroll
;       for (int mi = 0; mi < 4; ++mi) af[mi] = *(const bf16x8*)(As + (32 * mi + l31) * 72 + 16 * ks + 8 * h2);
; #pragma unroll
;       for (int mi = 0; mi < 4; ++mi)
; #pragma unroll
;         for (int ni = 0; ni < 2; ++ni) acc[mi][ni] = MFMA32(bc[ni][ks], af[mi], acc[mi][ni]);
;     }
;     __builtin_amdgcn_s_setprio(0);
;     __syncthreads();
;   }
.LBB0_1017:
	s_waitcnt vmcnt(4)
	v_mov_b64_e32 v[208:209], v[132:133]
	v_mov_b64_e32 v[206:207], v[130:131]
	v_lshl_add_u64 v[130:131], v[222:223], 0, s[42:43]
	s_mov_b32 s49, 0x23d1000
	s_and_b32 s45, 1, s28
	s_add_i32 s28, s28, 1
	v_add_co_u32_e32 v132, vcc, s49, v130
	s_and_b32 s48, 1, s28
	s_nop 0
	v_addc_co_u32_e32 v133, vcc, 0, v131, vcc
	s_mov_b32 s49, 0x23e1000
	s_cmp_eq_u32 s45, 1
	v_add_co_u32_e32 v130, vcc, s49, v130
	s_cselect_b32 s45, 0x4800, 0
	s_cmp_eq_u32 s48, 1
	v_addc_co_u32_e32 v131, vcc, 0, v131, vcc
	s_cselect_b32 s48, 0x4800, 0
	global_load_dwordx4 v[198:201], v[132:133], off
	global_load_dwordx4 v[202:205], v[130:131], off
	global_load_dwordx4 v[194:197], v[132:133], off offset:1024
	global_load_dwordx4 v[190:193], v[130:131], off offset:1024
	global_load_dwordx4 v[182:185], v[132:133], off offset:2048
	global_load_dwordx4 v[186:189], v[130:131], off offset:2048
	global_load_dwordx4 v[178:181], v[132:133], off offset:3072
	s_nop 0
	global_load_dwordx4 v[130:133], v[130:131], off offset:3072
	v_add_u32_e32 v0, s48, v236
	s_waitcnt vmcnt(11)
	ds_write_b128 v0, v[134:137]
	s_waitcnt vmcnt(10)
	ds_write_b128 v0, v[138:141] offset:4608
	s_waitcnt vmcnt(9)
	ds_write_b128 v0, v[142:145] offset:9216
	s_waitcnt vmcnt(8)
	ds_write_b128 v0, v[146:149] offset:13824
	v_add_u32_e32 v0, 0xfffd0000, v237
	global_load_dwordx4 v[134:137], v0, s[24:25]
	v_add_u32_e32 v0, 0xfffe0000, v237
	global_load_dwordx4 v[138:141], v0, s[24:25]
	v_add_u32_e32 v0, 0xffff0000, v237
	global_load_dwordx4 v[142:145], v0, s[24:25]
	global_load_dwordx4 v[146:149], v237, s[24:25]
	s_setprio 1
	v_add_u32_e32 v0, s45, v234
	ds_read_b128 v[238:241], v0
	ds_read_b128 v[248:251], v0 offset:4608
	s_waitcnt lgkmcnt(1)
	v_mfma_f32_32x32x16_bf16 v[114:129], v[170:173], v[238:241], v[114:129]
	v_mfma_f32_32x32x16_bf16 v[98:113], v[174:177], v[238:241], v[98:113]
	ds_read_b128 v[238:241], v0 offset:9216
	s_waitcnt lgkmcnt(1)
	v_mfma_f32_32x32x16_bf16 v[82:97], v[170:173], v[248:251], v[82:97]
	v_mfma_f32_32x32x16_bf16 v[66:81], v[174:177], v[248:251], v[66:81]
	ds_read_b128 v[248:251], v0 offset:13824
	s_waitcnt lgkmcnt(1)
	v_mfma_f32_32x32x16_bf16 v[50:65], v[170:173], v[238:241], v[50:65]
	v_mfma_f32_32x32x16_bf16 v[34:49], v[174:177], v[238:241], v[34:49]
	ds_read_b128 v[238:241], v0 offset:32
	s_waitcnt lgkmcnt(1)
	v_mfma_f32_32x32x16_bf16 v[18:33], v[170:173], v[248:251], v[18:33]
	v_mfma_f32_32x32x16_bf16 v[2:17], v[174:177], v[248:251], v[2:17]
	ds_read_b128 v[248:251], v0 offset:4640
	s_waitcnt lgkmcnt(1)
	v_mfma_f32_32x32x16_bf16 v[114:129], v[158:161], v[238:241], v[114:129]
	v_mfma_f32_32x32x16_bf16 v[98:113], v[166:169], v[238:241], v[98:113]
	ds_read_b128 v[238:241], v0 offset:9248
	s_waitcnt lgkmcnt(1)
	v_mfma_f32_32x32x16_bf16 v[82:97], v[158:161], v[248:251], v[82:97]
	v_mfma_f32_32x32x16_bf16 v[66:81], v[166:169], v[248:251], v[66:81]
	ds_read_b128 v[248:251], v0 offset:13856
	s_waitcnt lgkmcnt(1)
	v_mfma_f32_32x32x16_bf16 v[50:65], v[158:161], v[238:241], v[50:65]
	v_mfma_f32_32x32x16_bf16 v[34:49], v[166:169], v[238:241], v[34:49]
	ds_read_b128 v[238:241], v0 offset:64
	s_waitcnt lgkmcnt(1)
	v_mfma_f32_32x32x16_bf16 v[18:33], v[158:161], v[248:251], v[18:33]
	v_mfma_f32_32x32x16_bf16 v[2:17], v[166:169], v[248:251], v[2:17]
	ds_read_b128 v[248:251], v0 offset:4672
	s_waitcnt lgkmcnt(1)
	v_mfma_f32_32x32x16_bf16 v[114:129], v[154:157], v[238:241], v[114:129]
	v_mfma_f32_32x32x16_bf16 v[98:113], v[162:165], v[238:241], v[98:113]
	ds_read_b128 v[238:241], v0 offset:9280
	s_waitcnt lgkmcnt(1)
	v_mfma_f32_32x32x16_bf16 v[82:97], v[154:157], v[248:251], v[82:97]
	v_mfma_f32_32x32x16_bf16 v[66:81], v[162:165], v[248:251], v[66:81]
	ds_read_b128 v[248:251], v0 offset:13888
	s_waitcnt lgkmcnt(1)
	v_mfma_f32_32x32x16_bf16 v[50:65], v[154:157], v[238:241], v[50:65]
	v_mfma_f32_32x32x16_bf16 v[34:49], v[162:165], v[238:241], v[34:49]
	ds_read_b128 v[238:241], v0 offset:96
	s_waitcnt lgkmcnt(1)
	v_mfma_f32_32x32x16_bf16 v[18:33], v[154:157], v[248:251], v[18:33]
	v_mfma_f32_32x32x16_bf16 v[2:17], v[162:165], v[248:251], v[2:17]
	ds_read_b128 v[248:251], v0 offset:4704
	s_waitcnt lgkmcnt(1)
	v_mfma_f32_32x32x16_bf16 v[114:129], v[150:153], v[238:241], v[114:129]
	v_mfma_f32_32x32x16_bf16 v[98:113], v[206:209], v[238:241], v[98:113]
	ds_read_b128 v[238:241], v0 offset:9312
	s_waitcnt lgkmcnt(1)
	v_mfma_f32_32x32x16_bf16 v[82:97], v[150:153], v[248:251], v[82:97]
	v_mfma_f32_32x32x16_bf16 v[66:81], v[206:209], v[248:251], v[66:81]
	ds_read_b128 v[248:251], v0 offset:13920
	s_waitcnt lgkmcnt(1)
	v_mfma_f32_32x32x16_bf16 v[50:65], v[150:153], v[238:241], v[50:65]
	v_mfma_f32_32x32x16_bf16 v[34:49], v[206:209], v[238:241], v[34:49]
	s_waitcnt lgkmcnt(0)
	v_mfma_f32_32x32x16_bf16 v[18:33], v[150:153], v[248:251], v[18:33]
	v_mfma_f32_32x32x16_bf16 v[2:17], v[206:209], v[248:251], v[2:17]
	s_setprio 0
	s_add_u32 s42, s42, 0x1000
	s_addc_u32 s43, s43, 0
	v_add_u32_e32 v237, 0x80, v237
	s_cmpk_eq_u32 s42, 0xe000
	s_waitcnt vmcnt(11)
	v_mov_b32_e32 v170, v198
	v_mov_b32_e32 v171, v199
	v_mov_b32_e32 v172, v200
	v_mov_b32_e32 v173, v201
	s_waitcnt vmcnt(9)
	v_mov_b32_e32 v158, v194
	v_mov_b32_e32 v159, v195
	v_mov_b32_e32 v160, v196
	v_mov_b32_e32 v161, v197
	s_waitcnt vmcnt(7)
	v_mov_b32_e32 v154, v182
	v_mov_b32_e32 v155, v183
	v_mov_b32_e32 v156, v184
	v_mov_b32_e32 v157, v185
	s_waitcnt vmcnt(5)
	v_mov_b32_e32 v150, v178
	v_mov_b32_e32 v151, v179
	v_mov_b32_e32 v152, v180
	v_mov_b32_e32 v153, v181
	v_mov_b32_e32 v174, v202
	v_mov_b32_e32 v175, v203
	v_mov_b32_e32 v176, v204
	v_mov_b32_e32 v177, v205
	v_mov_b32_e32 v166, v190
	v_mov_b32_e32 v167, v191
	v_mov_b32_e32 v168, v192
	v_mov_b32_e32 v169, v193
	v_mov_b32_e32 v162, v186
	v_mov_b32_e32 v163, v187
	v_mov_b32_e32 v164, v188
	v_mov_b32_e32 v165, v189
	s_barrier
; #define MFMA32(a, b, c) __builtin_amdgcn_mfma_f32_32x32x16_bf16((a), (b), (c), 0, 0, 0)
; DI void gemm_main_bd(f32x16 (&acc)[4][2], const bf16_t* __restrict__ A, int lda, const bf16_t* __restrict__ Bf, int n0,
;                      int K, char* lds) {
;     ...
;   for (int k = 0; k < nsteps; ++k) {
;     const bf16_t* As = As0 + (k & 1) * (128 * 72);
;     bf16_t* Aw = As0 + ((k + 1) & 1) * (128 * 72);
; #pragma unroll
;     for (int ks = 0; ks < 4; ++ks) { bc[0][ks] = bn[0][ks]; bc[1][ks] = bn[1][ks]; }
;     if (k + 1 < nsteps) {
; #pragma unroll
;       for (int ks = 0; ks < 4; ++ks) {
;         bn[0][ks] = *(const bf16x8*)(Bb0 + (loff + 1024u * (unsigned)(4 * (k + 1) + ks)));
;         bn[1][ks] = *(const bf16x8*)(Bb1 + (loff + 1024u * (unsigned)(4 * (k + 1) + ks)));
;       }
; #pragma unroll
;       for (int i = 0; i < 4; ++i) *(u32x4*)(Aw + (lr + 32 * i) * 72 + lc) = ra[i];
;       if (k + 2 < nsteps) {
; #pragma unroll
;         for (int i = 0; i < 4; ++i) ra[i] = *(const u32x4*)(Ab + (aoff + astep * i + 128u * (unsigned)(k + 2)));
;       }
;     }
;     __builtin_amdgcn_s_setprio(1);
; #pragma unroll
;     for (int ks = 0; ks < 4; ++ks) {
;       bf16x8 af[4];
; #pragma unroll
;       for (int mi = 0; mi < 4; ++mi) af[mi] = *(const bf16x8*)(As + (32 * mi + l31) * 72 + 16 * ks + 8 * h2);
; #pragma unroll
;       for (int mi = 0; mi < 4; ++mi)
; #pragma unroll
;         for (int ni = 0; ni < 2; ++ni) acc[mi][ni] = MFMA32(bc[ni][ks], af[mi], acc[mi][ni]);
;     }
;     __builtin_amdgcn_s_setprio(0);
;     __syncthreads();
;   }
	s_cbranch_scc0 .LBB0_1017
	v_or_b32_e32 v150, 0xf000, v235
	global_load_dwordx4 v[174:177], v150, s[34:35]
	global_load_dwordx4 v[206:209], v150, s[38:39]
	v_or_b32_e32 v150, 0xf400, v235
	global_load_dwordx4 v[170:173], v150, s[34:35]
	global_load_dwordx4 v[166:169], v150, s[38:39]
	v_or_b32_e32 v150, 0xf800, v235
	global_load_dwordx4 v[158:161], v150, s[34:35]
	global_load_dwordx4 v[162:165], v150, s[38:39]
	v_or_b32_e32 v150, 0xfc00, v235
	global_load_dwordx4 v[154:157], v150, s[34:35]
	s_nop 0
	global_load_dwordx4 v[150:153], v150, s[38:39]
	s_waitcnt vmcnt(11)
	ds_write_b128 v236, v[134:137] offset:18432
	s_waitcnt vmcnt(10)
	ds_write_b128 v236, v[138:141] offset:23040
	s_waitcnt vmcnt(9)
	ds_write_b128 v236, v[142:145] offset:27648
	s_waitcnt vmcnt(8)
	ds_write_b128 v236, v[146:149] offset:32256
	s_setprio 1
	ds_read_b128 v[134:137], v234
	s_waitcnt lgkmcnt(0)
	v_mfma_f32_32x32x16_bf16 v[114:129], v[198:201], v[134:137], v[114:129]
	v_mfma_f32_32x32x16_bf16 v[98:113], v[202:205], v[134:137], v[98:113]
	ds_read_b128 v[134:137], v234 offset:4608
	s_waitcnt lgkmcnt(0)
	v_mfma_f32_32x32x16_bf16 v[82:97], v[198:201], v[134:137], v[82:97]
	v_mfma_f32_32x32x16_bf16 v[66:81], v[202:205], v[134:137], v[66:81]
	ds_read_b128 v[134:137], v234 offset:9216
	s_waitcnt lgkmcnt(0)
	v_mfma_f32_32x32x16_bf16 v[50:65], v[198:201], v[134:137], v[50:65]
	v_mfma_f32_32x32x16_bf16 v[34:49], v[202:205], v[134:137], v[34:49]
	ds_read_b128 v[134:137], v234 offset:13824
	s_waitcnt lgkmcnt(0)
	v_mfma_f32_32x32x16_bf16 v[18:33], v[198:201], v[134:137], v[18:33]
	v_mfma_f32_32x32x16_bf16 v[2:17], v[202:205], v[134:137], v[2:17]
	ds_read_b128 v[134:137], v234 offset:32
	s_waitcnt lgkmcnt(0)
	v_mfma_f32_32x32x16_bf16 v[114:129], v[194:197], v[134:137], v[114:129]
	v_mfma_f32_32x32x16_bf16 v[98:113], v[190:193], v[134:137], v[98:113]
	ds_read_b128 v[134:137], v234 offset:4640
	s_waitcnt lgkmcnt(0)
	v_mfma_f32_32x32x16_bf16 v[82:97], v[194:197], v[134:137], v[82:97]
	v_mfma_f32_32x32x16_bf16 v[66:81], v[190:193], v[134:137], v[66:81]
	ds_read_b128 v[134:137], v234 offset:9248
	s_waitcnt lgkmcnt(0)
	v_mfma_f32_32x32x16_bf16 v[50:65], v[194:197], v[134:137], v[50:65]
	v_mfma_f32_32x32x16_bf16 v[34:49], v[190:193], v[134:137], v[34:49]
	ds_read_b128 v[134:137], v234 offset:13856
	s_waitcnt lgkmcnt(0)
	v_mfma_f32_32x32x16_bf16 v[18:33], v[194:197], v[134:137], v[18:33]
	v_mfma_f32_32x32x16_bf16 v[2:17], v[190:193], v[134:137], v[2:17]
	ds_read_b128 v[134:137], v234 offset:64
	s_waitcnt lgkmcnt(0)
	v_mfma_f32_32x32x16_bf16 v[114:129], v[182:185], v[134:137], v[114:129]
	v_mfma_f32_32x32x16_bf16 v[98:113], v[186:189], v[134:137], v[98:113]
	ds_read_b128 v[134:137], v234 offset:4672
	s_waitcnt lgkmcnt(0)
	v_mfma_f32_32x32x16_bf16 v[82:97], v[182:185], v[134:137], v[82:97]
	v_mfma_f32_32x32x16_bf16 v[66:81], v[186:189], v[134:137], v[66:81]
	ds_read_b128 v[134:137], v234 offset:9280
	s_waitcnt lgkmcnt(0)
	v_mfma_f32_32x32x16_bf16 v[50:65], v[182:185], v[134:137], v[50:65]
	v_mfma_f32_32x32x16_bf16 v[34:49], v[186:189], v[134:137], v[34:49]
	ds_read_b128 v[134:137], v234 offset:13888
	s_waitcnt lgkmcnt(0)
	v_mfma_f32_32x32x16_bf16 v[18:33], v[182:185], v[134:137], v[18:33]
	v_mfma_f32_32x32x16_bf16 v[2:17], v[186:189], v[134:137], v[2:17]
	ds_read_b128 v[134:137], v234 offset:96
	s_waitcnt lgkmcnt(0)
	v_mfma_f32_32x32x16_bf16 v[114:129], v[178:181], v[134:137], v[114:129]
	v_mfma_f32_32x32x16_bf16 v[98:113], v[130:133], v[134:137], v[98:113]
	ds_read_b128 v[134:137], v234 offset:4704
	s_waitcnt lgkmcnt(0)
	v_mfma_f32_32x32x16_bf16 v[82:97], v[178:181], v[134:137], v[82:97]
	v_mfma_f32_32x32x16_bf16 v[66:81], v[130:133], v[134:137], v[66:81]
	ds_read_b128 v[134:137], v234 offset:9312
	s_waitcnt lgkmcnt(0)
	v_mfma_f32_32x32x16_bf16 v[50:65], v[178:181], v[134:137], v[50:65]
	v_mfma_f32_32x32x16_bf16 v[34:49], v[130:133], v[134:137], v[34:49]
	ds_read_b128 v[134:137], v234 offset:13920
	s_waitcnt lgkmcnt(0)
	v_mfma_f32_32x32x16_bf16 v[18:33], v[178:181], v[134:137], v[18:33]
	v_mfma_f32_32x32x16_bf16 v[2:17], v[130:133], v[134:137], v[2:17]
	s_setprio 0
	s_barrier
	s_and_b32 s28, s44, 0x7fffff00
	s_setprio 1
	ds_read_b128 v[130:133], v0
	s_waitcnt vmcnt(7) lgkmcnt(0)
	v_mfma_f32_32x32x16_bf16 v[114:129], v[174:177], v[130:133], v[114:129]
	s_waitcnt vmcnt(6)
	v_mfma_f32_32x32x16_bf16 v[98:113], v[206:209], v[130:133], v[98:113]
	ds_read_b128 v[130:133], v0 offset:4608
	s_waitcnt lgkmcnt(0)
	v_mfma_f32_32x32x16_bf16 v[82:97], v[174:177], v[130:133], v[82:97]
	v_mfma_f32_32x32x16_bf16 v[66:81], v[206:209], v[130:133], v[66:81]
	ds_read_b128 v[130:133], v0 offset:9216
	s_waitcnt lgkmcnt(0)
	v_mfma_f32_32x32x16_bf16 v[50:65], v[174:177], v[130:133], v[50:65]
	v_mfma_f32_32x32x16_bf16 v[34:49], v[206:209], v[130:133], v[34:49]
	ds_read_b128 v[130:133], v0 offset:13824
	s_waitcnt lgkmcnt(0)
	v_mfma_f32_32x32x16_bf16 v[18:33], v[174:177], v[130:133], v[18:33]
	v_mfma_f32_32x32x16_bf16 v[2:17], v[206:209], v[130:133], v[2:17]
	ds_read_b128 v[130:133], v0 offset:32
	s_waitcnt vmcnt(5) lgkmcnt(0)
	v_mfma_f32_32x32x16_bf16 v[114:129], v[170:173], v[130:133], v[114:129]
	s_waitcnt vmcnt(4)
	v_mfma_f32_32x32x16_bf16 v[98:113], v[166:169], v[130:133], v[98:113]
	ds_read_b128 v[130:133], v0 offset:4640
	s_waitcnt lgkmcnt(0)
	v_mfma_f32_32x32x16_bf16 v[82:97], v[170:173], v[130:133], v[82:97]
	v_mfma_f32_32x32x16_bf16 v[66:81], v[166:169], v[130:133], v[66:81]
	ds_read_b128 v[130:133], v0 offset:9248
	s_waitcnt lgkmcnt(0)
	v_mfma_f32_32x32x16_bf16 v[50:65], v[170:173], v[130:133], v[50:65]
	v_mfma_f32_32x32x16_bf16 v[34:49], v[166:169], v[130:133], v[34:49]
	ds_read_b128 v[130:133], v0 offset:13856
	s_waitcnt lgkmcnt(0)
; DI void phase_gemm_resid(const bf16_t* __restrict__ A, int K, const bf16_t* __restrict__ Bf, const float* xsrc, float* x,
;                          float scale, char* lds) {
;     ...
; #pragma unroll
;     for (int mi = 0; mi < 4; ++mi)
; #pragma unroll
;       for (int ni = 0; ni < 2; ++ni) {
;         float4 xs[4];
;         const size_t base = (size_t)(mt * 128 + 32 * mi + l31) * 1024 + nt * 256 + 64 * w + 32 * ni + 4 * h2;
; #pragma unroll
;         for (int g = 0; g < 4; ++g) xs[g] = *(const float4*)(xsrc + base + 8 * g);
; #pragma unroll
;         for (int g = 0; g < 4; ++g) {
;           float4 o;
;           o.x = xs[g].x + scale * a0[mi][ni][4 * g];
;           o.y = xs[g].y + scale * a0[mi][ni][4 * g + 1];
;           o.z = xs[g].z + scale * a0[mi][ni][4 * g + 2];
;           o.w = xs[g].w + scale * a0[mi][ni][4 * g + 3];
;           *(float4*)(x + base + 8 * g) = o;
;         }
;       }
	v_mfma_f32_32x32x16_bf16 v[18:33], v[170:173], v[130:133], v[18:33]
	v_mfma_f32_32x32x16_bf16 v[2:17], v[166:169], v[130:133], v[2:17]
	ds_read_b128 v[130:133], v0 offset:64
	s_waitcnt vmcnt(3) lgkmcnt(0)
	v_mfma_f32_32x32x16_bf16 v[114:129], v[158:161], v[130:133], v[114:129]
	s_waitcnt vmcnt(2)
	v_mfma_f32_32x32x16_bf16 v[98:113], v[162:165], v[130:133], v[98:113]
	ds_read_b128 v[130:133], v0 offset:4672
	s_waitcnt lgkmcnt(0)
	v_mfma_f32_32x32x16_bf16 v[82:97], v[158:161], v[130:133], v[82:97]
	v_mfma_f32_32x32x16_bf16 v[66:81], v[162:165], v[130:133], v[66:81]
	ds_read_b128 v[130:133], v0 offset:9280
	s_waitcnt lgkmcnt(0)
	v_mfma_f32_32x32x16_bf16 v[50:65], v[158:161], v[130:133], v[50:65]
	v_mfma_f32_32x32x16_bf16 v[34:49], v[162:165], v[130:133], v[34:49]
	ds_read_b128 v[130:133], v0 offset:13888
	s_waitcnt lgkmcnt(0)
	v_mfma_f32_32x32x16_bf16 v[18:33], v[158:161], v[130:133], v[18:33]
	v_mfma_f32_32x32x16_bf16 v[2:17], v[162:165], v[130:133], v[2:17]
	ds_read_b128 v[130:133], v0 offset:96
	s_waitcnt vmcnt(1) lgkmcnt(0)
	v_mfma_f32_32x32x16_bf16 v[114:129], v[154:157], v[130:133], v[114:129]
	s_waitcnt vmcnt(0)
	v_mfma_f32_32x32x16_bf16 v[98:113], v[150:153], v[130:133], v[98:113]
	ds_read_b128 v[130:133], v0 offset:4704
	s_waitcnt lgkmcnt(0)
	v_mfma_f32_32x32x16_bf16 v[82:97], v[154:157], v[130:133], v[82:97]
	v_mfma_f32_32x32x16_bf16 v[66:81], v[150:153], v[130:133], v[66:81]
	ds_read_b128 v[130:133], v0 offset:9312
	s_waitcnt lgkmcnt(0)
	v_mfma_f32_32x32x16_bf16 v[50:65], v[154:157], v[130:133], v[50:65]
	v_mfma_f32_32x32x16_bf16 v[34:49], v[150:153], v[130:133], v[34:49]
	ds_read_b128 v[130:133], v0 offset:13920
	s_waitcnt lgkmcnt(0)
	v_mfma_f32_32x32x16_bf16 v[18:33], v[154:157], v[130:133], v[18:33]
	v_mfma_f32_32x32x16_bf16 v[2:17], v[150:153], v[130:133], v[2:17]
	s_setprio 0
	v_lshl_add_u64 v[130:131], v[220:221], 0, s[28:29]
	v_or_b32_e32 v0, s41, v233
	v_lshl_add_u64 v[130:131], v[130:131], 2, s[0:1]
	v_lshlrev_b32_e32 v0, 2, v0
	v_lshl_add_u64 v[130:131], v[130:131], 0, v[0:1]
	s_barrier
	s_mov_b32 s24, 0x40000
	s_add_i32 s40, s40, 1
	v_readlane_b32 s25, v243, 23
	s_mov_b32 s24, 0x60000
	s_mul_i32 s24, s40, s66
	s_add_i32 s24, s24, s3
	s_cmp_ge_u32 s24, s25
	s_mov_b32 s100, 0x20000
	s_mov_b32 s101, 0
	v_lshl_add_u64 v[140:141], v[130:131], 0, s[100:101]
	v_lshl_add_u64 v[142:143], v[140:141], 0, s[100:101]
	v_lshl_add_u64 v[144:145], v[142:143], 0, s[100:101]
	global_load_dwordx4 v[146:149], v[130:131], off
	global_load_dwordx4 v[150:153], v[130:131], off offset:32
	global_load_dwordx4 v[154:157], v[130:131], off offset:64
	global_load_dwordx4 v[158:161], v[130:131], off offset:96
	global_load_dwordx4 v[162:165], v[130:131], off offset:128
	global_load_dwordx4 v[166:169], v[130:131], off offset:160
	global_load_dwordx4 v[170:173], v[130:131], off offset:192
	global_load_dwordx4 v[174:177], v[130:131], off offset:224
	global_load_dwordx4 v[178:181], v[140:141], off
	global_load_dwordx4 v[182:185], v[140:141], off offset:32
	global_load_dwordx4 v[186:189], v[140:141], off offset:64
	global_load_dwordx4 v[190:193], v[140:141], off offset:96
	global_load_dwordx4 v[194:197], v[140:141], off offset:128
	global_load_dwordx4 v[198:201], v[140:141], off offset:160
	global_load_dwordx4 v[202:205], v[140:141], off offset:192
	global_load_dwordx4 v[206:209], v[140:141], off offset:224
	s_waitcnt vmcnt(8)
	v_pk_add_f32 v[114:115], v[114:115], v[146:147]
	v_pk_add_f32 v[116:117], v[116:117], v[148:149]
	v_pk_add_f32 v[118:119], v[118:119], v[150:151]
	v_pk_add_f32 v[120:121], v[120:121], v[152:153]
	v_pk_add_f32 v[122:123], v[122:123], v[154:155]
	v_pk_add_f32 v[124:125], v[124:125], v[156:157]
	v_pk_add_f32 v[126:127], v[126:127], v[158:159]
	v_pk_add_f32 v[128:129], v[128:129], v[160:161]
	v_pk_add_f32 v[98:99], v[98:99], v[162:163]
	v_pk_add_f32 v[100:101], v[100:101], v[164:165]
	v_pk_add_f32 v[102:103], v[102:103], v[166:167]
	v_pk_add_f32 v[104:105], v[104:105], v[168:169]
	v_pk_add_f32 v[106:107], v[106:107], v[170:171]
	v_pk_add_f32 v[108:109], v[108:109], v[172:173]
	v_pk_add_f32 v[110:111], v[110:111], v[174:175]
	v_pk_add_f32 v[112:113], v[112:113], v[176:177]
	global_store_dwordx4 v[130:131], v[114:117], off
	global_store_dwordx4 v[130:131], v[118:121], off offset:32
	global_store_dwordx4 v[130:131], v[122:125], off offset:64
	global_store_dwordx4 v[130:131], v[126:129], off offset:96
	global_store_dwordx4 v[130:131], v[98:101], off offset:128
	global_store_dwordx4 v[130:131], v[102:105], off offset:160
	global_store_dwordx4 v[130:131], v[106:109], off offset:192
	global_store_dwordx4 v[130:131], v[110:113], off offset:224
	global_load_dwordx4 v[146:149], v[142:143], off
	global_load_dwordx4 v[150:153], v[142:143], off offset:32
	global_load_dwordx4 v[154:157], v[142:143], off offset:64
	global_load_dwordx4 v[158:161], v[142:143], off offset:96
	global_load_dwordx4 v[162:165], v[142:143], off offset:128
	global_load_dwordx4 v[166:169], v[142:143], off offset:160
	global_load_dwordx4 v[170:173], v[142:143], off offset:192
	global_load_dwordx4 v[174:177], v[142:143], off offset:224
	s_waitcnt vmcnt(16)
; DI void phase_gemm_resid(const bf16_t* __restrict__ A, int K, const bf16_t* __restrict__ Bf, const float* xsrc, float* x,
;                          float scale, char* lds) {
;     ...
; #pragma unroll
;     for (int mi = 0; mi < 4; ++mi)
; #pragma unroll
;       for (int ni = 0; ni < 2; ++ni) {
;         float4 xs[4];
;         const size_t base = (size_t)(mt * 128 + 32 * mi + l31) * 1024 + nt * 256 + 64 * w + 32 * ni + 4 * h2;
; #pragma unroll
;         for (int g = 0; g < 4; ++g) xs[g] = *(const float4*)(xsrc + base + 8 * g);
; #pragma unroll
;         for (int g = 0; g < 4; ++g) {
;           float4 o;
;           o.x = xs[g].x + scale * a0[mi][ni][4 * g];
;           o.y = xs[g].y + scale * a0[mi][ni][4 * g + 1];
;           o.z = xs[g].z + scale * a0[mi][ni][4 * g + 2];
;           o.w = xs[g].w + scale * a0[mi][ni][4 * g + 3];
;           *(float4*)(x + base + 8 * g) = o;
;         }
;       }
	v_pk_add_f32 v[82:83], v[82:83], v[178:179]
	v_pk_add_f32 v[84:85], v[84:85], v[180:181]
	v_pk_add_f32 v[86:87], v[86:87], v[182:183]
	v_pk_add_f32 v[88:89], v[88:89], v[184:185]
	v_pk_add_f32 v[90:91], v[90:91], v[186:187]
	v_pk_add_f32 v[92:93], v[92:93], v[188:189]
	v_pk_add_f32 v[94:95], v[94:95], v[190:191]
	v_pk_add_f32 v[96:97], v[96:97], v[192:193]
	v_pk_add_f32 v[66:67], v[66:67], v[194:195]
	v_pk_add_f32 v[68:69], v[68:69], v[196:197]
	v_pk_add_f32 v[70:71], v[70:71], v[198:199]
	v_pk_add_f32 v[72:73], v[72:73], v[200:201]
	v_pk_add_f32 v[74:75], v[74:75], v[202:203]
	v_pk_add_f32 v[76:77], v[76:77], v[204:205]
	v_pk_add_f32 v[78:79], v[78:79], v[206:207]
	v_pk_add_f32 v[80:81], v[80:81], v[208:209]
	global_store_dwordx4 v[140:141], v[82:85], off
	global_store_dwordx4 v[140:141], v[86:89], off offset:32
	global_store_dwordx4 v[140:141], v[90:93], off offset:64
	global_store_dwordx4 v[140:141], v[94:97], off offset:96
	global_store_dwordx4 v[140:141], v[66:69], off offset:128
	global_store_dwordx4 v[140:141], v[70:73], off offset:160
	global_store_dwordx4 v[140:141], v[74:77], off offset:192
	global_store_dwordx4 v[140:141], v[78:81], off offset:224
	global_load_dwordx4 v[178:181], v[144:145], off
	global_load_dwordx4 v[182:185], v[144:145], off offset:32
	global_load_dwordx4 v[186:189], v[144:145], off offset:64
	global_load_dwordx4 v[190:193], v[144:145], off offset:96
	global_load_dwordx4 v[194:197], v[144:145], off offset:128
	global_load_dwordx4 v[198:201], v[144:145], off offset:160
	global_load_dwordx4 v[202:205], v[144:145], off offset:192
	global_load_dwordx4 v[206:209], v[144:145], off offset:224
	s_waitcnt vmcnt(16)
	v_pk_add_f32 v[50:51], v[50:51], v[146:147]
	v_pk_add_f32 v[52:53], v[52:53], v[148:149]
	v_pk_add_f32 v[54:55], v[54:55], v[150:151]
	v_pk_add_f32 v[56:57], v[56:57], v[152:153]
	v_pk_add_f32 v[58:59], v[58:59], v[154:155]
	v_pk_add_f32 v[60:61], v[60:61], v[156:157]
	v_pk_add_f32 v[62:63], v[62:63], v[158:159]
	v_pk_add_f32 v[64:65], v[64:65], v[160:161]
	v_pk_add_f32 v[34:35], v[34:35], v[162:163]
	v_pk_add_f32 v[36:37], v[36:37], v[164:165]
	v_pk_add_f32 v[38:39], v[38:39], v[166:167]
	v_pk_add_f32 v[40:41], v[40:41], v[168:169]
	v_pk_add_f32 v[42:43], v[42:43], v[170:171]
	v_pk_add_f32 v[44:45], v[44:45], v[172:173]
	v_pk_add_f32 v[46:47], v[46:47], v[174:175]
	v_pk_add_f32 v[48:49], v[48:49], v[176:177]
	global_store_dwordx4 v[142:143], v[50:53], off
	global_store_dwordx4 v[142:143], v[54:57], off offset:32
	global_store_dwordx4 v[142:143], v[58:61], off offset:64
	global_store_dwordx4 v[142:143], v[62:65], off offset:96
	global_store_dwordx4 v[142:143], v[34:37], off offset:128
	global_store_dwordx4 v[142:143], v[38:41], off offset:160
	global_store_dwordx4 v[142:143], v[42:45], off offset:192
	global_store_dwordx4 v[142:143], v[46:49], off offset:224
	s_waitcnt vmcnt(8)
	v_pk_add_f32 v[18:19], v[18:19], v[178:179]
	v_pk_add_f32 v[20:21], v[20:21], v[180:181]
	v_pk_add_f32 v[22:23], v[22:23], v[182:183]
	v_pk_add_f32 v[24:25], v[24:25], v[184:185]
	v_pk_add_f32 v[26:27], v[26:27], v[186:187]
	v_pk_add_f32 v[28:29], v[28:29], v[188:189]
	v_pk_add_f32 v[30:31], v[30:31], v[190:191]
	v_pk_add_f32 v[32:33], v[32:33], v[192:193]
	v_pk_add_f32 v[2:3], v[2:3], v[194:195]
	v_pk_add_f32 v[4:5], v[4:5], v[196:197]
	v_pk_add_f32 v[6:7], v[6:7], v[198:199]
	v_pk_add_f32 v[8:9], v[8:9], v[200:201]
	v_pk_add_f32 v[10:11], v[10:11], v[202:203]
	v_pk_add_f32 v[12:13], v[12:13], v[204:205]
	v_pk_add_f32 v[14:15], v[14:15], v[206:207]
	v_pk_add_f32 v[16:17], v[16:17], v[208:209]
	global_store_dwordx4 v[144:145], v[18:21], off
	global_store_dwordx4 v[144:145], v[22:25], off offset:32
	global_store_dwordx4 v[144:145], v[26:29], off offset:64
	global_store_dwordx4 v[144:145], v[30:33], off offset:96
	global_store_dwordx4 v[144:145], v[2:5], off offset:128
	global_store_dwordx4 v[144:145], v[6:9], off offset:160
	global_store_dwordx4 v[144:145], v[10:13], off offset:192
	global_store_dwordx4 v[144:145], v[14:17], off offset:224
	s_cbranch_scc0 .LBB0_1016

; #define MFMA32(a, b, c) __builtin_amdgcn_mfma_f32_32x32x16_bf16((a), (b), (c), 0, 0, 0)
; DI void gemm_main_bd(f32x16 (&acc)[4][2], const bf16_t* __restrict__ A, int lda, const bf16_t* __restrict__ Bf, int n0,
;                      int K, char* lds) {
;     ...
;   for (int k = 0; k < nsteps; ++k) {
;     const bf16_t* As = As0 + (k & 1) * (128 * 72);
;     bf16_t* Aw = As0 + ((k + 1) & 1) * (128 * 72);
; #pragma unroll
;     for (int ks = 0; ks < 4; ++ks) { bc[0][ks] = bn[0][ks]; bc[1][ks] = bn[1][ks]; }
;     if (k + 1 < nsteps) {
; #pragma unroll
;       for (int ks = 0; ks < 4; ++ks) {
;         bn[0][ks] = *(const bf16x8*)(Bb0 + (loff + 1024u * (unsigned)(4 * (k + 1) + ks)));
;         bn[1][ks] = *(const bf16x8*)(Bb1 + (loff + 1024u * (unsigned)(4 * (k + 1) + ks)));
;       }
; #pragma unroll
;       for (int i = 0; i < 4; ++i) *(u32x4*)(Aw + (lr + 32 * i) * 72 + lc) = ra[i];
;       if (k + 2 < nsteps) {
; #pragma unroll
;         for (int i = 0; i < 4; ++i) ra[i] = *(const u32x4*)(Ab + (aoff + astep * i + 128u * (unsigned)(k + 2)));
;       }
;     }
;     __builtin_amdgcn_s_setprio(1);
; #pragma unroll
;     for (int ks = 0; ks < 4; ++ks) {
;       bf16x8 af[4];
; #pragma unroll
;       for (int mi = 0; mi < 4; ++mi) af[mi] = *(const bf16x8*)(As + (32 * mi + l31) * 72 + 16 * ks + 8 * h2);
; #pragma unroll
;       for (int mi = 0; mi < 4; ++mi)
; #pragma unroll
;         for (int ni = 0; ni < 2; ++ni) acc[mi][ni] = MFMA32(bc[ni][ks], af[mi], acc[mi][ni]);
;     }
;     __builtin_amdgcn_s_setprio(0);
;     __syncthreads();
;   }
.LBB0_1181:
	s_waitcnt vmcnt(4)
	v_mov_b64_e32 v[208:209], v[132:133]
	v_mov_b64_e32 v[206:207], v[130:131]
	v_lshl_add_u64 v[130:131], v[222:223], 0, s[42:43]
	s_mov_b32 s49, 0x30d1000
	s_and_b32 s45, 1, s44
	s_add_i32 s44, s44, 1
	v_add_co_u32_e32 v132, vcc, s49, v130
	s_and_b32 s48, 1, s44
	s_nop 0
	v_addc_co_u32_e32 v133, vcc, 0, v131, vcc
	s_mov_b32 s49, 0x30fd000
	s_cmp_eq_u32 s45, 1
	v_add_co_u32_e32 v130, vcc, s49, v130
	s_cselect_b32 s45, 0x4800, 0
	s_cmp_eq_u32 s48, 1
	v_addc_co_u32_e32 v131, vcc, 0, v131, vcc
	s_cselect_b32 s48, 0x4800, 0
	global_load_dwordx4 v[198:201], v[132:133], off
	global_load_dwordx4 v[202:205], v[130:131], off
	global_load_dwordx4 v[194:197], v[132:133], off offset:1024
	global_load_dwordx4 v[190:193], v[130:131], off offset:1024
	global_load_dwordx4 v[182:185], v[132:133], off offset:2048
	global_load_dwordx4 v[186:189], v[130:131], off offset:2048
	global_load_dwordx4 v[178:181], v[132:133], off offset:3072
	s_nop 0
	global_load_dwordx4 v[130:133], v[130:131], off offset:3072
	v_add_u32_e32 v0, s48, v236
	s_waitcnt vmcnt(11)
	ds_write_b128 v0, v[134:137]
	s_waitcnt vmcnt(10)
	ds_write_b128 v0, v[138:141] offset:4608
	s_waitcnt vmcnt(9)
	ds_write_b128 v0, v[142:145] offset:9216
	s_waitcnt vmcnt(8)
	ds_write_b128 v0, v[146:149] offset:13824
	v_add_u32_e32 v0, 0xfff7c000, v237
	global_load_dwordx4 v[134:137], v0, s[24:25]
	v_add_u32_e32 v0, 0xfffa8000, v237
	global_load_dwordx4 v[138:141], v0, s[24:25]
	v_add_u32_e32 v0, 0xfffd4000, v237
	global_load_dwordx4 v[142:145], v0, s[24:25]
	global_load_dwordx4 v[146:149], v237, s[24:25]
	s_setprio 1
	v_add_u32_e32 v0, s45, v234
	ds_read_b128 v[238:241], v0
	ds_read_b128 v[248:251], v0 offset:4608
	s_waitcnt lgkmcnt(1)
	v_mfma_f32_32x32x16_bf16 v[114:129], v[170:173], v[238:241], v[114:129]
	v_mfma_f32_32x32x16_bf16 v[98:113], v[174:177], v[238:241], v[98:113]
	ds_read_b128 v[238:241], v0 offset:9216
	s_waitcnt lgkmcnt(1)
	v_mfma_f32_32x32x16_bf16 v[82:97], v[170:173], v[248:251], v[82:97]
	v_mfma_f32_32x32x16_bf16 v[66:81], v[174:177], v[248:251], v[66:81]
	ds_read_b128 v[248:251], v0 offset:13824
	s_waitcnt lgkmcnt(1)
	v_mfma_f32_32x32x16_bf16 v[50:65], v[170:173], v[238:241], v[50:65]
	v_mfma_f32_32x32x16_bf16 v[34:49], v[174:177], v[238:241], v[34:49]
	ds_read_b128 v[238:241], v0 offset:32
	s_waitcnt lgkmcnt(1)
	v_mfma_f32_32x32x16_bf16 v[18:33], v[170:173], v[248:251], v[18:33]
	v_mfma_f32_32x32x16_bf16 v[2:17], v[174:177], v[248:251], v[2:17]
	ds_read_b128 v[248:251], v0 offset:4640
	s_waitcnt lgkmcnt(1)
	v_mfma_f32_32x32x16_bf16 v[114:129], v[158:161], v[238:241], v[114:129]
	v_mfma_f32_32x32x16_bf16 v[98:113], v[166:169], v[238:241], v[98:113]
	ds_read_b128 v[238:241], v0 offset:9248
	s_waitcnt lgkmcnt(1)
	v_mfma_f32_32x32x16_bf16 v[82:97], v[158:161], v[248:251], v[82:97]
	v_mfma_f32_32x32x16_bf16 v[66:81], v[166:169], v[248:251], v[66:81]
	ds_read_b128 v[248:251], v0 offset:13856
	s_waitcnt lgkmcnt(1)
	v_mfma_f32_32x32x16_bf16 v[50:65], v[158:161], v[238:241], v[50:65]
	v_mfma_f32_32x32x16_bf16 v[34:49], v[166:169], v[238:241], v[34:49]
	ds_read_b128 v[238:241], v0 offset:64
	s_waitcnt lgkmcnt(1)
	v_mfma_f32_32x32x16_bf16 v[18:33], v[158:161], v[248:251], v[18:33]
	v_mfma_f32_32x32x16_bf16 v[2:17], v[166:169], v[248:251], v[2:17]
	ds_read_b128 v[248:251], v0 offset:4672
	s_waitcnt lgkmcnt(1)
	v_mfma_f32_32x32x16_bf16 v[114:129], v[154:157], v[238:241], v[114:129]
	v_mfma_f32_32x32x16_bf16 v[98:113], v[162:165], v[238:241], v[98:113]
	ds_read_b128 v[238:241], v0 offset:9280
	s_waitcnt lgkmcnt(1)
	v_mfma_f32_32x32x16_bf16 v[82:97], v[154:157], v[248:251], v[82:97]
	v_mfma_f32_32x32x16_bf16 v[66:81], v[162:165], v[248:251], v[66:81]
	ds_read_b128 v[248:251], v0 offset:13888
	s_waitcnt lgkmcnt(1)
	v_mfma_f32_32x32x16_bf16 v[50:65], v[154:157], v[238:241], v[50:65]
	v_mfma_f32_32x32x16_bf16 v[34:49], v[162:165], v[238:241], v[34:49]
	ds_read_b128 v[238:241], v0 offset:96
	s_waitcnt lgkmcnt(1)
	v_mfma_f32_32x32x16_bf16 v[18:33], v[154:157], v[248:251], v[18:33]
	v_mfma_f32_32x32x16_bf16 v[2:17], v[162:165], v[248:251], v[2:17]
	ds_read_b128 v[248:251], v0 offset:4704
	s_waitcnt lgkmcnt(1)
	v_mfma_f32_32x32x16_bf16 v[114:129], v[150:153], v[238:241], v[114:129]
	v_mfma_f32_32x32x16_bf16 v[98:113], v[206:209], v[238:241], v[98:113]
	ds_read_b128 v[238:241], v0 offset:9312
	s_waitcnt lgkmcnt(1)
	v_mfma_f32_32x32x16_bf16 v[82:97], v[150:153], v[248:251], v[82:97]
	v_mfma_f32_32x32x16_bf16 v[66:81], v[206:209], v[248:251], v[66:81]
	ds_read_b128 v[248:251], v0 offset:13920
	s_waitcnt lgkmcnt(1)
	v_mfma_f32_32x32x16_bf16 v[50:65], v[150:153], v[238:241], v[50:65]
	v_mfma_f32_32x32x16_bf16 v[34:49], v[206:209], v[238:241], v[34:49]
	s_waitcnt lgkmcnt(0)
	v_mfma_f32_32x32x16_bf16 v[18:33], v[150:153], v[248:251], v[18:33]
	v_mfma_f32_32x32x16_bf16 v[2:17], v[206:209], v[248:251], v[2:17]
	s_setprio 0
	s_add_u32 s42, s42, 0x1000
	s_addc_u32 s43, s43, 0
	v_add_u32_e32 v237, 0x80, v237
	s_cmp_eq_u32 s42, 0x2a000
	s_waitcnt vmcnt(11)
	v_mov_b32_e32 v170, v198
	v_mov_b32_e32 v171, v199
	v_mov_b32_e32 v172, v200
	v_mov_b32_e32 v173, v201
	s_waitcnt vmcnt(9)
	v_mov_b32_e32 v158, v194
	v_mov_b32_e32 v159, v195
	v_mov_b32_e32 v160, v196
	v_mov_b32_e32 v161, v197
	s_waitcnt vmcnt(7)
	v_mov_b32_e32 v154, v182
	v_mov_b32_e32 v155, v183
	v_mov_b32_e32 v156, v184
	v_mov_b32_e32 v157, v185
	s_waitcnt vmcnt(5)
	v_mov_b32_e32 v150, v178
	v_mov_b32_e32 v151, v179
	v_mov_b32_e32 v152, v180
	v_mov_b32_e32 v153, v181
	v_mov_b32_e32 v174, v202
	v_mov_b32_e32 v175, v203
	v_mov_b32_e32 v176, v204
	v_mov_b32_e32 v177, v205
	v_mov_b32_e32 v166, v190
	v_mov_b32_e32 v167, v191
	v_mov_b32_e32 v168, v192
	v_mov_b32_e32 v169, v193
	v_mov_b32_e32 v162, v186
	v_mov_b32_e32 v163, v187
	v_mov_b32_e32 v164, v188
	v_mov_b32_e32 v165, v189
	s_barrier
; #define MFMA32(a, b, c) __builtin_amdgcn_mfma_f32_32x32x16_bf16((a), (b), (c), 0, 0, 0)
; DI void gemm_main_bd(f32x16 (&acc)[4][2], const bf16_t* __restrict__ A, int lda, const bf16_t* __restrict__ Bf, int n0,
;                      int K, char* lds) {
;     ...
;   for (int k = 0; k < nsteps; ++k) {
;     const bf16_t* As = As0 + (k & 1) * (128 * 72);
;     bf16_t* Aw = As0 + ((k + 1) & 1) * (128 * 72);
; #pragma unroll
;     for (int ks = 0; ks < 4; ++ks) { bc[0][ks] = bn[0][ks]; bc[1][ks] = bn[1][ks]; }
;     if (k + 1 < nsteps) {
; #pragma unroll
;       for (int ks = 0; ks < 4; ++ks) {
;         bn[0][ks] = *(const bf16x8*)(Bb0 + (loff + 1024u * (unsigned)(4 * (k + 1) + ks)));
;         bn[1][ks] = *(const bf16x8*)(Bb1 + (loff + 1024u * (unsigned)(4 * (k + 1) + ks)));
;       }
; #pragma unroll
;       for (int i = 0; i < 4; ++i) *(u32x4*)(Aw + (lr + 32 * i) * 72 + lc) = ra[i];
;       if (k + 2 < nsteps) {
; #pragma unroll
;         for (int i = 0; i < 4; ++i) ra[i] = *(const u32x4*)(Ab + (aoff + astep * i + 128u * (unsigned)(k + 2)));
;       }
;     }
;     __builtin_amdgcn_s_setprio(1);
; #pragma unroll
;     for (int ks = 0; ks < 4; ++ks) {
;       bf16x8 af[4];
; #pragma unroll
;       for (int mi = 0; mi < 4; ++mi) af[mi] = *(const bf16x8*)(As + (32 * mi + l31) * 72 + 16 * ks + 8 * h2);
; #pragma unroll
;       for (int mi = 0; mi < 4; ++mi)
; #pragma unroll
;         for (int ni = 0; ni < 2; ++ni) acc[mi][ni] = MFMA32(bc[ni][ks], af[mi], acc[mi][ni]);
;     }
;     __builtin_amdgcn_s_setprio(0);
;     __syncthreads();
;   }
	s_cbranch_scc0 .LBB0_1181
	v_or_b32_e32 v150, 0x2b000, v235
	global_load_dwordx4 v[174:177], v150, s[34:35]
	global_load_dwordx4 v[206:209], v150, s[38:39]
	v_or_b32_e32 v150, 0x2b400, v235
	global_load_dwordx4 v[170:173], v150, s[34:35]
	global_load_dwordx4 v[166:169], v150, s[38:39]
	v_or_b32_e32 v150, 0x2b800, v235
	global_load_dwordx4 v[158:161], v150, s[34:35]
	global_load_dwordx4 v[162:165], v150, s[38:39]
	v_or_b32_e32 v150, 0x2bc00, v235
	global_load_dwordx4 v[154:157], v150, s[34:35]
	s_nop 0
	global_load_dwordx4 v[150:153], v150, s[38:39]
	s_waitcnt vmcnt(11)
	ds_write_b128 v236, v[134:137] offset:18432
	s_waitcnt vmcnt(10)
	ds_write_b128 v236, v[138:141] offset:23040
	s_waitcnt vmcnt(9)
	ds_write_b128 v236, v[142:145] offset:27648
	s_waitcnt vmcnt(8)
	ds_write_b128 v236, v[146:149] offset:32256
	s_setprio 1
	ds_read_b128 v[134:137], v234
	s_waitcnt lgkmcnt(0)
	v_mfma_f32_32x32x16_bf16 v[114:129], v[198:201], v[134:137], v[114:129]
	v_mfma_f32_32x32x16_bf16 v[98:113], v[202:205], v[134:137], v[98:113]
	ds_read_b128 v[134:137], v234 offset:4608
	s_waitcnt lgkmcnt(0)
	v_mfma_f32_32x32x16_bf16 v[82:97], v[198:201], v[134:137], v[82:97]
	v_mfma_f32_32x32x16_bf16 v[66:81], v[202:205], v[134:137], v[66:81]
	ds_read_b128 v[134:137], v234 offset:9216
	s_waitcnt lgkmcnt(0)
	v_mfma_f32_32x32x16_bf16 v[50:65], v[198:201], v[134:137], v[50:65]
	v_mfma_f32_32x32x16_bf16 v[34:49], v[202:205], v[134:137], v[34:49]
	ds_read_b128 v[134:137], v234 offset:13824
	s_waitcnt lgkmcnt(0)
	v_mfma_f32_32x32x16_bf16 v[18:33], v[198:201], v[134:137], v[18:33]
	v_mfma_f32_32x32x16_bf16 v[2:17], v[202:205], v[134:137], v[2:17]
	ds_read_b128 v[134:137], v234 offset:32
	s_waitcnt lgkmcnt(0)
	v_mfma_f32_32x32x16_bf16 v[114:129], v[194:197], v[134:137], v[114:129]
	v_mfma_f32_32x32x16_bf16 v[98:113], v[190:193], v[134:137], v[98:113]
	ds_read_b128 v[134:137], v234 offset:4640
	s_waitcnt lgkmcnt(0)
	v_mfma_f32_32x32x16_bf16 v[82:97], v[194:197], v[134:137], v[82:97]
	v_mfma_f32_32x32x16_bf16 v[66:81], v[190:193], v[134:137], v[66:81]
	ds_read_b128 v[134:137], v234 offset:9248
	s_waitcnt lgkmcnt(0)
	v_mfma_f32_32x32x16_bf16 v[50:65], v[194:197], v[134:137], v[50:65]
	v_mfma_f32_32x32x16_bf16 v[34:49], v[190:193], v[134:137], v[34:49]
	ds_read_b128 v[134:137], v234 offset:13856
	s_waitcnt lgkmcnt(0)
	v_mfma_f32_32x32x16_bf16 v[18:33], v[194:197], v[134:137], v[18:33]
	v_mfma_f32_32x32x16_bf16 v[2:17], v[190:193], v[134:137], v[2:17]
	ds_read_b128 v[134:137], v234 offset:64
	s_waitcnt lgkmcnt(0)
	v_mfma_f32_32x32x16_bf16 v[114:129], v[182:185], v[134:137], v[114:129]
	v_mfma_f32_32x32x16_bf16 v[98:113], v[186:189], v[134:137], v[98:113]
	ds_read_b128 v[134:137], v234 offset:4672
	s_waitcnt lgkmcnt(0)
	v_mfma_f32_32x32x16_bf16 v[82:97], v[182:185], v[134:137], v[82:97]
	v_mfma_f32_32x32x16_bf16 v[66:81], v[186:189], v[134:137], v[66:81]
	ds_read_b128 v[134:137], v234 offset:9280
	s_waitcnt lgkmcnt(0)
	v_mfma_f32_32x32x16_bf16 v[50:65], v[182:185], v[134:137], v[50:65]
	v_mfma_f32_32x32x16_bf16 v[34:49], v[186:189], v[134:137], v[34:49]
	ds_read_b128 v[134:137], v234 offset:13888
	s_waitcnt lgkmcnt(0)
	v_mfma_f32_32x32x16_bf16 v[18:33], v[182:185], v[134:137], v[18:33]
	v_mfma_f32_32x32x16_bf16 v[2:17], v[186:189], v[134:137], v[2:17]
	ds_read_b128 v[134:137], v234 offset:96
	s_waitcnt lgkmcnt(0)
	v_mfma_f32_32x32x16_bf16 v[114:129], v[178:181], v[134:137], v[114:129]
	v_mfma_f32_32x32x16_bf16 v[98:113], v[130:133], v[134:137], v[98:113]
	ds_read_b128 v[134:137], v234 offset:4704
	s_waitcnt lgkmcnt(0)
	v_mfma_f32_32x32x16_bf16 v[82:97], v[178:181], v[134:137], v[82:97]
	v_mfma_f32_32x32x16_bf16 v[66:81], v[130:133], v[134:137], v[66:81]
	ds_read_b128 v[134:137], v234 offset:9312
	s_waitcnt lgkmcnt(0)
	v_mfma_f32_32x32x16_bf16 v[50:65], v[178:181], v[134:137], v[50:65]
	v_mfma_f32_32x32x16_bf16 v[34:49], v[130:133], v[134:137], v[34:49]
	ds_read_b128 v[134:137], v234 offset:13920
	s_waitcnt lgkmcnt(0)
	v_mfma_f32_32x32x16_bf16 v[18:33], v[178:181], v[134:137], v[18:33]
	v_mfma_f32_32x32x16_bf16 v[2:17], v[130:133], v[134:137], v[2:17]
	s_setprio 0
	s_barrier
	s_and_b32 s28, s28, 0x7fffff00
	s_setprio 1
	ds_read_b128 v[130:133], v0
	s_waitcnt vmcnt(7) lgkmcnt(0)
	v_mfma_f32_32x32x16_bf16 v[114:129], v[174:177], v[130:133], v[114:129]
	s_waitcnt vmcnt(6)
	v_mfma_f32_32x32x16_bf16 v[98:113], v[206:209], v[130:133], v[98:113]
	ds_read_b128 v[130:133], v0 offset:4608
	s_waitcnt lgkmcnt(0)
	v_mfma_f32_32x32x16_bf16 v[82:97], v[174:177], v[130:133], v[82:97]
	v_mfma_f32_32x32x16_bf16 v[66:81], v[206:209], v[130:133], v[66:81]
	ds_read_b128 v[130:133], v0 offset:9216
	s_waitcnt lgkmcnt(0)
	v_mfma_f32_32x32x16_bf16 v[50:65], v[174:177], v[130:133], v[50:65]
	v_mfma_f32_32x32x16_bf16 v[34:49], v[206:209], v[130:133], v[34:49]
	ds_read_b128 v[130:133], v0 offset:13824
	s_waitcnt lgkmcnt(0)
	v_mfma_f32_32x32x16_bf16 v[18:33], v[174:177], v[130:133], v[18:33]
	v_mfma_f32_32x32x16_bf16 v[2:17], v[206:209], v[130:133], v[2:17]
	ds_read_b128 v[130:133], v0 offset:32
	s_waitcnt vmcnt(5) lgkmcnt(0)
	v_mfma_f32_32x32x16_bf16 v[114:129], v[170:173], v[130:133], v[114:129]
	s_waitcnt vmcnt(4)
	v_mfma_f32_32x32x16_bf16 v[98:113], v[166:169], v[130:133], v[98:113]
	ds_read_b128 v[130:133], v0 offset:4640
	s_waitcnt lgkmcnt(0)
	v_mfma_f32_32x32x16_bf16 v[82:97], v[170:173], v[130:133], v[82:97]
	v_mfma_f32_32x32x16_bf16 v[66:81], v[166:169], v[130:133], v[66:81]
	ds_read_b128 v[130:133], v0 offset:9248
	s_waitcnt lgkmcnt(0)
	v_mfma_f32_32x32x16_bf16 v[50:65], v[170:173], v[130:133], v[50:65]
	v_mfma_f32_32x32x16_bf16 v[34:49], v[166:169], v[130:133], v[34:49]
	ds_read_b128 v[130:133], v0 offset:13856
	s_waitcnt lgkmcnt(0)
; #define MFMA32(a, b, c) __builtin_amdgcn_mfma_f32_32x32x16_bf16((a), (b), (c), 0, 0, 0)
; DI void gemm_main_bd(f32x16 (&acc)[4][2], const bf16_t* __restrict__ A, int lda, const bf16_t* __restrict__ Bf, int n0,
;                      int K, char* lds) {
;     ...
;     for (int ks = 0; ks < 4; ++ks) {
;       bf16x8 af[4];
; #pragma unroll
;       for (int mi = 0; mi < 4; ++mi) af[mi] = *(const bf16x8*)(As + (32 * mi + l31) * 72 + 16 * ks + 8 * h2);
; #pragma unroll
;       for (int mi = 0; mi < 4; ++mi)
; #pragma unroll
;         for (int ni = 0; ni < 2; ++ni) acc[mi][ni] = MFMA32(bc[ni][ks], af[mi], acc[mi][ni]);
;     }
;     __builtin_amdgcn_s_setprio(0);
;     __syncthreads();
;   }
; DI void phase_gemm_resid(const bf16_t* __restrict__ A, int K, const bf16_t* __restrict__ Bf, const float* xsrc, float* x,
;                          float scale, char* lds) {
;     ...
; #pragma unroll
;     for (int mi = 0; mi < 4; ++mi)
; #pragma unroll
;       for (int ni = 0; ni < 2; ++ni) {
;         float4 xs[4];
;         const size_t base = (size_t)(mt * 128 + 32 * mi + l31) * 1024 + nt * 256 + 64 * w + 32 * ni + 4 * h2;
; #pragma unroll
;         for (int g = 0; g < 4; ++g) xs[g] = *(const float4*)(xsrc + base + 8 * g);
; #pragma unroll
;         for (int g = 0; g < 4; ++g) {
;           float4 o;
;           o.x = xs[g].x + scale * a0[mi][ni][4 * g];
;           o.y = xs[g].y + scale * a0[mi][ni][4 * g + 1];
;           o.z = xs[g].z + scale * a0[mi][ni][4 * g + 2];
;           o.w = xs[g].w + scale * a0[mi][ni][4 * g + 3];
;           *(float4*)(x + base + 8 * g) = o;
;         }
;       }
	v_mfma_f32_32x32x16_bf16 v[18:33], v[170:173], v[130:133], v[18:33]
	v_mfma_f32_32x32x16_bf16 v[2:17], v[166:169], v[130:133], v[2:17]
	ds_read_b128 v[130:133], v0 offset:64
	s_waitcnt vmcnt(3) lgkmcnt(0)
	v_mfma_f32_32x32x16_bf16 v[114:129], v[158:161], v[130:133], v[114:129]
	s_waitcnt vmcnt(2)
	v_mfma_f32_32x32x16_bf16 v[98:113], v[162:165], v[130:133], v[98:113]
	ds_read_b128 v[130:133], v0 offset:4672
	s_waitcnt lgkmcnt(0)
	v_mfma_f32_32x32x16_bf16 v[82:97], v[158:161], v[130:133], v[82:97]
	v_mfma_f32_32x32x16_bf16 v[66:81], v[162:165], v[130:133], v[66:81]
	ds_read_b128 v[130:133], v0 offset:9280
	s_waitcnt lgkmcnt(0)
	v_mfma_f32_32x32x16_bf16 v[50:65], v[158:161], v[130:133], v[50:65]
	v_mfma_f32_32x32x16_bf16 v[34:49], v[162:165], v[130:133], v[34:49]
	ds_read_b128 v[130:133], v0 offset:13888
	s_waitcnt lgkmcnt(0)
	v_mfma_f32_32x32x16_bf16 v[18:33], v[158:161], v[130:133], v[18:33]
	v_mfma_f32_32x32x16_bf16 v[2:17], v[162:165], v[130:133], v[2:17]
	ds_read_b128 v[130:133], v0 offset:96
	s_waitcnt vmcnt(1) lgkmcnt(0)
	v_mfma_f32_32x32x16_bf16 v[114:129], v[154:157], v[130:133], v[114:129]
	s_waitcnt vmcnt(0)
	v_mfma_f32_32x32x16_bf16 v[98:113], v[150:153], v[130:133], v[98:113]
	ds_read_b128 v[130:133], v0 offset:4704
	s_waitcnt lgkmcnt(0)
	v_mfma_f32_32x32x16_bf16 v[82:97], v[154:157], v[130:133], v[82:97]
	v_mfma_f32_32x32x16_bf16 v[66:81], v[150:153], v[130:133], v[66:81]
	ds_read_b128 v[130:133], v0 offset:9312
	s_waitcnt lgkmcnt(0)
	v_mfma_f32_32x32x16_bf16 v[50:65], v[154:157], v[130:133], v[50:65]
	v_mfma_f32_32x32x16_bf16 v[34:49], v[150:153], v[130:133], v[34:49]
	ds_read_b128 v[130:133], v0 offset:13920
	s_waitcnt lgkmcnt(0)
	v_mfma_f32_32x32x16_bf16 v[18:33], v[154:157], v[130:133], v[18:33]
	v_mfma_f32_32x32x16_bf16 v[2:17], v[150:153], v[130:133], v[2:17]
	s_setprio 0
	v_lshl_add_u64 v[130:131], v[220:221], 0, s[28:29]
	v_lshl_add_u64 v[130:131], v[130:131], 2, s[0:1]
	v_lshl_or_b32 v0, s41, 19, v233
	v_lshl_add_u64 v[130:131], v[130:131], 0, v[0:1]
	s_barrier
	s_mov_b32 s24, 0x40000
	s_add_i32 s40, s40, 1
	v_readlane_b32 s25, v243, 23
	s_mov_b32 s24, 0x60000
	s_mul_i32 s24, s40, s66
	s_add_i32 s24, s24, s3
	s_cmp_ge_u32 s24, s25
	s_mov_b32 s100, 0x20000
	s_mov_b32 s101, 0
	v_lshl_add_u64 v[140:141], v[130:131], 0, s[100:101]
	v_lshl_add_u64 v[142:143], v[140:141], 0, s[100:101]
	v_lshl_add_u64 v[144:145], v[142:143], 0, s[100:101]
	global_load_dwordx4 v[146:149], v[130:131], off
	global_load_dwordx4 v[150:153], v[130:131], off offset:32
	global_load_dwordx4 v[154:157], v[130:131], off offset:64
	global_load_dwordx4 v[158:161], v[130:131], off offset:96
	global_load_dwordx4 v[162:165], v[130:131], off offset:128
	global_load_dwordx4 v[166:169], v[130:131], off offset:160
	global_load_dwordx4 v[170:173], v[130:131], off offset:192
	global_load_dwordx4 v[174:177], v[130:131], off offset:224
	global_load_dwordx4 v[178:181], v[140:141], off
	global_load_dwordx4 v[182:185], v[140:141], off offset:32
	global_load_dwordx4 v[186:189], v[140:141], off offset:64
	global_load_dwordx4 v[190:193], v[140:141], off offset:96
	global_load_dwordx4 v[194:197], v[140:141], off offset:128
	global_load_dwordx4 v[198:201], v[140:141], off offset:160
	global_load_dwordx4 v[202:205], v[140:141], off offset:192
	global_load_dwordx4 v[206:209], v[140:141], off offset:224
	s_waitcnt vmcnt(8)
	v_pk_fma_f32 v[114:115], v[114:115], 0.5, v[146:147] op_sel_hi:[1,0,1]
	v_pk_fma_f32 v[116:117], v[116:117], 0.5, v[148:149] op_sel_hi:[1,0,1]
	v_pk_fma_f32 v[118:119], v[118:119], 0.5, v[150:151] op_sel_hi:[1,0,1]
	v_pk_fma_f32 v[120:121], v[120:121], 0.5, v[152:153] op_sel_hi:[1,0,1]
	v_pk_fma_f32 v[122:123], v[122:123], 0.5, v[154:155] op_sel_hi:[1,0,1]
	v_pk_fma_f32 v[124:125], v[124:125], 0.5, v[156:157] op_sel_hi:[1,0,1]
	v_pk_fma_f32 v[126:127], v[126:127], 0.5, v[158:159] op_sel_hi:[1,0,1]
	v_pk_fma_f32 v[128:129], v[128:129], 0.5, v[160:161] op_sel_hi:[1,0,1]
	v_pk_fma_f32 v[98:99], v[98:99], 0.5, v[162:163] op_sel_hi:[1,0,1]
	v_pk_fma_f32 v[100:101], v[100:101], 0.5, v[164:165] op_sel_hi:[1,0,1]
	v_pk_fma_f32 v[102:103], v[102:103], 0.5, v[166:167] op_sel_hi:[1,0,1]
	v_pk_fma_f32 v[104:105], v[104:105], 0.5, v[168:169] op_sel_hi:[1,0,1]
	v_pk_fma_f32 v[106:107], v[106:107], 0.5, v[170:171] op_sel_hi:[1,0,1]
	v_pk_fma_f32 v[108:109], v[108:109], 0.5, v[172:173] op_sel_hi:[1,0,1]
	v_pk_fma_f32 v[110:111], v[110:111], 0.5, v[174:175] op_sel_hi:[1,0,1]
	v_pk_fma_f32 v[112:113], v[112:113], 0.5, v[176:177] op_sel_hi:[1,0,1]
	global_store_dwordx4 v[130:131], v[114:117], off
	global_store_dwordx4 v[130:131], v[118:121], off offset:32
	global_store_dwordx4 v[130:131], v[122:125], off offset:64
	global_store_dwordx4 v[130:131], v[126:129], off offset:96
	global_store_dwordx4 v[130:131], v[98:101], off offset:128
	global_store_dwordx4 v[130:131], v[102:105], off offset:160
	global_store_dwordx4 v[130:131], v[106:109], off offset:192
	global_store_dwordx4 v[130:131], v[110:113], off offset:224
	global_load_dwordx4 v[146:149], v[142:143], off
	global_load_dwordx4 v[150:153], v[142:143], off offset:32
	global_load_dwordx4 v[154:157], v[142:143], off offset:64
	global_load_dwordx4 v[158:161], v[142:143], off offset:96
	global_load_dwordx4 v[162:165], v[142:143], off offset:128
	global_load_dwordx4 v[166:169], v[142:143], off offset:160
	global_load_dwordx4 v[170:173], v[142:143], off offset:192
	global_load_dwordx4 v[174:177], v[142:143], off offset:224
	s_waitcnt vmcnt(16)
; DI void phase_gemm_resid(const bf16_t* __restrict__ A, int K, const bf16_t* __restrict__ Bf, const float* xsrc, float* x,
;                          float scale, char* lds) {
;     ...
; #pragma unroll
;     for (int mi = 0; mi < 4; ++mi)
; #pragma unroll
;       for (int ni = 0; ni < 2; ++ni) {
;         float4 xs[4];
;         const size_t base = (size_t)(mt * 128 + 32 * mi + l31) * 1024 + nt * 256 + 64 * w + 32 * ni + 4 * h2;
; #pragma unroll
;         for (int g = 0; g < 4; ++g) xs[g] = *(const float4*)(xsrc + base + 8 * g);
; #pragma unroll
;         for (int g = 0; g < 4; ++g) {
;           float4 o;
;           o.x = xs[g].x + scale * a0[mi][ni][4 * g];
;           o.y = xs[g].y + scale * a0[mi][ni][4 * g + 1];
;           o.z = xs[g].z + scale * a0[mi][ni][4 * g + 2];
;           o.w = xs[g].w + scale * a0[mi][ni][4 * g + 3];
;           *(float4*)(x + base + 8 * g) = o;
;         }
;       }
	v_pk_fma_f32 v[82:83], v[82:83], 0.5, v[178:179] op_sel_hi:[1,0,1]
	v_pk_fma_f32 v[84:85], v[84:85], 0.5, v[180:181] op_sel_hi:[1,0,1]
	v_pk_fma_f32 v[86:87], v[86:87], 0.5, v[182:183] op_sel_hi:[1,0,1]
	v_pk_fma_f32 v[88:89], v[88:89], 0.5, v[184:185] op_sel_hi:[1,0,1]
	v_pk_fma_f32 v[90:91], v[90:91], 0.5, v[186:187] op_sel_hi:[1,0,1]
	v_pk_fma_f32 v[92:93], v[92:93], 0.5, v[188:189] op_sel_hi:[1,0,1]
	v_pk_fma_f32 v[94:95], v[94:95], 0.5, v[190:191] op_sel_hi:[1,0,1]
	v_pk_fma_f32 v[96:97], v[96:97], 0.5, v[192:193] op_sel_hi:[1,0,1]
	v_pk_fma_f32 v[66:67], v[66:67], 0.5, v[194:195] op_sel_hi:[1,0,1]
	v_pk_fma_f32 v[68:69], v[68:69], 0.5, v[196:197] op_sel_hi:[1,0,1]
	v_pk_fma_f32 v[70:71], v[70:71], 0.5, v[198:199] op_sel_hi:[1,0,1]
	v_pk_fma_f32 v[72:73], v[72:73], 0.5, v[200:201] op_sel_hi:[1,0,1]
	v_pk_fma_f32 v[74:75], v[74:75], 0.5, v[202:203] op_sel_hi:[1,0,1]
	v_pk_fma_f32 v[76:77], v[76:77], 0.5, v[204:205] op_sel_hi:[1,0,1]
	v_pk_fma_f32 v[78:79], v[78:79], 0.5, v[206:207] op_sel_hi:[1,0,1]
	v_pk_fma_f32 v[80:81], v[80:81], 0.5, v[208:209] op_sel_hi:[1,0,1]
	global_store_dwordx4 v[140:141], v[82:85], off
	global_store_dwordx4 v[140:141], v[86:89], off offset:32
	global_store_dwordx4 v[140:141], v[90:93], off offset:64
	global_store_dwordx4 v[140:141], v[94:97], off offset:96
	global_store_dwordx4 v[140:141], v[66:69], off offset:128
	global_store_dwordx4 v[140:141], v[70:73], off offset:160
	global_store_dwordx4 v[140:141], v[74:77], off offset:192
	global_store_dwordx4 v[140:141], v[78:81], off offset:224
	global_load_dwordx4 v[178:181], v[144:145], off
	global_load_dwordx4 v[182:185], v[144:145], off offset:32
	global_load_dwordx4 v[186:189], v[144:145], off offset:64
	global_load_dwordx4 v[190:193], v[144:145], off offset:96
	global_load_dwordx4 v[194:197], v[144:145], off offset:128
	global_load_dwordx4 v[198:201], v[144:145], off offset:160
	global_load_dwordx4 v[202:205], v[144:145], off offset:192
	global_load_dwordx4 v[206:209], v[144:145], off offset:224
	s_waitcnt vmcnt(16)
	v_pk_fma_f32 v[50:51], v[50:51], 0.5, v[146:147] op_sel_hi:[1,0,1]
	v_pk_fma_f32 v[52:53], v[52:53], 0.5, v[148:149] op_sel_hi:[1,0,1]
	v_pk_fma_f32 v[54:55], v[54:55], 0.5, v[150:151] op_sel_hi:[1,0,1]
	v_pk_fma_f32 v[56:57], v[56:57], 0.5, v[152:153] op_sel_hi:[1,0,1]
	v_pk_fma_f32 v[58:59], v[58:59], 0.5, v[154:155] op_sel_hi:[1,0,1]
	v_pk_fma_f32 v[60:61], v[60:61], 0.5, v[156:157] op_sel_hi:[1,0,1]
	v_pk_fma_f32 v[62:63], v[62:63], 0.5, v[158:159] op_sel_hi:[1,0,1]
	v_pk_fma_f32 v[64:65], v[64:65], 0.5, v[160:161] op_sel_hi:[1,0,1]
	v_pk_fma_f32 v[34:35], v[34:35], 0.5, v[162:163] op_sel_hi:[1,0,1]
	v_pk_fma_f32 v[36:37], v[36:37], 0.5, v[164:165] op_sel_hi:[1,0,1]
	v_pk_fma_f32 v[38:39], v[38:39], 0.5, v[166:167] op_sel_hi:[1,0,1]
	v_pk_fma_f32 v[40:41], v[40:41], 0.5, v[168:169] op_sel_hi:[1,0,1]
	v_pk_fma_f32 v[42:43], v[42:43], 0.5, v[170:171] op_sel_hi:[1,0,1]
	v_pk_fma_f32 v[44:45], v[44:45], 0.5, v[172:173] op_sel_hi:[1,0,1]
	v_pk_fma_f32 v[46:47], v[46:47], 0.5, v[174:175] op_sel_hi:[1,0,1]
	v_pk_fma_f32 v[48:49], v[48:49], 0.5, v[176:177] op_sel_hi:[1,0,1]
	global_store_dwordx4 v[142:143], v[50:53], off
	global_store_dwordx4 v[142:143], v[54:57], off offset:32
	global_store_dwordx4 v[142:143], v[58:61], off offset:64
	global_store_dwordx4 v[142:143], v[62:65], off offset:96
	global_store_dwordx4 v[142:143], v[34:37], off offset:128
	global_store_dwordx4 v[142:143], v[38:41], off offset:160
	global_store_dwordx4 v[142:143], v[42:45], off offset:192
	global_store_dwordx4 v[142:143], v[46:49], off offset:224
	s_waitcnt vmcnt(8)
	v_pk_fma_f32 v[18:19], v[18:19], 0.5, v[178:179] op_sel_hi:[1,0,1]
	v_pk_fma_f32 v[20:21], v[20:21], 0.5, v[180:181] op_sel_hi:[1,0,1]
	v_pk_fma_f32 v[22:23], v[22:23], 0.5, v[182:183] op_sel_hi:[1,0,1]
	v_pk_fma_f32 v[24:25], v[24:25], 0.5, v[184:185] op_sel_hi:[1,0,1]
	v_pk_fma_f32 v[26:27], v[26:27], 0.5, v[186:187] op_sel_hi:[1,0,1]
	v_pk_fma_f32 v[28:29], v[28:29], 0.5, v[188:189] op_sel_hi:[1,0,1]
	v_pk_fma_f32 v[30:31], v[30:31], 0.5, v[190:191] op_sel_hi:[1,0,1]
	v_pk_fma_f32 v[32:33], v[32:33], 0.5, v[192:193] op_sel_hi:[1,0,1]
	v_pk_fma_f32 v[2:3], v[2:3], 0.5, v[194:195] op_sel_hi:[1,0,1]
	v_pk_fma_f32 v[4:5], v[4:5], 0.5, v[196:197] op_sel_hi:[1,0,1]
	v_pk_fma_f32 v[6:7], v[6:7], 0.5, v[198:199] op_sel_hi:[1,0,1]
	v_pk_fma_f32 v[8:9], v[8:9], 0.5, v[200:201] op_sel_hi:[1,0,1]
	v_pk_fma_f32 v[10:11], v[10:11], 0.5, v[202:203] op_sel_hi:[1,0,1]
	v_pk_fma_f32 v[12:13], v[12:13], 0.5, v[204:205] op_sel_hi:[1,0,1]
	v_pk_fma_f32 v[14:15], v[14:15], 0.5, v[206:207] op_sel_hi:[1,0,1]
	v_pk_fma_f32 v[16:17], v[16:17], 0.5, v[208:209] op_sel_hi:[1,0,1]
	global_store_dwordx4 v[144:145], v[18:21], off
	global_store_dwordx4 v[144:145], v[22:25], off offset:32
	global_store_dwordx4 v[144:145], v[26:29], off offset:64
	global_store_dwordx4 v[144:145], v[30:33], off offset:96
	global_store_dwordx4 v[144:145], v[2:5], off offset:128
	global_store_dwordx4 v[144:145], v[6:9], off offset:160
	global_store_dwordx4 v[144:145], v[10:13], off offset:192
	global_store_dwordx4 v[144:145], v[14:17], off offset:224
	s_cbranch_scc0 .LBB0_1180

; DI unsigned pack2(float a, float b) { f2_t v = {a, b}; return __builtin_bit_cast(unsigned, __builtin_convertvector(v, bf2_t)); }
; DI void phase_norm(const float* __restrict__ x, const float* __restrict__ g, bf16_t* __restrict__ dst,
;                            const float* __restrict__ psrc, bf16_t* __restrict__ pdst) {
;     ...
;   for (int r = blockIdx.x * 4 + wave; r < TG; r += gridDim.x * 4) {
;     const float4* xr = (const float4*)(x + (size_t)r * 1024);
;     float4 v[4];
;     float ss = 0.f;
; #pragma unroll
;     for (int i = 0; i < 4; ++i) { v[i] = xr[lane + 64 * i]; ss += v[i].x * v[i].x + v[i].y * v[i].y + v[i].z * v[i].z + v[i].w * v[i].w; }
;     ss = wave_sum(ss);
;     const float rs = rsqrtf(ss * (1.f / 1024.f) + EPS);
; #pragma unroll
;     for (int i = 0; i < 4; ++i) {
;       const float4 gg = ((const float4*)g)[lane + 64 * i];
;       u32x2 o; o.x = pack2(v[i].x * rs * gg.x, v[i].y * rs * gg.y); o.y = pack2(v[i].z * rs * gg.z, v[i].w * rs * gg.w);
;       ((u32x2*)(dst + (size_t)r * 1024))[lane + 64 * i] = o;
;     }
;     if (psrc) {
;       const float4 pv = ((const float4*)(psrc + (size_t)r * 256))[lane];
;       u32x2 o; o.x = pack2(pv.x, pv.y); o.y = pack2(pv.z, pv.w);
;       ((u32x2*)(pdst + (size_t)r * 256))[lane] = o;
;     }
;   }
.LBB0_1297:
	v_ashrrev_i32_e32 v19, 31, v18
	v_lshlrev_b64 v[30:31], 12, v[18:19]
	v_lshl_add_u64 v[42:43], v[20:21], 0, v[30:31]
	v_lshlrev_b64 v[34:35], 11, v[18:19]
	global_load_dwordx4 v[30:33], v[42:43], off
	v_lshl_add_u64 v[46:47], v[22:23], 0, v[34:35]
	global_load_dwordx4 v[34:37], v[42:43], off offset:1024
	global_load_dwordx4 v[58:61], v[42:43], off offset:2048
	global_load_dwordx4 v[62:65], v[42:43], off offset:3072
	v_add_u32_e32 v18, s56, v18
	s_waitcnt vmcnt(3)
	v_mov_b32_e32 v48, v31
	v_mov_b32_e32 v44, v30
	s_waitcnt vmcnt(2)
	v_mov_b32_e32 v49, v35
	v_mov_b32_e32 v45, v34
	v_pk_mul_f32 v[48:49], v[48:49], v[48:49]
	v_mov_b32_e32 v38, v32
	v_mov_b32_e32 v39, v36
	v_pk_fma_f32 v[44:45], v[44:45], v[44:45], v[48:49]
	v_mov_b32_e32 v40, v33
	v_mov_b32_e32 v41, v37
	v_pk_fma_f32 v[38:39], v[38:39], v[38:39], v[44:45]
	s_nop 0
	v_pk_fma_f32 v[48:49], v[40:41], v[40:41], v[38:39]
	v_add_f32_e32 v0, v48, v49
	s_waitcnt vmcnt(1)
	v_mov_b32_e32 v56, v59
	s_waitcnt vmcnt(0)
	v_mov_b32_e32 v57, v63
	v_mov_b32_e32 v54, v58
	v_mov_b32_e32 v55, v62
	v_pk_mul_f32 v[56:57], v[56:57], v[56:57]
	v_mov_b32_e32 v50, v60
	v_mov_b32_e32 v51, v64
	v_pk_fma_f32 v[54:55], v[54:55], v[54:55], v[56:57]
	v_mov_b32_e32 v52, v61
	v_mov_b32_e32 v53, v65
	v_pk_fma_f32 v[50:51], v[50:51], v[50:51], v[54:55]
	s_nop 0
	v_pk_fma_f32 v[50:51], v[52:53], v[52:53], v[50:51]
	s_nop 0
	v_add_f32_e32 v0, v0, v50
	v_add_f32_e32 v0, v0, v51
	ds_bpermute_b32 v19, v24, v0
	s_waitcnt lgkmcnt(0)
	v_add_f32_e32 v0, v0, v19
	ds_bpermute_b32 v19, v25, v0
	s_waitcnt lgkmcnt(0)
	v_add_f32_e32 v0, v0, v19
	ds_bpermute_b32 v19, v26, v0
	s_waitcnt lgkmcnt(0)
	v_add_f32_e32 v0, v0, v19
	ds_bpermute_b32 v19, v27, v0
	s_waitcnt lgkmcnt(0)
	v_add_f32_e32 v0, v0, v19
	ds_bpermute_b32 v19, v28, v0
	s_waitcnt lgkmcnt(0)
	v_add_f32_e32 v0, v0, v19
	ds_bpermute_b32 v19, v29, v0
	s_waitcnt lgkmcnt(0)
	v_add_f32_e32 v0, v0, v19
	v_fmamk_f32 v0, v0, 0x3a800000, v216
	v_cmp_gt_f32_e32 vcc, s15, v0
	v_mul_f32_e32 v19, 0x4b800000, v0
	s_nop 0
	v_cndmask_b32_e32 v0, v0, v19, vcc
	v_rsq_f32_e32 v0, v0
	s_nop 0
	v_mul_f32_e32 v19, 0x45800000, v0
	v_cndmask_b32_e32 v0, v0, v19, vcc
	v_pk_mul_f32 v[30:31], v[30:31], v[0:1] op_sel_hi:[1,0]
	v_pk_mul_f32 v[32:33], v[32:33], v[0:1] op_sel_hi:[1,0]
	v_pk_mul_f32 v[30:31], v[2:3], v[30:31]
	v_pk_mul_f32 v[32:33], v[4:5], v[32:33]
	v_cvt_pk_bf16_f32 v30, v30, v31
	v_cvt_pk_bf16_f32 v31, v32, v33
	global_store_dwordx2 v[46:47], v[30:31], off
	v_pk_mul_f32 v[30:31], v[34:35], v[0:1] op_sel_hi:[1,0]
	v_pk_mul_f32 v[32:33], v[36:37], v[0:1] op_sel_hi:[1,0]
	v_pk_mul_f32 v[30:31], v[6:7], v[30:31]
	v_pk_mul_f32 v[32:33], v[8:9], v[32:33]
	v_cvt_pk_bf16_f32 v30, v30, v31
	v_cvt_pk_bf16_f32 v31, v32, v33
	global_store_dwordx2 v[46:47], v[30:31], off offset:512
	v_pk_mul_f32 v[30:31], v[58:59], v[0:1] op_sel_hi:[1,0]
	v_pk_mul_f32 v[32:33], v[60:61], v[0:1] op_sel_hi:[1,0]
	v_pk_mul_f32 v[30:31], v[10:11], v[30:31]
	v_pk_mul_f32 v[32:33], v[12:13], v[32:33]
	v_cvt_pk_bf16_f32 v30, v30, v31
	v_cvt_pk_bf16_f32 v31, v32, v33
	global_store_dwordx2 v[46:47], v[30:31], off offset:1024
	v_pk_mul_f32 v[30:31], v[62:63], v[0:1] op_sel_hi:[1,0]
	v_pk_mul_f32 v[32:33], v[64:65], v[0:1] op_sel_hi:[1,0]
	v_pk_mul_f32 v[30:31], v[14:15], v[30:31]
	v_pk_mul_f32 v[32:33], v[16:17], v[32:33]
	v_cmp_lt_i32_e32 vcc, s38, v18
	v_cvt_pk_bf16_f32 v30, v30, v31
	v_cvt_pk_bf16_f32 v31, v32, v33
	s_or_b64 s[24:25], vcc, s[24:25]
	global_store_dwordx2 v[46:47], v[30:31], off offset:1536
	s_andn2_b64 exec, exec, s[24:25]
	s_cbranch_execnz .LBB0_1297
